# phase 2 (h@W_in) epilogue rewritten: transposed MFMA tiles, vector rope-table loads, 8B stores, scalar kind dispatch; plus phase 9 epilogue + attention address hoists
# speedup vs baseline: 1.0872x; 1.0366x over previous
.LBB0_350:
	s_lshl_b32 s6, s9, 7
	s_ashr_i32 s7, s6, 31
	s_lshl_b64 s[12:13], s[6:7], 11
	v_mov_b32_e32 v0, 0
	s_add_u32 s14, s72, s12
	v_mov_b32_e32 v47, v186
	s_addc_u32 s15, s73, s13
	s_ashr_i32 s9, s8, 31
	s_lshl_b64 s[12:13], s[8:9], 18
	v_lshlrev_b32_e32 v1, 4, v47
	s_waitcnt vmcnt(0)
	v_ashrrev_i32_e32 v13, 3, v47
	v_and_b32_e32 v46, 0x70, v1
	s_add_u32 s12, s0, s12
	v_lshl_or_b32 v64, v13, 11, v46
	s_addc_u32 s13, s1, s13
	v_add_u32_e32 v68, 0x10000, v64
	v_add_u32_e32 v72, 0x20000, v64
	v_add_u32_e32 v76, 0x30000, v64
	s_barrier
	global_load_dwordx4 v[14:17], v64, s[14:15]
	global_load_dwordx4 v[18:21], v68, s[14:15]
	global_load_dwordx4 v[22:25], v72, s[14:15]
	global_load_dwordx4 v[26:29], v76, s[14:15]
	global_load_dwordx4 v[30:33], v64, s[12:13]
	global_load_dwordx4 v[34:37], v68, s[12:13]
	global_load_dwordx4 v[38:41], v72, s[12:13]
	global_load_dwordx4 v[42:45], v76, s[12:13]
	v_lshrrev_b32_e32 v49, 1, v47
	v_and_b32_e32 v50, 31, v47
	v_and_b32_e32 v48, 16, v49
	v_and_or_b32 v49, v49, s44, v50
	v_mad_u64_u32 v[106:107], s[30:31], v13, s43, v[46:47]
	v_mad_u64_u32 v[104:105], s[30:31], v49, s43, v[48:49]
	v_mov_b32_e32 v1, v0
	v_mov_b32_e32 v2, v0
	v_mov_b32_e32 v3, v0
	v_mov_b32_e32 v4, v0
	v_mov_b32_e32 v5, v0
	v_mov_b32_e32 v6, v0
	v_mov_b32_e32 v7, v0
	v_mov_b32_e32 v8, v0
	v_mov_b32_e32 v9, v0
	v_mov_b32_e32 v10, v0
	v_mov_b32_e32 v11, v0
	v_mov_b32_e32 v12, v0
	v_mov_b32_e32 v13, v0
	v_add_u32_e32 v107, 0xd800, v106
	s_lshl_b32 s7, s8, 1
	s_waitcnt vmcnt(7)
	ds_write_b128 v106, v[14:17]
	s_waitcnt vmcnt(6)
	ds_write_b128 v106, v[18:21] offset:4608
	s_waitcnt vmcnt(5)
	ds_write_b128 v106, v[22:25] offset:9216
	s_waitcnt vmcnt(4)
	ds_write_b128 v106, v[26:29] offset:13824
	s_waitcnt vmcnt(3)
	ds_write_b128 v106, v[30:33] offset:36864
	s_waitcnt vmcnt(2)
	ds_write_b128 v106, v[34:37] offset:41472
	s_waitcnt vmcnt(1)
	ds_write_b128 v106, v[38:41] offset:46080
	s_waitcnt vmcnt(0)
	ds_write_b128 v106, v[42:45] offset:50688
	global_load_dwordx4 v[78:81], v64, s[14:15] offset:128
	global_load_dwordx4 v[82:85], v68, s[14:15] offset:128
	global_load_dwordx4 v[86:89], v72, s[14:15] offset:128
	global_load_dwordx4 v[90:93], v76, s[14:15] offset:128
	global_load_dwordx4 v[112:115], v64, s[12:13] offset:128
	global_load_dwordx4 v[116:119], v68, s[12:13] offset:128
	global_load_dwordx4 v[120:123], v72, s[12:13] offset:128
	global_load_dwordx4 v[124:127], v76, s[12:13] offset:128
	s_waitcnt lgkmcnt(0)
	s_barrier
	ds_read_b128 v[16:19], v104
	v_and_b32_e32 v14, 0x5f, v47
	v_mad_u32_u24 v105, v14, s43, v48
	ds_read_b128 v[128:131], v105 offset:41472
	ds_read_b128 v[132:135], v104 offset:4608
	v_mov_b32_e32 v14, v0
	v_mov_b32_e32 v15, v0
	ds_read_b128 v[136:139], v104 offset:32
	s_waitcnt lgkmcnt(2)
	v_mfma_f32_32x32x16_bf16 v[32:47], v[128:131], v[16:19], v[0:15]
	ds_read_b128 v[140:143], v105 offset:36864
	ds_read_b128 v[144:147], v104 offset:4640
	ds_read_b128 v[148:151], v105 offset:36896
	ds_read_b128 v[152:155], v105 offset:41504
	s_waitcnt lgkmcnt(3)
	v_mfma_f32_32x32x16_bf16 v[48:63], v[140:143], v[16:19], v[0:15]
	v_mfma_f32_32x32x16_bf16 v[16:31], v[140:143], v[132:135], v[0:15]
	v_mfma_f32_32x32x16_bf16 v[0:15], v[128:131], v[132:135], v[0:15]
	s_waitcnt lgkmcnt(1)
	v_mfma_f32_32x32x16_bf16 v[48:63], v[148:151], v[136:139], v[48:63]
	s_waitcnt lgkmcnt(0)
	v_mfma_f32_32x32x16_bf16 v[32:47], v[152:155], v[136:139], v[32:47]
	v_mfma_f32_32x32x16_bf16 v[16:31], v[148:151], v[144:147], v[16:31]
	v_mfma_f32_32x32x16_bf16 v[0:15], v[152:155], v[144:147], v[0:15]
	ds_read_b128 v[128:131], v104 offset:64
	ds_read_b128 v[136:139], v104 offset:4672
	ds_read_b128 v[132:135], v105 offset:36928
	ds_read_b128 v[140:143], v105 offset:41536
	s_waitcnt lgkmcnt(1)
	v_mfma_f32_32x32x16_bf16 v[48:63], v[132:135], v[128:131], v[48:63]
	s_waitcnt lgkmcnt(0)
	v_mfma_f32_32x32x16_bf16 v[32:47], v[140:143], v[128:131], v[32:47]
	v_mfma_f32_32x32x16_bf16 v[16:31], v[132:135], v[136:139], v[16:31]
	v_mfma_f32_32x32x16_bf16 v[0:15], v[140:143], v[136:139], v[0:15]
	global_load_dwordx4 v[128:131], v64, s[14:15] offset:256
	global_load_dwordx4 v[132:135], v68, s[14:15] offset:256
	global_load_dwordx4 v[136:139], v72, s[14:15] offset:256
	global_load_dwordx4 v[140:143], v76, s[14:15] offset:256
	global_load_dwordx4 v[144:147], v64, s[12:13] offset:256
	global_load_dwordx4 v[148:151], v68, s[12:13] offset:256
	global_load_dwordx4 v[152:155], v72, s[12:13] offset:256
	global_load_dwordx4 v[156:159], v76, s[12:13] offset:256
	s_waitcnt vmcnt(15)
	ds_write_b128 v106, v[78:81] offset:18432
	s_waitcnt vmcnt(14)
	ds_write_b128 v106, v[82:85] offset:23040
	s_waitcnt vmcnt(13)
	ds_write_b128 v106, v[86:89] offset:27648
	s_waitcnt vmcnt(12)
	ds_write_b128 v106, v[90:93] offset:32256
	ds_read_b128 v[78:81], v104 offset:96
	ds_read_b128 v[82:85], v104 offset:4704
	ds_read_b128 v[86:89], v105 offset:36960
	ds_read_b128 v[90:93], v105 offset:41568
	s_waitcnt vmcnt(11)
	ds_write_b128 v106, v[112:115] offset:55296
	s_waitcnt vmcnt(10)
	ds_write_b128 v106, v[116:119] offset:59904
	s_waitcnt vmcnt(9)
	ds_write_b128 v106, v[120:123] offset:64512
	s_waitcnt vmcnt(8)
	ds_write_b128 v107, v[124:127] offset:13824
	s_waitcnt lgkmcnt(5)
	v_mfma_f32_32x32x16_bf16 v[48:63], v[86:89], v[78:81], v[48:63]
	s_waitcnt lgkmcnt(0)
	s_barrier
	v_mfma_f32_32x32x16_bf16 v[32:47], v[90:93], v[78:81], v[32:47]
	v_mfma_f32_32x32x16_bf16 v[16:31], v[86:89], v[82:85], v[16:31]
	v_mfma_f32_32x32x16_bf16 v[0:15], v[90:93], v[82:85], v[0:15]
	ds_read_b128 v[78:81], v104 offset:18432
	ds_read_b128 v[82:85], v104 offset:23040
	ds_read_b128 v[86:89], v105 offset:59904
	ds_read_b128 v[90:93], v105 offset:55296
	ds_read_b128 v[112:115], v104 offset:18464
	ds_read_b128 v[116:119], v104 offset:23072
	ds_read_b128 v[120:123], v105 offset:55328
	ds_read_b128 v[124:127], v105 offset:59936
	s_waitcnt lgkmcnt(4)
	v_mfma_f32_32x32x16_bf16 v[48:63], v[90:93], v[78:81], v[48:63]
	v_mfma_f32_32x32x16_bf16 v[32:47], v[86:89], v[78:81], v[32:47]
	v_mfma_f32_32x32x16_bf16 v[16:31], v[90:93], v[82:85], v[16:31]
	v_mfma_f32_32x32x16_bf16 v[0:15], v[86:89], v[82:85], v[0:15]
	global_load_dwordx4 v[78:81], v64, s[14:15] offset:384
	global_load_dwordx4 v[82:85], v68, s[14:15] offset:384
	global_load_dwordx4 v[86:89], v72, s[14:15] offset:384
	global_load_dwordx4 v[90:93], v76, s[14:15] offset:384
	global_load_dwordx4 v[164:167], v64, s[12:13] offset:384
	global_load_dwordx4 v[168:171], v68, s[12:13] offset:384
	global_load_dwordx4 v[172:175], v72, s[12:13] offset:384
	global_load_dwordx4 v[176:179], v76, s[12:13] offset:384
	ds_read_b128 v[180:183], v104 offset:18496
	ds_read_b128 v[210:213], v104 offset:23104
	ds_read_b128 v[214:217], v105 offset:55360
	ds_read_b128 v[218:221], v105 offset:59968
	s_waitcnt vmcnt(15)
	ds_write_b128 v106, v[128:131]
	s_waitcnt vmcnt(14)
	ds_write_b128 v106, v[132:135] offset:4608
	s_waitcnt vmcnt(13)
	ds_write_b128 v106, v[136:139] offset:9216
	s_waitcnt vmcnt(12)
	ds_write_b128 v106, v[140:143] offset:13824
	s_waitcnt lgkmcnt(9)
	v_mfma_f32_32x32x16_bf16 v[48:63], v[120:123], v[112:115], v[48:63]
	s_waitcnt lgkmcnt(8)
	v_mfma_f32_32x32x16_bf16 v[32:47], v[124:127], v[112:115], v[32:47]
	v_mfma_f32_32x32x16_bf16 v[16:31], v[120:123], v[116:119], v[16:31]
	v_mfma_f32_32x32x16_bf16 v[0:15], v[124:127], v[116:119], v[0:15]
	ds_read_b128 v[112:115], v104 offset:18528
	ds_read_b128 v[116:119], v104 offset:23136
	ds_read_b128 v[120:123], v105 offset:55392
	ds_read_b128 v[124:127], v105 offset:60000
	s_waitcnt vmcnt(11)
	ds_write_b128 v106, v[144:147] offset:36864
	s_waitcnt vmcnt(10)
	ds_write_b128 v106, v[148:151] offset:41472
	s_waitcnt vmcnt(9)
	ds_write_b128 v106, v[152:155] offset:46080
	s_waitcnt vmcnt(8)
	ds_write_b128 v106, v[156:159] offset:50688
	s_waitcnt lgkmcnt(13)
	v_mfma_f32_32x32x16_bf16 v[48:63], v[214:217], v[180:183], v[48:63]
	s_waitcnt lgkmcnt(0)
	s_barrier
	v_mfma_f32_32x32x16_bf16 v[32:47], v[218:221], v[180:183], v[32:47]
	v_mfma_f32_32x32x16_bf16 v[16:31], v[214:217], v[210:213], v[16:31]
	v_mfma_f32_32x32x16_bf16 v[0:15], v[218:221], v[210:213], v[0:15]
	v_mfma_f32_32x32x16_bf16 v[48:63], v[120:123], v[112:115], v[48:63]
	v_mfma_f32_32x32x16_bf16 v[32:47], v[124:127], v[112:115], v[32:47]
	v_mfma_f32_32x32x16_bf16 v[16:31], v[120:123], v[116:119], v[16:31]
	v_mfma_f32_32x32x16_bf16 v[0:15], v[124:127], v[116:119], v[0:15]
	ds_read_b128 v[112:115], v104
	ds_read_b128 v[116:119], v104 offset:4608
	ds_read_b128 v[120:123], v105 offset:41472
	ds_read_b128 v[124:127], v105 offset:36864
	ds_read_b128 v[128:131], v104 offset:32
	ds_read_b128 v[132:135], v104 offset:4640
	ds_read_b128 v[136:139], v105 offset:36896
	ds_read_b128 v[140:143], v105 offset:41504
	s_waitcnt lgkmcnt(4)
	v_mfma_f32_32x32x16_bf16 v[48:63], v[124:127], v[112:115], v[48:63]
	v_mfma_f32_32x32x16_bf16 v[32:47], v[120:123], v[112:115], v[32:47]
	v_mfma_f32_32x32x16_bf16 v[16:31], v[124:127], v[116:119], v[16:31]
	v_mfma_f32_32x32x16_bf16 v[0:15], v[120:123], v[116:119], v[0:15]
	global_load_dwordx4 v[112:115], v64, s[14:15] offset:512
	global_load_dwordx4 v[116:119], v68, s[14:15] offset:512
	global_load_dwordx4 v[120:123], v72, s[14:15] offset:512
	global_load_dwordx4 v[124:127], v76, s[14:15] offset:512
	global_load_dwordx4 v[144:147], v64, s[12:13] offset:512
	global_load_dwordx4 v[148:151], v68, s[12:13] offset:512
	global_load_dwordx4 v[152:155], v72, s[12:13] offset:512
	global_load_dwordx4 v[156:159], v76, s[12:13] offset:512
	ds_read_b128 v[180:183], v104 offset:64
	ds_read_b128 v[210:213], v104 offset:4672
	ds_read_b128 v[214:217], v105 offset:36928
	ds_read_b128 v[218:221], v105 offset:41536
	s_waitcnt vmcnt(15)
	ds_write_b128 v106, v[78:81] offset:18432
	s_waitcnt vmcnt(14)
	ds_write_b128 v106, v[82:85] offset:23040
	s_waitcnt vmcnt(13)
	ds_write_b128 v106, v[86:89] offset:27648
	s_waitcnt vmcnt(12)
	ds_write_b128 v106, v[90:93] offset:32256
	s_waitcnt lgkmcnt(9)
	v_mfma_f32_32x32x16_bf16 v[48:63], v[136:139], v[128:131], v[48:63]
	s_waitcnt lgkmcnt(8)
	v_mfma_f32_32x32x16_bf16 v[32:47], v[140:143], v[128:131], v[32:47]
	v_mfma_f32_32x32x16_bf16 v[16:31], v[136:139], v[132:135], v[16:31]
	v_mfma_f32_32x32x16_bf16 v[0:15], v[140:143], v[132:135], v[0:15]
	ds_read_b128 v[78:81], v104 offset:96
	ds_read_b128 v[82:85], v104 offset:4704
	ds_read_b128 v[86:89], v105 offset:36960
	ds_read_b128 v[90:93], v105 offset:41568
	s_waitcnt vmcnt(11)
	ds_write_b128 v106, v[164:167] offset:55296
	s_waitcnt vmcnt(10)
	ds_write_b128 v106, v[168:171] offset:59904
	s_waitcnt vmcnt(9)
	ds_write_b128 v106, v[172:175] offset:64512
	s_waitcnt vmcnt(8)
	ds_write_b128 v107, v[176:179] offset:13824
	s_waitcnt lgkmcnt(13)
	v_mfma_f32_32x32x16_bf16 v[48:63], v[214:217], v[180:183], v[48:63]
	s_waitcnt lgkmcnt(0)
	s_barrier
	v_mfma_f32_32x32x16_bf16 v[32:47], v[218:221], v[180:183], v[32:47]
	v_mfma_f32_32x32x16_bf16 v[16:31], v[214:217], v[210:213], v[16:31]
	v_mfma_f32_32x32x16_bf16 v[0:15], v[218:221], v[210:213], v[0:15]
	v_mfma_f32_32x32x16_bf16 v[48:63], v[86:89], v[78:81], v[48:63]
	v_mfma_f32_32x32x16_bf16 v[32:47], v[90:93], v[78:81], v[32:47]
	v_mfma_f32_32x32x16_bf16 v[16:31], v[86:89], v[82:85], v[16:31]
	v_mfma_f32_32x32x16_bf16 v[0:15], v[90:93], v[82:85], v[0:15]
	ds_read_b128 v[78:81], v104 offset:18432
	ds_read_b128 v[82:85], v104 offset:23040
	ds_read_b128 v[86:89], v105 offset:59904
	ds_read_b128 v[90:93], v105 offset:55296
	ds_read_b128 v[128:131], v104 offset:18464
	ds_read_b128 v[132:135], v104 offset:23072
	ds_read_b128 v[136:139], v105 offset:55328
	ds_read_b128 v[140:143], v105 offset:59936
	s_waitcnt lgkmcnt(4)
	v_mfma_f32_32x32x16_bf16 v[48:63], v[90:93], v[78:81], v[48:63]
	v_mfma_f32_32x32x16_bf16 v[32:47], v[86:89], v[78:81], v[32:47]
	v_mfma_f32_32x32x16_bf16 v[16:31], v[90:93], v[82:85], v[16:31]
	v_mfma_f32_32x32x16_bf16 v[0:15], v[86:89], v[82:85], v[0:15]
	global_load_dwordx4 v[78:81], v64, s[14:15] offset:640
	global_load_dwordx4 v[82:85], v68, s[14:15] offset:640
	global_load_dwordx4 v[86:89], v72, s[14:15] offset:640
	global_load_dwordx4 v[90:93], v76, s[14:15] offset:640
	global_load_dwordx4 v[164:167], v64, s[12:13] offset:640
	global_load_dwordx4 v[168:171], v68, s[12:13] offset:640
	global_load_dwordx4 v[172:175], v72, s[12:13] offset:640
	global_load_dwordx4 v[176:179], v76, s[12:13] offset:640
	ds_read_b128 v[180:183], v104 offset:18496
	ds_read_b128 v[210:213], v104 offset:23104
	ds_read_b128 v[214:217], v105 offset:55360
	ds_read_b128 v[218:221], v105 offset:59968
	s_waitcnt vmcnt(15)
	ds_write_b128 v106, v[112:115]
	s_waitcnt vmcnt(14)
	ds_write_b128 v106, v[116:119] offset:4608
	s_waitcnt vmcnt(13)
	ds_write_b128 v106, v[120:123] offset:9216
	s_waitcnt vmcnt(12)
	ds_write_b128 v106, v[124:127] offset:13824
	s_waitcnt lgkmcnt(9)
	v_mfma_f32_32x32x16_bf16 v[48:63], v[136:139], v[128:131], v[48:63]
	s_waitcnt lgkmcnt(8)
	v_mfma_f32_32x32x16_bf16 v[32:47], v[140:143], v[128:131], v[32:47]
	v_mfma_f32_32x32x16_bf16 v[16:31], v[136:139], v[132:135], v[16:31]
	v_mfma_f32_32x32x16_bf16 v[0:15], v[140:143], v[132:135], v[0:15]
	ds_read_b128 v[112:115], v104 offset:18528
	ds_read_b128 v[116:119], v104 offset:23136
	ds_read_b128 v[120:123], v105 offset:55392
	ds_read_b128 v[124:127], v105 offset:60000
	s_waitcnt vmcnt(11)
	ds_write_b128 v106, v[144:147] offset:36864
	s_waitcnt vmcnt(10)
	ds_write_b128 v106, v[148:151] offset:41472
	s_waitcnt vmcnt(9)
	ds_write_b128 v106, v[152:155] offset:46080
	s_waitcnt vmcnt(8)
	ds_write_b128 v106, v[156:159] offset:50688
	s_waitcnt lgkmcnt(13)
	v_mfma_f32_32x32x16_bf16 v[48:63], v[214:217], v[180:183], v[48:63]
	s_waitcnt lgkmcnt(0)
	s_barrier
	v_mfma_f32_32x32x16_bf16 v[32:47], v[218:221], v[180:183], v[32:47]
	v_mfma_f32_32x32x16_bf16 v[16:31], v[214:217], v[210:213], v[16:31]
	v_mfma_f32_32x32x16_bf16 v[0:15], v[218:221], v[210:213], v[0:15]
	v_mfma_f32_32x32x16_bf16 v[48:63], v[120:123], v[112:115], v[48:63]
	v_mfma_f32_32x32x16_bf16 v[32:47], v[124:127], v[112:115], v[32:47]
	v_mfma_f32_32x32x16_bf16 v[16:31], v[120:123], v[116:119], v[16:31]
	v_mfma_f32_32x32x16_bf16 v[0:15], v[124:127], v[116:119], v[0:15]
	ds_read_b128 v[112:115], v104
	ds_read_b128 v[116:119], v104 offset:4608
	ds_read_b128 v[120:123], v105 offset:41472
	ds_read_b128 v[124:127], v105 offset:36864
	ds_read_b128 v[128:131], v104 offset:32
	ds_read_b128 v[132:135], v104 offset:4640
	ds_read_b128 v[136:139], v105 offset:36896
	ds_read_b128 v[140:143], v105 offset:41504
	s_waitcnt lgkmcnt(4)
	v_mfma_f32_32x32x16_bf16 v[48:63], v[124:127], v[112:115], v[48:63]
	v_mfma_f32_32x32x16_bf16 v[32:47], v[120:123], v[112:115], v[32:47]
	v_mfma_f32_32x32x16_bf16 v[16:31], v[124:127], v[116:119], v[16:31]
	v_mfma_f32_32x32x16_bf16 v[0:15], v[120:123], v[116:119], v[0:15]
	global_load_dwordx4 v[112:115], v64, s[14:15] offset:768
	global_load_dwordx4 v[116:119], v68, s[14:15] offset:768
	global_load_dwordx4 v[120:123], v72, s[14:15] offset:768
	global_load_dwordx4 v[124:127], v76, s[14:15] offset:768
	global_load_dwordx4 v[144:147], v64, s[12:13] offset:768
	global_load_dwordx4 v[148:151], v68, s[12:13] offset:768
	global_load_dwordx4 v[152:155], v72, s[12:13] offset:768
	global_load_dwordx4 v[156:159], v76, s[12:13] offset:768
	ds_read_b128 v[180:183], v104 offset:64
	ds_read_b128 v[210:213], v104 offset:4672
	ds_read_b128 v[214:217], v105 offset:36928
	ds_read_b128 v[218:221], v105 offset:41536
	s_waitcnt vmcnt(15)
	ds_write_b128 v106, v[78:81] offset:18432
	s_waitcnt vmcnt(14)
	ds_write_b128 v106, v[82:85] offset:23040
	s_waitcnt vmcnt(13)
	ds_write_b128 v106, v[86:89] offset:27648
	s_waitcnt vmcnt(12)
	ds_write_b128 v106, v[90:93] offset:32256
	s_waitcnt lgkmcnt(9)
	v_mfma_f32_32x32x16_bf16 v[48:63], v[136:139], v[128:131], v[48:63]
	s_waitcnt lgkmcnt(8)
	v_mfma_f32_32x32x16_bf16 v[32:47], v[140:143], v[128:131], v[32:47]
	v_mfma_f32_32x32x16_bf16 v[16:31], v[136:139], v[132:135], v[16:31]
	v_mfma_f32_32x32x16_bf16 v[0:15], v[140:143], v[132:135], v[0:15]
	ds_read_b128 v[78:81], v104 offset:96
	ds_read_b128 v[82:85], v104 offset:4704
	ds_read_b128 v[86:89], v105 offset:36960
	ds_read_b128 v[90:93], v105 offset:41568
	s_waitcnt vmcnt(11)
	ds_write_b128 v106, v[164:167] offset:55296
	s_waitcnt vmcnt(10)
	ds_write_b128 v106, v[168:171] offset:59904
	s_waitcnt vmcnt(9)
	ds_write_b128 v106, v[172:175] offset:64512
	s_waitcnt vmcnt(8)
	ds_write_b128 v107, v[176:179] offset:13824
	s_waitcnt lgkmcnt(13)
	v_mfma_f32_32x32x16_bf16 v[48:63], v[214:217], v[180:183], v[48:63]
	s_waitcnt lgkmcnt(0)
	s_barrier
	v_mfma_f32_32x32x16_bf16 v[32:47], v[218:221], v[180:183], v[32:47]
	v_mfma_f32_32x32x16_bf16 v[16:31], v[214:217], v[210:213], v[16:31]
	v_mfma_f32_32x32x16_bf16 v[0:15], v[218:221], v[210:213], v[0:15]
	v_mfma_f32_32x32x16_bf16 v[48:63], v[86:89], v[78:81], v[48:63]
	v_mfma_f32_32x32x16_bf16 v[32:47], v[90:93], v[78:81], v[32:47]
	v_mfma_f32_32x32x16_bf16 v[16:31], v[86:89], v[82:85], v[16:31]
	v_mfma_f32_32x32x16_bf16 v[0:15], v[90:93], v[82:85], v[0:15]
	ds_read_b128 v[78:81], v104 offset:18432
	ds_read_b128 v[82:85], v104 offset:23040
	ds_read_b128 v[86:89], v105 offset:59904
	ds_read_b128 v[90:93], v105 offset:55296
	ds_read_b128 v[128:131], v104 offset:18464
	ds_read_b128 v[132:135], v104 offset:23072
	ds_read_b128 v[136:139], v105 offset:55328
	ds_read_b128 v[140:143], v105 offset:59936
	s_waitcnt lgkmcnt(4)
	v_mfma_f32_32x32x16_bf16 v[48:63], v[90:93], v[78:81], v[48:63]
	v_mfma_f32_32x32x16_bf16 v[32:47], v[86:89], v[78:81], v[32:47]
	v_mfma_f32_32x32x16_bf16 v[16:31], v[90:93], v[82:85], v[16:31]
	v_mfma_f32_32x32x16_bf16 v[0:15], v[86:89], v[82:85], v[0:15]
	global_load_dwordx4 v[78:81], v64, s[14:15] offset:896
	global_load_dwordx4 v[82:85], v68, s[14:15] offset:896
	global_load_dwordx4 v[86:89], v72, s[14:15] offset:896
	global_load_dwordx4 v[90:93], v76, s[14:15] offset:896
	global_load_dwordx4 v[164:167], v64, s[12:13] offset:896
	global_load_dwordx4 v[168:171], v68, s[12:13] offset:896
	global_load_dwordx4 v[172:175], v72, s[12:13] offset:896
	global_load_dwordx4 v[176:179], v76, s[12:13] offset:896
	ds_read_b128 v[180:183], v104 offset:18496
	ds_read_b128 v[210:213], v104 offset:23104
	ds_read_b128 v[214:217], v105 offset:55360
	ds_read_b128 v[218:221], v105 offset:59968
	s_waitcnt vmcnt(15)
	ds_write_b128 v106, v[112:115]
	s_waitcnt vmcnt(14)
	ds_write_b128 v106, v[116:119] offset:4608
	s_waitcnt vmcnt(13)
	ds_write_b128 v106, v[120:123] offset:9216
	s_waitcnt vmcnt(12)
	ds_write_b128 v106, v[124:127] offset:13824
	s_waitcnt lgkmcnt(9)
	v_mfma_f32_32x32x16_bf16 v[48:63], v[136:139], v[128:131], v[48:63]
	s_waitcnt lgkmcnt(8)
	v_mfma_f32_32x32x16_bf16 v[32:47], v[140:143], v[128:131], v[32:47]
	v_mfma_f32_32x32x16_bf16 v[16:31], v[136:139], v[132:135], v[16:31]
	v_mfma_f32_32x32x16_bf16 v[0:15], v[140:143], v[132:135], v[0:15]
	ds_read_b128 v[112:115], v104 offset:18528
	ds_read_b128 v[116:119], v104 offset:23136
	ds_read_b128 v[120:123], v105 offset:55392
	ds_read_b128 v[124:127], v105 offset:60000
	s_waitcnt vmcnt(11)
	ds_write_b128 v106, v[144:147] offset:36864
	s_waitcnt vmcnt(10)
	ds_write_b128 v106, v[148:151] offset:41472
	s_waitcnt vmcnt(9)
	ds_write_b128 v106, v[152:155] offset:46080
	s_waitcnt vmcnt(8)
	ds_write_b128 v106, v[156:159] offset:50688
	s_waitcnt lgkmcnt(13)
	v_mfma_f32_32x32x16_bf16 v[48:63], v[214:217], v[180:183], v[48:63]
	s_waitcnt lgkmcnt(0)
	s_barrier
	v_mfma_f32_32x32x16_bf16 v[32:47], v[218:221], v[180:183], v[32:47]
	v_mfma_f32_32x32x16_bf16 v[16:31], v[214:217], v[210:213], v[16:31]
	v_mfma_f32_32x32x16_bf16 v[0:15], v[218:221], v[210:213], v[0:15]
	v_mfma_f32_32x32x16_bf16 v[48:63], v[120:123], v[112:115], v[48:63]
	v_mfma_f32_32x32x16_bf16 v[32:47], v[124:127], v[112:115], v[32:47]
	v_mfma_f32_32x32x16_bf16 v[16:31], v[120:123], v[116:119], v[16:31]
	v_mfma_f32_32x32x16_bf16 v[0:15], v[124:127], v[116:119], v[0:15]
	ds_read_b128 v[112:115], v104
	ds_read_b128 v[116:119], v104 offset:4608
	ds_read_b128 v[120:123], v105 offset:41472
	ds_read_b128 v[124:127], v105 offset:36864
	ds_read_b128 v[128:131], v104 offset:32
	ds_read_b128 v[132:135], v104 offset:4640
	ds_read_b128 v[136:139], v105 offset:36896
	ds_read_b128 v[140:143], v105 offset:41504
	s_waitcnt lgkmcnt(4)
	v_mfma_f32_32x32x16_bf16 v[48:63], v[124:127], v[112:115], v[48:63]
	v_mfma_f32_32x32x16_bf16 v[32:47], v[120:123], v[112:115], v[32:47]
	v_mfma_f32_32x32x16_bf16 v[16:31], v[124:127], v[116:119], v[16:31]
	v_mfma_f32_32x32x16_bf16 v[0:15], v[120:123], v[116:119], v[0:15]
	global_load_dwordx4 v[112:115], v64, s[14:15] offset:1024
	global_load_dwordx4 v[116:119], v68, s[14:15] offset:1024
	global_load_dwordx4 v[120:123], v72, s[14:15] offset:1024
	global_load_dwordx4 v[124:127], v76, s[14:15] offset:1024
	global_load_dwordx4 v[144:147], v64, s[12:13] offset:1024
	global_load_dwordx4 v[148:151], v68, s[12:13] offset:1024
	global_load_dwordx4 v[152:155], v72, s[12:13] offset:1024
	global_load_dwordx4 v[156:159], v76, s[12:13] offset:1024
	ds_read_b128 v[180:183], v104 offset:64
	ds_read_b128 v[210:213], v104 offset:4672
	ds_read_b128 v[214:217], v105 offset:36928
	ds_read_b128 v[218:221], v105 offset:41536
	s_waitcnt vmcnt(15)
	ds_write_b128 v106, v[78:81] offset:18432
	s_waitcnt vmcnt(14)
	ds_write_b128 v106, v[82:85] offset:23040
	s_waitcnt vmcnt(13)
	ds_write_b128 v106, v[86:89] offset:27648
	s_waitcnt vmcnt(12)
	ds_write_b128 v106, v[90:93] offset:32256
	s_waitcnt lgkmcnt(9)
	v_mfma_f32_32x32x16_bf16 v[48:63], v[136:139], v[128:131], v[48:63]
	s_waitcnt lgkmcnt(8)
	v_mfma_f32_32x32x16_bf16 v[32:47], v[140:143], v[128:131], v[32:47]
	v_mfma_f32_32x32x16_bf16 v[16:31], v[136:139], v[132:135], v[16:31]
	v_mfma_f32_32x32x16_bf16 v[0:15], v[140:143], v[132:135], v[0:15]
	ds_read_b128 v[78:81], v104 offset:96
	ds_read_b128 v[82:85], v104 offset:4704
	ds_read_b128 v[86:89], v105 offset:36960
	ds_read_b128 v[90:93], v105 offset:41568
	s_waitcnt vmcnt(11)
	ds_write_b128 v106, v[164:167] offset:55296
	s_waitcnt vmcnt(10)
	ds_write_b128 v106, v[168:171] offset:59904
	s_waitcnt vmcnt(9)
	ds_write_b128 v106, v[172:175] offset:64512
	s_waitcnt vmcnt(8)
	ds_write_b128 v107, v[176:179] offset:13824
	s_waitcnt lgkmcnt(13)
	v_mfma_f32_32x32x16_bf16 v[48:63], v[214:217], v[180:183], v[48:63]
	s_waitcnt lgkmcnt(0)
	s_barrier
	v_mfma_f32_32x32x16_bf16 v[32:47], v[218:221], v[180:183], v[32:47]
	v_mfma_f32_32x32x16_bf16 v[16:31], v[214:217], v[210:213], v[16:31]
	v_mfma_f32_32x32x16_bf16 v[0:15], v[218:221], v[210:213], v[0:15]
	v_mfma_f32_32x32x16_bf16 v[48:63], v[86:89], v[78:81], v[48:63]
	v_mfma_f32_32x32x16_bf16 v[32:47], v[90:93], v[78:81], v[32:47]
	v_mfma_f32_32x32x16_bf16 v[16:31], v[86:89], v[82:85], v[16:31]
	v_mfma_f32_32x32x16_bf16 v[0:15], v[90:93], v[82:85], v[0:15]
	ds_read_b128 v[78:81], v104 offset:18432
	ds_read_b128 v[82:85], v104 offset:23040
	ds_read_b128 v[86:89], v105 offset:59904
	ds_read_b128 v[90:93], v105 offset:55296
	ds_read_b128 v[128:131], v104 offset:18464
	ds_read_b128 v[132:135], v104 offset:23072
	ds_read_b128 v[136:139], v105 offset:55328
	ds_read_b128 v[140:143], v105 offset:59936
	s_waitcnt lgkmcnt(4)
	v_mfma_f32_32x32x16_bf16 v[48:63], v[90:93], v[78:81], v[48:63]
	v_mfma_f32_32x32x16_bf16 v[32:47], v[86:89], v[78:81], v[32:47]
	v_mfma_f32_32x32x16_bf16 v[16:31], v[90:93], v[82:85], v[16:31]
	v_mfma_f32_32x32x16_bf16 v[0:15], v[86:89], v[82:85], v[0:15]
	global_load_dwordx4 v[78:81], v64, s[14:15] offset:1152
	global_load_dwordx4 v[82:85], v68, s[14:15] offset:1152
	global_load_dwordx4 v[86:89], v72, s[14:15] offset:1152
	global_load_dwordx4 v[90:93], v76, s[14:15] offset:1152
	global_load_dwordx4 v[164:167], v64, s[12:13] offset:1152
	global_load_dwordx4 v[168:171], v68, s[12:13] offset:1152
	global_load_dwordx4 v[172:175], v72, s[12:13] offset:1152
	global_load_dwordx4 v[176:179], v76, s[12:13] offset:1152
	ds_read_b128 v[180:183], v104 offset:18496
	ds_read_b128 v[210:213], v104 offset:23104
	ds_read_b128 v[214:217], v105 offset:55360
	ds_read_b128 v[218:221], v105 offset:59968
	s_waitcnt vmcnt(15)
	ds_write_b128 v106, v[112:115]
	s_waitcnt vmcnt(14)
	ds_write_b128 v106, v[116:119] offset:4608
	s_waitcnt vmcnt(13)
	ds_write_b128 v106, v[120:123] offset:9216
	s_waitcnt vmcnt(12)
	ds_write_b128 v106, v[124:127] offset:13824
	s_waitcnt lgkmcnt(9)
	v_mfma_f32_32x32x16_bf16 v[48:63], v[136:139], v[128:131], v[48:63]
	s_waitcnt lgkmcnt(8)
	v_mfma_f32_32x32x16_bf16 v[32:47], v[140:143], v[128:131], v[32:47]
	v_mfma_f32_32x32x16_bf16 v[16:31], v[136:139], v[132:135], v[16:31]
	v_mfma_f32_32x32x16_bf16 v[0:15], v[140:143], v[132:135], v[0:15]
	ds_read_b128 v[112:115], v104 offset:18528
	ds_read_b128 v[116:119], v104 offset:23136
	ds_read_b128 v[120:123], v105 offset:55392
	ds_read_b128 v[124:127], v105 offset:60000
	s_waitcnt vmcnt(11)
	ds_write_b128 v106, v[144:147] offset:36864
	s_waitcnt vmcnt(10)
	ds_write_b128 v106, v[148:151] offset:41472
	s_waitcnt vmcnt(9)
	ds_write_b128 v106, v[152:155] offset:46080
	s_waitcnt vmcnt(8)
	ds_write_b128 v106, v[156:159] offset:50688
	s_waitcnt lgkmcnt(13)
	v_mfma_f32_32x32x16_bf16 v[48:63], v[214:217], v[180:183], v[48:63]
	s_waitcnt lgkmcnt(0)
	s_barrier
	v_mfma_f32_32x32x16_bf16 v[32:47], v[218:221], v[180:183], v[32:47]
	v_mfma_f32_32x32x16_bf16 v[16:31], v[214:217], v[210:213], v[16:31]
	v_mfma_f32_32x32x16_bf16 v[0:15], v[218:221], v[210:213], v[0:15]
	v_mfma_f32_32x32x16_bf16 v[48:63], v[120:123], v[112:115], v[48:63]
	v_mfma_f32_32x32x16_bf16 v[32:47], v[124:127], v[112:115], v[32:47]
	v_mfma_f32_32x32x16_bf16 v[16:31], v[120:123], v[116:119], v[16:31]
	v_mfma_f32_32x32x16_bf16 v[0:15], v[124:127], v[116:119], v[0:15]
	ds_read_b128 v[112:115], v104
	ds_read_b128 v[116:119], v104 offset:4608
	ds_read_b128 v[120:123], v105 offset:41472
	ds_read_b128 v[124:127], v105 offset:36864
	ds_read_b128 v[128:131], v104 offset:32
	ds_read_b128 v[132:135], v104 offset:4640
	ds_read_b128 v[136:139], v105 offset:36896
	ds_read_b128 v[140:143], v105 offset:41504
	s_waitcnt lgkmcnt(4)
	v_mfma_f32_32x32x16_bf16 v[48:63], v[124:127], v[112:115], v[48:63]
	v_mfma_f32_32x32x16_bf16 v[32:47], v[120:123], v[112:115], v[32:47]
	v_mfma_f32_32x32x16_bf16 v[16:31], v[124:127], v[116:119], v[16:31]
	v_mfma_f32_32x32x16_bf16 v[0:15], v[120:123], v[116:119], v[0:15]
	global_load_dwordx4 v[112:115], v64, s[14:15] offset:1280
	global_load_dwordx4 v[116:119], v68, s[14:15] offset:1280
	global_load_dwordx4 v[120:123], v72, s[14:15] offset:1280
	global_load_dwordx4 v[124:127], v76, s[14:15] offset:1280
	global_load_dwordx4 v[144:147], v64, s[12:13] offset:1280
	global_load_dwordx4 v[148:151], v68, s[12:13] offset:1280
	global_load_dwordx4 v[152:155], v72, s[12:13] offset:1280
	global_load_dwordx4 v[156:159], v76, s[12:13] offset:1280
	ds_read_b128 v[180:183], v104 offset:64
	ds_read_b128 v[210:213], v104 offset:4672
	ds_read_b128 v[214:217], v105 offset:36928
	ds_read_b128 v[218:221], v105 offset:41536
	s_waitcnt vmcnt(15)
	ds_write_b128 v106, v[78:81] offset:18432
	s_waitcnt vmcnt(14)
	ds_write_b128 v106, v[82:85] offset:23040
	s_waitcnt vmcnt(13)
	ds_write_b128 v106, v[86:89] offset:27648
	s_waitcnt vmcnt(12)
	ds_write_b128 v106, v[90:93] offset:32256
	s_waitcnt lgkmcnt(9)
	v_mfma_f32_32x32x16_bf16 v[48:63], v[136:139], v[128:131], v[48:63]
	s_waitcnt lgkmcnt(8)
	v_mfma_f32_32x32x16_bf16 v[32:47], v[140:143], v[128:131], v[32:47]
	v_mfma_f32_32x32x16_bf16 v[16:31], v[136:139], v[132:135], v[16:31]
	v_mfma_f32_32x32x16_bf16 v[0:15], v[140:143], v[132:135], v[0:15]
	ds_read_b128 v[78:81], v104 offset:96
	ds_read_b128 v[82:85], v104 offset:4704
	ds_read_b128 v[86:89], v105 offset:36960
	ds_read_b128 v[90:93], v105 offset:41568
	s_waitcnt vmcnt(11)
	ds_write_b128 v106, v[164:167] offset:55296
	s_waitcnt vmcnt(10)
	ds_write_b128 v106, v[168:171] offset:59904
	s_waitcnt vmcnt(9)
	ds_write_b128 v106, v[172:175] offset:64512
	s_waitcnt vmcnt(8)
	ds_write_b128 v107, v[176:179] offset:13824
	s_waitcnt lgkmcnt(13)
	v_mfma_f32_32x32x16_bf16 v[48:63], v[214:217], v[180:183], v[48:63]
	s_waitcnt lgkmcnt(0)
	s_barrier
	v_mfma_f32_32x32x16_bf16 v[32:47], v[218:221], v[180:183], v[32:47]
	v_mfma_f32_32x32x16_bf16 v[16:31], v[214:217], v[210:213], v[16:31]
	v_mfma_f32_32x32x16_bf16 v[0:15], v[218:221], v[210:213], v[0:15]
	v_mfma_f32_32x32x16_bf16 v[48:63], v[86:89], v[78:81], v[48:63]
	v_mfma_f32_32x32x16_bf16 v[32:47], v[90:93], v[78:81], v[32:47]
	v_mfma_f32_32x32x16_bf16 v[16:31], v[86:89], v[82:85], v[16:31]
	v_mfma_f32_32x32x16_bf16 v[0:15], v[90:93], v[82:85], v[0:15]
	ds_read_b128 v[78:81], v104 offset:18432
	ds_read_b128 v[82:85], v104 offset:23040
	ds_read_b128 v[86:89], v105 offset:59904
	ds_read_b128 v[90:93], v105 offset:55296
	ds_read_b128 v[128:131], v104 offset:18464
	ds_read_b128 v[132:135], v104 offset:23072
	ds_read_b128 v[136:139], v105 offset:55328
	ds_read_b128 v[140:143], v105 offset:59936
	s_waitcnt lgkmcnt(4)
	v_mfma_f32_32x32x16_bf16 v[48:63], v[90:93], v[78:81], v[48:63]
	v_mfma_f32_32x32x16_bf16 v[32:47], v[86:89], v[78:81], v[32:47]
	v_mfma_f32_32x32x16_bf16 v[16:31], v[90:93], v[82:85], v[16:31]
	v_mfma_f32_32x32x16_bf16 v[0:15], v[86:89], v[82:85], v[0:15]
	global_load_dwordx4 v[78:81], v64, s[14:15] offset:1408
	global_load_dwordx4 v[82:85], v68, s[14:15] offset:1408
	global_load_dwordx4 v[86:89], v72, s[14:15] offset:1408
	global_load_dwordx4 v[90:93], v76, s[14:15] offset:1408
	global_load_dwordx4 v[164:167], v64, s[12:13] offset:1408
	global_load_dwordx4 v[168:171], v68, s[12:13] offset:1408
	global_load_dwordx4 v[172:175], v72, s[12:13] offset:1408
	global_load_dwordx4 v[176:179], v76, s[12:13] offset:1408
	ds_read_b128 v[180:183], v104 offset:18496
	ds_read_b128 v[210:213], v104 offset:23104
	ds_read_b128 v[214:217], v105 offset:55360
	ds_read_b128 v[218:221], v105 offset:59968
	s_waitcnt vmcnt(15)
	ds_write_b128 v106, v[112:115]
	s_waitcnt vmcnt(14)
	ds_write_b128 v106, v[116:119] offset:4608
	s_waitcnt vmcnt(13)
	ds_write_b128 v106, v[120:123] offset:9216
	s_waitcnt vmcnt(12)
	ds_write_b128 v106, v[124:127] offset:13824
	s_waitcnt lgkmcnt(9)
	v_mfma_f32_32x32x16_bf16 v[48:63], v[136:139], v[128:131], v[48:63]
	s_waitcnt lgkmcnt(8)
	v_mfma_f32_32x32x16_bf16 v[32:47], v[140:143], v[128:131], v[32:47]
	v_mfma_f32_32x32x16_bf16 v[16:31], v[136:139], v[132:135], v[16:31]
	v_mfma_f32_32x32x16_bf16 v[0:15], v[140:143], v[132:135], v[0:15]
	ds_read_b128 v[112:115], v104 offset:18528
	ds_read_b128 v[116:119], v104 offset:23136
	ds_read_b128 v[120:123], v105 offset:55392
	ds_read_b128 v[124:127], v105 offset:60000
	s_waitcnt vmcnt(11)
	ds_write_b128 v106, v[144:147] offset:36864
	s_waitcnt vmcnt(10)
	ds_write_b128 v106, v[148:151] offset:41472
	s_waitcnt vmcnt(9)
	ds_write_b128 v106, v[152:155] offset:46080
	s_waitcnt vmcnt(8)
	ds_write_b128 v106, v[156:159] offset:50688
	s_waitcnt lgkmcnt(13)
	v_mfma_f32_32x32x16_bf16 v[48:63], v[214:217], v[180:183], v[48:63]
	s_waitcnt lgkmcnt(0)
	s_barrier
	v_mfma_f32_32x32x16_bf16 v[32:47], v[218:221], v[180:183], v[32:47]
	v_mfma_f32_32x32x16_bf16 v[16:31], v[214:217], v[210:213], v[16:31]
	v_mfma_f32_32x32x16_bf16 v[0:15], v[218:221], v[210:213], v[0:15]
	v_mfma_f32_32x32x16_bf16 v[48:63], v[120:123], v[112:115], v[48:63]
	v_mfma_f32_32x32x16_bf16 v[32:47], v[124:127], v[112:115], v[32:47]
	v_mfma_f32_32x32x16_bf16 v[16:31], v[120:123], v[116:119], v[16:31]
	v_mfma_f32_32x32x16_bf16 v[0:15], v[124:127], v[116:119], v[0:15]
	ds_read_b128 v[112:115], v104
	ds_read_b128 v[116:119], v104 offset:4608
	ds_read_b128 v[120:123], v105 offset:41472
	ds_read_b128 v[124:127], v105 offset:36864
	ds_read_b128 v[128:131], v104 offset:32
	ds_read_b128 v[132:135], v104 offset:4640
	ds_read_b128 v[136:139], v105 offset:36896
	ds_read_b128 v[140:143], v105 offset:41504
	s_waitcnt lgkmcnt(4)
	v_mfma_f32_32x32x16_bf16 v[48:63], v[124:127], v[112:115], v[48:63]
	v_mfma_f32_32x32x16_bf16 v[32:47], v[120:123], v[112:115], v[32:47]
	v_mfma_f32_32x32x16_bf16 v[16:31], v[124:127], v[116:119], v[16:31]
	v_mfma_f32_32x32x16_bf16 v[0:15], v[120:123], v[116:119], v[0:15]
	global_load_dwordx4 v[112:115], v64, s[14:15] offset:1536
	global_load_dwordx4 v[116:119], v68, s[14:15] offset:1536
	global_load_dwordx4 v[120:123], v72, s[14:15] offset:1536
	global_load_dwordx4 v[124:127], v76, s[14:15] offset:1536
	global_load_dwordx4 v[144:147], v64, s[12:13] offset:1536
	global_load_dwordx4 v[148:151], v68, s[12:13] offset:1536
	global_load_dwordx4 v[152:155], v72, s[12:13] offset:1536
	global_load_dwordx4 v[156:159], v76, s[12:13] offset:1536
	ds_read_b128 v[180:183], v104 offset:64
	ds_read_b128 v[210:213], v104 offset:4672
	ds_read_b128 v[214:217], v105 offset:36928
	ds_read_b128 v[218:221], v105 offset:41536
	s_waitcnt vmcnt(15)
	ds_write_b128 v106, v[78:81] offset:18432
	s_waitcnt vmcnt(14)
	ds_write_b128 v106, v[82:85] offset:23040
	s_waitcnt vmcnt(13)
	ds_write_b128 v106, v[86:89] offset:27648
	s_waitcnt vmcnt(12)
	ds_write_b128 v106, v[90:93] offset:32256
	s_waitcnt lgkmcnt(9)
	v_mfma_f32_32x32x16_bf16 v[48:63], v[136:139], v[128:131], v[48:63]
	s_waitcnt lgkmcnt(8)
	v_mfma_f32_32x32x16_bf16 v[32:47], v[140:143], v[128:131], v[32:47]
	v_mfma_f32_32x32x16_bf16 v[16:31], v[136:139], v[132:135], v[16:31]
	v_mfma_f32_32x32x16_bf16 v[0:15], v[140:143], v[132:135], v[0:15]
	ds_read_b128 v[78:81], v104 offset:96
	ds_read_b128 v[82:85], v104 offset:4704
	ds_read_b128 v[86:89], v105 offset:36960
	ds_read_b128 v[90:93], v105 offset:41568
	s_waitcnt vmcnt(11)
	ds_write_b128 v106, v[164:167] offset:55296
	s_waitcnt vmcnt(10)
	ds_write_b128 v106, v[168:171] offset:59904
	s_waitcnt vmcnt(9)
	ds_write_b128 v106, v[172:175] offset:64512
	s_waitcnt vmcnt(8)
	ds_write_b128 v107, v[176:179] offset:13824
	s_waitcnt lgkmcnt(13)
	v_mfma_f32_32x32x16_bf16 v[48:63], v[214:217], v[180:183], v[48:63]
	s_waitcnt lgkmcnt(0)
	s_barrier
	v_mfma_f32_32x32x16_bf16 v[32:47], v[218:221], v[180:183], v[32:47]
	v_mfma_f32_32x32x16_bf16 v[16:31], v[214:217], v[210:213], v[16:31]
	v_mfma_f32_32x32x16_bf16 v[0:15], v[218:221], v[210:213], v[0:15]
	v_mfma_f32_32x32x16_bf16 v[48:63], v[86:89], v[78:81], v[48:63]
	v_mfma_f32_32x32x16_bf16 v[32:47], v[90:93], v[78:81], v[32:47]
	v_mfma_f32_32x32x16_bf16 v[16:31], v[86:89], v[82:85], v[16:31]
	v_mfma_f32_32x32x16_bf16 v[0:15], v[90:93], v[82:85], v[0:15]
	ds_read_b128 v[78:81], v104 offset:18432
	ds_read_b128 v[82:85], v104 offset:23040
	ds_read_b128 v[86:89], v105 offset:59904
	ds_read_b128 v[90:93], v105 offset:55296
	ds_read_b128 v[128:131], v104 offset:18464
	ds_read_b128 v[132:135], v104 offset:23072
	ds_read_b128 v[136:139], v105 offset:55328
	ds_read_b128 v[140:143], v105 offset:59936
	s_waitcnt lgkmcnt(4)
	v_mfma_f32_32x32x16_bf16 v[48:63], v[90:93], v[78:81], v[48:63]
	v_mfma_f32_32x32x16_bf16 v[32:47], v[86:89], v[78:81], v[32:47]
	v_mfma_f32_32x32x16_bf16 v[16:31], v[90:93], v[82:85], v[16:31]
	v_mfma_f32_32x32x16_bf16 v[0:15], v[86:89], v[82:85], v[0:15]
	global_load_dwordx4 v[78:81], v64, s[14:15] offset:1664
	global_load_dwordx4 v[82:85], v68, s[14:15] offset:1664
	global_load_dwordx4 v[86:89], v72, s[14:15] offset:1664
	global_load_dwordx4 v[90:93], v76, s[14:15] offset:1664
	global_load_dwordx4 v[164:167], v64, s[12:13] offset:1664
	global_load_dwordx4 v[168:171], v68, s[12:13] offset:1664
	global_load_dwordx4 v[172:175], v72, s[12:13] offset:1664
	global_load_dwordx4 v[176:179], v76, s[12:13] offset:1664
	ds_read_b128 v[180:183], v104 offset:18496
	ds_read_b128 v[210:213], v104 offset:23104
	ds_read_b128 v[214:217], v105 offset:55360
	ds_read_b128 v[218:221], v105 offset:59968
	s_waitcnt vmcnt(15)
	ds_write_b128 v106, v[112:115]
	s_waitcnt vmcnt(14)
	ds_write_b128 v106, v[116:119] offset:4608
	s_waitcnt vmcnt(13)
	ds_write_b128 v106, v[120:123] offset:9216
	s_waitcnt vmcnt(12)
	ds_write_b128 v106, v[124:127] offset:13824
	s_waitcnt lgkmcnt(9)
	v_mfma_f32_32x32x16_bf16 v[48:63], v[136:139], v[128:131], v[48:63]
	s_waitcnt lgkmcnt(8)
	v_mfma_f32_32x32x16_bf16 v[32:47], v[140:143], v[128:131], v[32:47]
	v_mfma_f32_32x32x16_bf16 v[16:31], v[136:139], v[132:135], v[16:31]
	v_mfma_f32_32x32x16_bf16 v[0:15], v[140:143], v[132:135], v[0:15]
	ds_read_b128 v[112:115], v104 offset:18528
	ds_read_b128 v[116:119], v104 offset:23136
	ds_read_b128 v[120:123], v105 offset:55392
	ds_read_b128 v[124:127], v105 offset:60000
	s_waitcnt vmcnt(11)
	ds_write_b128 v106, v[144:147] offset:36864
	s_waitcnt vmcnt(10)
	ds_write_b128 v106, v[148:151] offset:41472
	s_waitcnt vmcnt(9)
	ds_write_b128 v106, v[152:155] offset:46080
	s_waitcnt vmcnt(8)
	ds_write_b128 v106, v[156:159] offset:50688
	s_waitcnt lgkmcnt(13)
	v_mfma_f32_32x32x16_bf16 v[48:63], v[214:217], v[180:183], v[48:63]
	s_waitcnt lgkmcnt(0)
	s_barrier
	v_mfma_f32_32x32x16_bf16 v[32:47], v[218:221], v[180:183], v[32:47]
	v_mfma_f32_32x32x16_bf16 v[16:31], v[214:217], v[210:213], v[16:31]
	v_mfma_f32_32x32x16_bf16 v[0:15], v[218:221], v[210:213], v[0:15]
	v_mfma_f32_32x32x16_bf16 v[48:63], v[120:123], v[112:115], v[48:63]
	v_mfma_f32_32x32x16_bf16 v[32:47], v[124:127], v[112:115], v[32:47]
	v_mfma_f32_32x32x16_bf16 v[16:31], v[120:123], v[116:119], v[16:31]
	v_mfma_f32_32x32x16_bf16 v[0:15], v[124:127], v[116:119], v[0:15]
	ds_read_b128 v[112:115], v104
	ds_read_b128 v[116:119], v104 offset:4608
	ds_read_b128 v[120:123], v105 offset:41472
	ds_read_b128 v[124:127], v105 offset:36864
	ds_read_b128 v[128:131], v104 offset:32
	ds_read_b128 v[132:135], v104 offset:4640
	ds_read_b128 v[136:139], v105 offset:36896
	ds_read_b128 v[140:143], v105 offset:41504
	s_waitcnt lgkmcnt(4)
	v_mfma_f32_32x32x16_bf16 v[48:63], v[124:127], v[112:115], v[48:63]
	v_mfma_f32_32x32x16_bf16 v[32:47], v[120:123], v[112:115], v[32:47]
	v_mfma_f32_32x32x16_bf16 v[16:31], v[124:127], v[116:119], v[16:31]
	v_mfma_f32_32x32x16_bf16 v[0:15], v[120:123], v[116:119], v[0:15]
	global_load_dwordx4 v[112:115], v64, s[14:15] offset:1792
	global_load_dwordx4 v[116:119], v68, s[14:15] offset:1792
	global_load_dwordx4 v[120:123], v72, s[14:15] offset:1792
	global_load_dwordx4 v[124:127], v76, s[14:15] offset:1792
	global_load_dwordx4 v[144:147], v64, s[12:13] offset:1792
	global_load_dwordx4 v[148:151], v68, s[12:13] offset:1792
	global_load_dwordx4 v[152:155], v72, s[12:13] offset:1792
	global_load_dwordx4 v[156:159], v76, s[12:13] offset:1792
	ds_read_b128 v[180:183], v104 offset:64
	ds_read_b128 v[210:213], v104 offset:4672
	ds_read_b128 v[214:217], v105 offset:36928
	ds_read_b128 v[218:221], v105 offset:41536
	s_waitcnt vmcnt(15)
	ds_write_b128 v106, v[78:81] offset:18432
	s_waitcnt vmcnt(14)
	ds_write_b128 v106, v[82:85] offset:23040
	s_waitcnt vmcnt(13)
	ds_write_b128 v106, v[86:89] offset:27648
	s_waitcnt vmcnt(12)
	ds_write_b128 v106, v[90:93] offset:32256
	s_waitcnt lgkmcnt(9)
	v_mfma_f32_32x32x16_bf16 v[48:63], v[136:139], v[128:131], v[48:63]
	s_waitcnt lgkmcnt(8)
	v_mfma_f32_32x32x16_bf16 v[32:47], v[140:143], v[128:131], v[32:47]
	v_mfma_f32_32x32x16_bf16 v[16:31], v[136:139], v[132:135], v[16:31]
	v_mfma_f32_32x32x16_bf16 v[0:15], v[140:143], v[132:135], v[0:15]
	ds_read_b128 v[78:81], v104 offset:96
	ds_read_b128 v[82:85], v104 offset:4704
	ds_read_b128 v[86:89], v105 offset:36960
	ds_read_b128 v[90:93], v105 offset:41568
	s_waitcnt vmcnt(11)
	ds_write_b128 v106, v[164:167] offset:55296
	s_waitcnt vmcnt(10)
	ds_write_b128 v106, v[168:171] offset:59904
	s_waitcnt vmcnt(9)
	ds_write_b128 v106, v[172:175] offset:64512
	s_waitcnt vmcnt(8)
	ds_write_b128 v107, v[176:179] offset:13824
	s_waitcnt lgkmcnt(13)
	v_mfma_f32_32x32x16_bf16 v[48:63], v[214:217], v[180:183], v[48:63]
	s_waitcnt lgkmcnt(0)
	s_barrier
	v_mfma_f32_32x32x16_bf16 v[32:47], v[218:221], v[180:183], v[32:47]
	v_mfma_f32_32x32x16_bf16 v[16:31], v[214:217], v[210:213], v[16:31]
	v_mfma_f32_32x32x16_bf16 v[0:15], v[218:221], v[210:213], v[0:15]
	v_mfma_f32_32x32x16_bf16 v[48:63], v[86:89], v[78:81], v[48:63]
	v_mfma_f32_32x32x16_bf16 v[32:47], v[90:93], v[78:81], v[32:47]
	v_mfma_f32_32x32x16_bf16 v[16:31], v[86:89], v[82:85], v[16:31]
	v_mfma_f32_32x32x16_bf16 v[0:15], v[90:93], v[82:85], v[0:15]
	ds_read_b128 v[82:85], v104 offset:23040
	ds_read_b128 v[86:89], v105 offset:59904
	ds_read_b128 v[90:93], v105 offset:55296
	ds_read_b128 v[78:81], v104 offset:18432
	ds_read_b128 v[132:135], v104 offset:23072
	ds_read_b128 v[128:131], v104 offset:18464
	ds_read_b128 v[136:139], v105 offset:55328
	ds_read_b128 v[140:143], v105 offset:59936
	s_waitcnt lgkmcnt(5)
	v_mfma_f32_32x32x16_bf16 v[16:31], v[90:93], v[82:85], v[16:31]
	v_mfma_f32_32x32x16_bf16 v[0:15], v[86:89], v[82:85], v[0:15]
	s_waitcnt lgkmcnt(4)
	v_mfma_f32_32x32x16_bf16 v[48:63], v[90:93], v[78:81], v[48:63]
	v_mfma_f32_32x32x16_bf16 v[32:47], v[86:89], v[78:81], v[32:47]
	global_load_dwordx4 v[80:83], v64, s[14:15] offset:1920
	global_load_dwordx4 v[84:87], v68, s[14:15] offset:1920
	global_load_dwordx4 v[88:91], v72, s[14:15] offset:1920
	global_load_dwordx4 v[92:95], v76, s[14:15] offset:1920
	s_nop 0
	global_load_dwordx4 v[64:67], v64, s[12:13] offset:1920
	s_nop 0
	global_load_dwordx4 v[68:71], v68, s[12:13] offset:1920
	s_nop 0
	global_load_dwordx4 v[72:75], v72, s[12:13] offset:1920
	s_nop 0
	global_load_dwordx4 v[76:79], v76, s[12:13] offset:1920
	ds_read_b128 v[168:171], v104 offset:23104
	ds_read_b128 v[164:167], v104 offset:18496
	ds_read_b128 v[172:175], v105 offset:55360
	ds_read_b128 v[176:179], v105 offset:59968
	s_waitcnt vmcnt(15)
	ds_write_b128 v106, v[112:115]
	s_waitcnt vmcnt(14)
	ds_write_b128 v106, v[116:119] offset:4608
	s_waitcnt vmcnt(13)
	ds_write_b128 v106, v[120:123] offset:9216
	s_waitcnt vmcnt(12)
	ds_write_b128 v106, v[124:127] offset:13824
	s_waitcnt lgkmcnt(9)
	v_mfma_f32_32x32x16_bf16 v[16:31], v[136:139], v[132:135], v[16:31]
	s_waitcnt lgkmcnt(8)
	v_mfma_f32_32x32x16_bf16 v[0:15], v[140:143], v[132:135], v[0:15]
	ds_read_b128 v[116:119], v104 offset:23136
	ds_read_b128 v[112:115], v104 offset:18528
	ds_read_b128 v[120:123], v105 offset:55392
	ds_read_b128 v[124:127], v105 offset:60000
	s_waitcnt vmcnt(11)
	ds_write_b128 v106, v[144:147] offset:36864
	s_waitcnt vmcnt(10)
	ds_write_b128 v106, v[148:151] offset:41472
	s_waitcnt vmcnt(9)
	ds_write_b128 v106, v[152:155] offset:46080
	s_waitcnt vmcnt(8)
	ds_write_b128 v106, v[156:159] offset:50688
	s_waitcnt lgkmcnt(13)
	v_mfma_f32_32x32x16_bf16 v[16:31], v[172:175], v[168:171], v[16:31]
	s_waitcnt lgkmcnt(0)
	s_barrier
	v_mfma_f32_32x32x16_bf16 v[0:15], v[176:179], v[168:171], v[0:15]
	v_mfma_f32_32x32x16_bf16 v[16:31], v[120:123], v[116:119], v[16:31]
	v_mfma_f32_32x32x16_bf16 v[0:15], v[124:127], v[116:119], v[0:15]
	ds_read_b128 v[116:119], v105 offset:36864
	v_mfma_f32_32x32x16_bf16 v[48:63], v[136:139], v[128:131], v[48:63]
	v_mfma_f32_32x32x16_bf16 v[48:63], v[172:175], v[164:167], v[48:63]
	v_mfma_f32_32x32x16_bf16 v[48:63], v[120:123], v[112:115], v[48:63]
	ds_read_b128 v[120:123], v105 offset:41472
	v_mfma_f32_32x32x16_bf16 v[32:47], v[140:143], v[128:131], v[32:47]
	v_mfma_f32_32x32x16_bf16 v[32:47], v[176:179], v[164:167], v[32:47]
	v_mfma_f32_32x32x16_bf16 v[32:47], v[124:127], v[112:115], v[32:47]
	ds_read_b128 v[112:115], v104
	s_waitcnt lgkmcnt(0)
	v_mfma_f32_32x32x16_bf16 v[48:63], v[116:119], v[112:115], v[48:63]
	v_mfma_f32_32x32x16_bf16 v[32:47], v[120:123], v[112:115], v[32:47]
	ds_read_b128 v[112:115], v104 offset:4608
	s_waitcnt lgkmcnt(0)
	v_mfma_f32_32x32x16_bf16 v[0:15], v[120:123], v[112:115], v[0:15]
	ds_read_b128 v[120:123], v105 offset:41504
	v_mfma_f32_32x32x16_bf16 v[16:31], v[116:119], v[112:115], v[16:31]
	ds_read_b128 v[112:115], v104 offset:32
	ds_read_b128 v[116:119], v105 offset:36896
	s_waitcnt lgkmcnt(0)
	v_mfma_f32_32x32x16_bf16 v[48:63], v[116:119], v[112:115], v[48:63]
	v_mfma_f32_32x32x16_bf16 v[32:47], v[120:123], v[112:115], v[32:47]
	ds_read_b128 v[112:115], v104 offset:4640
	s_waitcnt lgkmcnt(0)
	v_mfma_f32_32x32x16_bf16 v[0:15], v[120:123], v[112:115], v[0:15]
	ds_read_b128 v[120:123], v105 offset:41536
	v_mfma_f32_32x32x16_bf16 v[16:31], v[116:119], v[112:115], v[16:31]
	ds_read_b128 v[112:115], v104 offset:64
	ds_read_b128 v[116:119], v105 offset:36928
	s_waitcnt lgkmcnt(1)
	v_mfma_f32_32x32x16_bf16 v[32:47], v[120:123], v[112:115], v[32:47]
	s_waitcnt lgkmcnt(0)
	v_mfma_f32_32x32x16_bf16 v[48:63], v[116:119], v[112:115], v[48:63]
	ds_read_b128 v[112:115], v104 offset:4672
	s_waitcnt vmcnt(7)
	ds_write_b128 v106, v[80:83] offset:18432
	s_waitcnt vmcnt(6)
	ds_write_b128 v106, v[84:87] offset:23040
	s_waitcnt vmcnt(5)
	ds_write_b128 v106, v[88:91] offset:27648
	s_waitcnt vmcnt(4)
	ds_write_b128 v106, v[92:95] offset:32256
	ds_read_b128 v[80:83], v104 offset:96
	ds_read_b128 v[84:87], v105 offset:36960
	ds_read_b128 v[88:91], v105 offset:41568
	s_waitcnt lgkmcnt(1)
	v_mfma_f32_32x32x16_bf16 v[48:63], v[84:87], v[80:83], v[48:63]
	s_waitcnt lgkmcnt(0)
	v_mfma_f32_32x32x16_bf16 v[32:47], v[88:91], v[80:83], v[32:47]
	ds_read_b128 v[80:83], v104 offset:4704
	s_waitcnt vmcnt(3)
	ds_write_b128 v106, v[64:67] offset:55296
	s_waitcnt vmcnt(2)
	ds_write_b128 v106, v[68:71] offset:59904
	s_waitcnt vmcnt(1)
	ds_write_b128 v106, v[72:75] offset:64512
	s_waitcnt vmcnt(0)
	ds_write_b128 v107, v[76:79] offset:13824
	s_waitcnt lgkmcnt(0)
	s_barrier
	ds_read_b128 v[64:67], v104 offset:18432
	ds_read_b128 v[68:71], v105 offset:55296
	ds_read_b128 v[72:75], v105 offset:59904
	s_waitcnt lgkmcnt(1)
	v_mfma_f32_32x32x16_bf16 v[48:63], v[68:71], v[64:67], v[48:63]
	s_waitcnt lgkmcnt(0)
	v_mfma_f32_32x32x16_bf16 v[32:47], v[72:75], v[64:67], v[32:47]
	ds_read_b128 v[64:67], v104 offset:23040
	v_mfma_f32_32x32x16_bf16 v[0:15], v[120:123], v[112:115], v[0:15]
	v_mfma_f32_32x32x16_bf16 v[0:15], v[88:91], v[80:83], v[0:15]
	s_waitcnt lgkmcnt(0)
	v_mfma_f32_32x32x16_bf16 v[0:15], v[72:75], v[64:67], v[0:15]
	ds_read_b128 v[72:75], v105 offset:59936
	v_mfma_f32_32x32x16_bf16 v[16:31], v[116:119], v[112:115], v[16:31]
	v_mfma_f32_32x32x16_bf16 v[16:31], v[84:87], v[80:83], v[16:31]
	v_or_b32_e32 v82, s7, v97
	v_mov_b32_e32 v86, 0
	v_cmp_lt_i32_e32 vcc, 7, v82
	v_mfma_f32_32x32x16_bf16 v[16:31], v[68:71], v[64:67], v[16:31]
	ds_read_b128 v[64:67], v104 offset:18464
	ds_read_b128 v[68:71], v105 offset:55328
	s_waitcnt lgkmcnt(0)
	v_mfma_f32_32x32x16_bf16 v[48:63], v[68:71], v[64:67], v[48:63]
	v_mfma_f32_32x32x16_bf16 v[32:47], v[72:75], v[64:67], v[32:47]
	ds_read_b128 v[64:67], v104 offset:23072
	s_waitcnt lgkmcnt(0)
	v_mfma_f32_32x32x16_bf16 v[0:15], v[72:75], v[64:67], v[0:15]
	ds_read_b128 v[72:75], v105 offset:59968
	v_mfma_f32_32x32x16_bf16 v[16:31], v[68:71], v[64:67], v[16:31]
	ds_read_b128 v[64:67], v104 offset:18496
	ds_read_b128 v[68:71], v105 offset:55360
	s_waitcnt lgkmcnt(0)
	v_mfma_f32_32x32x16_bf16 v[48:63], v[68:71], v[64:67], v[48:63]
	v_mfma_f32_32x32x16_bf16 v[32:47], v[72:75], v[64:67], v[32:47]
	ds_read_b128 v[64:67], v104 offset:23104
	s_waitcnt lgkmcnt(0)
	v_mfma_f32_32x32x16_bf16 v[0:15], v[72:75], v[64:67], v[0:15]
	ds_read_b128 v[72:75], v105 offset:55392
	v_mfma_f32_32x32x16_bf16 v[16:31], v[68:71], v[64:67], v[16:31]
	ds_read_b128 v[68:71], v104 offset:18528
	ds_read_b128 v[64:67], v105 offset:60000
	s_waitcnt lgkmcnt(1)
	v_mfma_f32_32x32x16_bf16 v[48:63], v[72:75], v[68:71], v[48:63]
	s_waitcnt lgkmcnt(0)
	v_mfma_f32_32x32x16_bf16 v[32:47], v[64:67], v[68:71], v[32:47]
	ds_read_b128 v[68:71], v104 offset:23136
	s_waitcnt lgkmcnt(0)
	s_barrier
	v_mfma_f32_32x32x16_bf16 v[16:31], v[72:75], v[68:71], v[16:31]
	v_mfma_f32_32x32x16_bf16 v[0:15], v[64:67], v[68:71], v[0:15]
	v_readfirstlane_b32 s12, v186
	v_and_b32_e32 v64, 31, v186
	v_bfe_u32 v65, v186, 5, 1
	s_lshr_b32 s12, s12, 6
	s_and_b32 s13, s12, 1
	s_lshr_b32 s12, s12, 1
	s_lshl_b32 s12, s12, 6
	v_add_u32_e32 v64, s12, v64
	s_lshr_b32 s30, s6, 13
	s_and_b32 s31, s6, 0x1fff
	s_nop 7
	s_cmp_lt_u32 s8, 4
	s_cbranch_scc1 .Lp2_aq
	s_cmp_lt_u32 s8, 10
	s_cbranch_scc1 .Lp2_akc
	s_cmp_lt_u32 s8, 14
	s_cbranch_scc1 .Lp2_bq
	s_cmp_eq_u32 s8, 14
	s_cbranch_scc1 .Lp2_bk
	s_cmp_eq_u32 s8, 15
	s_cbranch_scc1 .Lp2_bvt
	s_cmp_lt_u32 s8, 18
	s_cbranch_scc1 .Lp2_cq
	s_branch .Lp2_ckv
.Lp2_aq:
	s_mov_b32 s33, s8
	s_lshl_b32 s33, s33, 1
	s_add_u32 s33, s33, s13
	s_lshl_b32 s33, s33, 7
	s_lshl_b32 s34, s6, 10
	s_add_u32 s33, s33, s34
	s_add_u32 s33, s33, 0x4800000
	s_add_u32 s40, s88, s33
	s_addc_u32 s41, s89, 0
	s_movk_i32 s14, 0x400
	s_branch .Lp2_rope
.Lp2_bq:
	s_sub_u32 s33, s8, 10
	s_lshl_b32 s33, s33, 1
	s_add_u32 s33, s33, s13
	s_lshl_b32 s33, s33, 7
	s_lshl_b32 s34, s6, 10
	s_add_u32 s33, s33, s34
	s_add_u32 s33, s33, 0x7000000
	s_add_u32 s40, s88, s33
	s_addc_u32 s41, s89, 0
	s_movk_i32 s14, 0x400
	s_branch .Lp2_rope
.Lp2_akc:
	s_sub_u32 s35, s8, 4
	s_lshl_b32 s33, s35, 22
	s_add_u32 s33, s33, 0x5800000
	s_cmp_eq_u32 s35, 3
	s_cbranch_scc1 .Lp2_trans_setup
	s_cmp_eq_u32 s35, 5
	s_cbranch_scc1 .Lp2_trans_setup
	s_cmp_eq_u32 s35, 1
	s_cselect_b32 s52, 1, 0
	s_lshl_b32 s34, s30, 1
	s_add_u32 s34, s34, s13
	s_lshl_b32 s34, s34, 20
	s_lshl_b32 s35, s31, 7
	s_add_u32 s34, s34, s35
	s_add_u32 s33, s33, s34
	s_add_u32 s40, s88, s33
	s_addc_u32 s41, s89, 0
	s_movk_i32 s14, 0x80
	s_cmp_eq_u32 s52, 1
	s_cbranch_scc1 .Lp2_plain
	s_branch .Lp2_rope
.Lp2_bk:
	s_mov_b32 s33, 0x8000000
	s_lshl_b32 s34, s30, 1
	s_add_u32 s34, s34, s13
	s_lshl_b32 s34, s34, 20
	s_lshl_b32 s35, s31, 7
	s_add_u32 s34, s34, s35
	s_add_u32 s33, s33, s34
	s_add_u32 s40, s88, s33
	s_addc_u32 s41, s89, 0
	s_movk_i32 s14, 0x80
	s_branch .Lp2_rope
.Lp2_bvt:
	s_mov_b32 s33, 0x8400000
	s_branch .Lp2_trans_setup
.Lp2_cq:
	s_sub_u32 s33, s8, 16
	s_lshl_b32 s33, s33, 1
	s_add_u32 s33, s33, s13
	s_lshl_b32 s33, s33, 7
	s_lshl_b32 s34, s6, 9
	s_add_u32 s33, s33, s34
	s_add_u32 s33, s33, 0x8800000
	s_add_u32 s40, s88, s33
	s_addc_u32 s41, s89, 0
	s_movk_i32 s14, 0x200
	s_branch .Lp2_plain
.Lp2_ckv:
	s_sub_u32 s33, s8, 18
	s_lshl_b32 s33, s33, 1
	s_add_u32 s33, s33, s13
	s_lshl_b32 s33, s33, 7
	s_lshl_b32 s34, s6, 9
	s_add_u32 s33, s33, s34
	s_add_u32 s33, s33, 0x9000000
	s_add_u32 s40, s88, s33
	s_addc_u32 s41, s89, 0
	s_movk_i32 s14, 0x200
	s_branch .Lp2_plain
.Lp2_rope:
	v_mul_lo_u32 v66, v64, s14
	v_lshl_add_u32 v66, v65, 3, v66
	s_lshl_b32 s15, s14, 5
	v_add_u32_e32 v67, s15, v66
	v_lshlrev_b32_e32 v68, 7, v64
	v_lshl_add_u32 v68, v65, 4, v68
	v_add_u32_e32 v69, 0x1000, v68
	s_lshl_b32 s33, s6, 7
	s_add_u32 s34, s33, 0xda00000
	s_add_u32 s68, s88, s34
	s_addc_u32 s69, s89, 0
	s_add_u32 s34, s33, 0xdc00000
	s_add_u32 s70, s88, s34
	s_addc_u32 s71, s89, 0
	global_load_dwordx4 v[96:99], v68, s[68:69]
	global_load_dwordx4 v[112:115], v68, s[70:71]
	global_load_dwordx4 v[100:103], v68, s[68:69] offset:32
	global_load_dwordx4 v[116:119], v68, s[70:71] offset:32
	global_load_dwordx4 v[104:107], v68, s[68:69] offset:64
	global_load_dwordx4 v[120:123], v68, s[70:71] offset:64
	global_load_dwordx4 v[108:111], v68, s[68:69] offset:96
	global_load_dwordx4 v[124:127], v68, s[70:71] offset:96
	s_waitcnt vmcnt(6)
	v_mul_f32_e32 v70, v32, v112
	v_mul_f32_e32 v71, v33, v113
	v_mul_f32_e32 v72, v34, v114
	v_mul_f32_e32 v73, v35, v115
	v_mul_f32_e32 v74, v48, v112
	v_mul_f32_e32 v75, v49, v113
	v_mul_f32_e32 v76, v50, v114
	v_mul_f32_e32 v77, v51, v115
	v_fma_f32 v70, v48, v96, -v70
	v_fma_f32 v71, v49, v97, -v71
	v_fma_f32 v72, v50, v98, -v72
	v_fma_f32 v73, v51, v99, -v73
	v_fmac_f32_e32 v74, v32, v96
	v_fmac_f32_e32 v75, v33, v97
	v_fmac_f32_e32 v76, v34, v98
	v_fmac_f32_e32 v77, v35, v99
	v_cvt_pk_bf16_f32 v78, v70, v71
	v_cvt_pk_bf16_f32 v79, v72, v73
	v_cvt_pk_bf16_f32 v80, v74, v75
	v_cvt_pk_bf16_f32 v81, v76, v77
	global_store_dwordx2 v66, v[78:79], s[40:41]
	global_store_dwordx2 v66, v[80:81], s[40:41] offset:64
	s_waitcnt vmcnt(6)
	v_mul_f32_e32 v70, v36, v116
	v_mul_f32_e32 v71, v37, v117
	v_mul_f32_e32 v72, v38, v118
	v_mul_f32_e32 v73, v39, v119
	v_mul_f32_e32 v74, v52, v116
	v_mul_f32_e32 v75, v53, v117
	v_mul_f32_e32 v76, v54, v118
	v_mul_f32_e32 v77, v55, v119
	v_fma_f32 v70, v52, v100, -v70
	v_fma_f32 v71, v53, v101, -v71
	v_fma_f32 v72, v54, v102, -v72
	v_fma_f32 v73, v55, v103, -v73
	v_fmac_f32_e32 v74, v36, v100
	v_fmac_f32_e32 v75, v37, v101
	v_fmac_f32_e32 v76, v38, v102
	v_fmac_f32_e32 v77, v39, v103
	v_cvt_pk_bf16_f32 v82, v70, v71
	v_cvt_pk_bf16_f32 v83, v72, v73
	v_cvt_pk_bf16_f32 v84, v74, v75
	v_cvt_pk_bf16_f32 v85, v76, v77
	global_store_dwordx2 v66, v[82:83], s[40:41] offset:16
	global_store_dwordx2 v66, v[84:85], s[40:41] offset:80
	s_waitcnt vmcnt(6)
	v_mul_f32_e32 v70, v40, v120
	v_mul_f32_e32 v71, v41, v121
	v_mul_f32_e32 v72, v42, v122
	v_mul_f32_e32 v73, v43, v123
	v_mul_f32_e32 v74, v56, v120
	v_mul_f32_e32 v75, v57, v121
	v_mul_f32_e32 v76, v58, v122
	v_mul_f32_e32 v77, v59, v123
	v_fma_f32 v70, v56, v104, -v70
	v_fma_f32 v71, v57, v105, -v71
	v_fma_f32 v72, v58, v106, -v72
	v_fma_f32 v73, v59, v107, -v73
	v_fmac_f32_e32 v74, v40, v104
	v_fmac_f32_e32 v75, v41, v105
	v_fmac_f32_e32 v76, v42, v106
	v_fmac_f32_e32 v77, v43, v107
	v_cvt_pk_bf16_f32 v78, v70, v71
	v_cvt_pk_bf16_f32 v79, v72, v73
	v_cvt_pk_bf16_f32 v80, v74, v75
	v_cvt_pk_bf16_f32 v81, v76, v77
	global_store_dwordx2 v66, v[78:79], s[40:41] offset:32
	global_store_dwordx2 v66, v[80:81], s[40:41] offset:96
	s_waitcnt vmcnt(6)
	v_mul_f32_e32 v70, v44, v124
	v_mul_f32_e32 v71, v45, v125
	v_mul_f32_e32 v72, v46, v126
	v_mul_f32_e32 v73, v47, v127
	v_mul_f32_e32 v74, v60, v124
	v_mul_f32_e32 v75, v61, v125
	v_mul_f32_e32 v76, v62, v126
	v_mul_f32_e32 v77, v63, v127
	v_fma_f32 v70, v60, v108, -v70
	v_fma_f32 v71, v61, v109, -v71
	v_fma_f32 v72, v62, v110, -v72
	v_fma_f32 v73, v63, v111, -v73
	v_fmac_f32_e32 v74, v44, v108
	v_fmac_f32_e32 v75, v45, v109
	v_fmac_f32_e32 v76, v46, v110
	v_fmac_f32_e32 v77, v47, v111
	v_cvt_pk_bf16_f32 v82, v70, v71
	v_cvt_pk_bf16_f32 v83, v72, v73
	v_cvt_pk_bf16_f32 v84, v74, v75
	v_cvt_pk_bf16_f32 v85, v76, v77
	global_store_dwordx2 v66, v[82:83], s[40:41] offset:48
	global_store_dwordx2 v66, v[84:85], s[40:41] offset:112
	global_load_dwordx4 v[96:99], v69, s[68:69]
	global_load_dwordx4 v[112:115], v69, s[70:71]
	global_load_dwordx4 v[100:103], v69, s[68:69] offset:32
	global_load_dwordx4 v[116:119], v69, s[70:71] offset:32
	global_load_dwordx4 v[104:107], v69, s[68:69] offset:64
	global_load_dwordx4 v[120:123], v69, s[70:71] offset:64
	global_load_dwordx4 v[108:111], v69, s[68:69] offset:96
	global_load_dwordx4 v[124:127], v69, s[70:71] offset:96
	s_waitcnt vmcnt(6)
	v_mul_f32_e32 v70, v0, v112
	v_mul_f32_e32 v71, v1, v113
	v_mul_f32_e32 v72, v2, v114
	v_mul_f32_e32 v73, v3, v115
	v_mul_f32_e32 v74, v16, v112
	v_mul_f32_e32 v75, v17, v113
	v_mul_f32_e32 v76, v18, v114
	v_mul_f32_e32 v77, v19, v115
	v_fma_f32 v70, v16, v96, -v70
	v_fma_f32 v71, v17, v97, -v71
	v_fma_f32 v72, v18, v98, -v72
	v_fma_f32 v73, v19, v99, -v73
	v_fmac_f32_e32 v74, v0, v96
	v_fmac_f32_e32 v75, v1, v97
	v_fmac_f32_e32 v76, v2, v98
	v_fmac_f32_e32 v77, v3, v99
	v_cvt_pk_bf16_f32 v78, v70, v71
	v_cvt_pk_bf16_f32 v79, v72, v73
	v_cvt_pk_bf16_f32 v80, v74, v75
	v_cvt_pk_bf16_f32 v81, v76, v77
	global_store_dwordx2 v67, v[78:79], s[40:41]
	global_store_dwordx2 v67, v[80:81], s[40:41] offset:64
	s_waitcnt vmcnt(6)
	v_mul_f32_e32 v70, v4, v116
	v_mul_f32_e32 v71, v5, v117
	v_mul_f32_e32 v72, v6, v118
	v_mul_f32_e32 v73, v7, v119
	v_mul_f32_e32 v74, v20, v116
	v_mul_f32_e32 v75, v21, v117
	v_mul_f32_e32 v76, v22, v118
	v_mul_f32_e32 v77, v23, v119
	v_fma_f32 v70, v20, v100, -v70
	v_fma_f32 v71, v21, v101, -v71
	v_fma_f32 v72, v22, v102, -v72
	v_fma_f32 v73, v23, v103, -v73
	v_fmac_f32_e32 v74, v4, v100
	v_fmac_f32_e32 v75, v5, v101
	v_fmac_f32_e32 v76, v6, v102
	v_fmac_f32_e32 v77, v7, v103
	v_cvt_pk_bf16_f32 v82, v70, v71
	v_cvt_pk_bf16_f32 v83, v72, v73
	v_cvt_pk_bf16_f32 v84, v74, v75
	v_cvt_pk_bf16_f32 v85, v76, v77
	global_store_dwordx2 v67, v[82:83], s[40:41] offset:16
	global_store_dwordx2 v67, v[84:85], s[40:41] offset:80
	s_waitcnt vmcnt(6)
	v_mul_f32_e32 v70, v8, v120
	v_mul_f32_e32 v71, v9, v121
	v_mul_f32_e32 v72, v10, v122
	v_mul_f32_e32 v73, v11, v123
	v_mul_f32_e32 v74, v24, v120
	v_mul_f32_e32 v75, v25, v121
	v_mul_f32_e32 v76, v26, v122
	v_mul_f32_e32 v77, v27, v123
	v_fma_f32 v70, v24, v104, -v70
	v_fma_f32 v71, v25, v105, -v71
	v_fma_f32 v72, v26, v106, -v72
	v_fma_f32 v73, v27, v107, -v73
	v_fmac_f32_e32 v74, v8, v104
	v_fmac_f32_e32 v75, v9, v105
	v_fmac_f32_e32 v76, v10, v106
	v_fmac_f32_e32 v77, v11, v107
	v_cvt_pk_bf16_f32 v78, v70, v71
	v_cvt_pk_bf16_f32 v79, v72, v73
	v_cvt_pk_bf16_f32 v80, v74, v75
	v_cvt_pk_bf16_f32 v81, v76, v77
	global_store_dwordx2 v67, v[78:79], s[40:41] offset:32
	global_store_dwordx2 v67, v[80:81], s[40:41] offset:96
	s_waitcnt vmcnt(6)
	v_mul_f32_e32 v70, v12, v124
	v_mul_f32_e32 v71, v13, v125
	v_mul_f32_e32 v72, v14, v126
	v_mul_f32_e32 v73, v15, v127
	v_mul_f32_e32 v74, v28, v124
	v_mul_f32_e32 v75, v29, v125
	v_mul_f32_e32 v76, v30, v126
	v_mul_f32_e32 v77, v31, v127
	v_fma_f32 v70, v28, v108, -v70
	v_fma_f32 v71, v29, v109, -v71
	v_fma_f32 v72, v30, v110, -v72
	v_fma_f32 v73, v31, v111, -v73
	v_fmac_f32_e32 v74, v12, v108
	v_fmac_f32_e32 v75, v13, v109
	v_fmac_f32_e32 v76, v14, v110
	v_fmac_f32_e32 v77, v15, v111
	v_cvt_pk_bf16_f32 v82, v70, v71
	v_cvt_pk_bf16_f32 v83, v72, v73
	v_cvt_pk_bf16_f32 v84, v74, v75
	v_cvt_pk_bf16_f32 v85, v76, v77
	global_store_dwordx2 v67, v[82:83], s[40:41] offset:48
	global_store_dwordx2 v67, v[84:85], s[40:41] offset:112
	s_branch .LBB0_341
.Lp2_plain:
	v_mul_lo_u32 v66, v64, s14
	v_lshl_add_u32 v66, v65, 3, v66
	s_lshl_b32 s15, s14, 5
	v_add_u32_e32 v67, s15, v66
	v_cvt_pk_bf16_f32 v78, v48, v49
	v_cvt_pk_bf16_f32 v79, v50, v51
	v_cvt_pk_bf16_f32 v80, v32, v33
	v_cvt_pk_bf16_f32 v81, v34, v35
	global_store_dwordx2 v66, v[78:79], s[40:41]
	global_store_dwordx2 v66, v[80:81], s[40:41] offset:64
	v_cvt_pk_bf16_f32 v82, v52, v53
	v_cvt_pk_bf16_f32 v83, v54, v55
	v_cvt_pk_bf16_f32 v84, v36, v37
	v_cvt_pk_bf16_f32 v85, v38, v39
	global_store_dwordx2 v66, v[82:83], s[40:41] offset:16
	global_store_dwordx2 v66, v[84:85], s[40:41] offset:80
	v_cvt_pk_bf16_f32 v78, v56, v57
	v_cvt_pk_bf16_f32 v79, v58, v59
	v_cvt_pk_bf16_f32 v80, v40, v41
	v_cvt_pk_bf16_f32 v81, v42, v43
	global_store_dwordx2 v66, v[78:79], s[40:41] offset:32
	global_store_dwordx2 v66, v[80:81], s[40:41] offset:96
	v_cvt_pk_bf16_f32 v82, v60, v61
	v_cvt_pk_bf16_f32 v83, v62, v63
	v_cvt_pk_bf16_f32 v84, v44, v45
	v_cvt_pk_bf16_f32 v85, v46, v47
	global_store_dwordx2 v66, v[82:83], s[40:41] offset:48
	global_store_dwordx2 v66, v[84:85], s[40:41] offset:112
	v_cvt_pk_bf16_f32 v78, v16, v17
	v_cvt_pk_bf16_f32 v79, v18, v19
	v_cvt_pk_bf16_f32 v80, v0, v1
	v_cvt_pk_bf16_f32 v81, v2, v3
	global_store_dwordx2 v67, v[78:79], s[40:41]
	global_store_dwordx2 v67, v[80:81], s[40:41] offset:64
	v_cvt_pk_bf16_f32 v82, v20, v21
	v_cvt_pk_bf16_f32 v83, v22, v23
	v_cvt_pk_bf16_f32 v84, v4, v5
	v_cvt_pk_bf16_f32 v85, v6, v7
	global_store_dwordx2 v67, v[82:83], s[40:41] offset:16
	global_store_dwordx2 v67, v[84:85], s[40:41] offset:80
	v_cvt_pk_bf16_f32 v78, v24, v25
	v_cvt_pk_bf16_f32 v79, v26, v27
	v_cvt_pk_bf16_f32 v80, v8, v9
	v_cvt_pk_bf16_f32 v81, v10, v11
	global_store_dwordx2 v67, v[78:79], s[40:41] offset:32
	global_store_dwordx2 v67, v[80:81], s[40:41] offset:96
	v_cvt_pk_bf16_f32 v82, v28, v29
	v_cvt_pk_bf16_f32 v83, v30, v31
	v_cvt_pk_bf16_f32 v84, v12, v13
	v_cvt_pk_bf16_f32 v85, v14, v15
	global_store_dwordx2 v67, v[82:83], s[40:41] offset:48
	global_store_dwordx2 v67, v[84:85], s[40:41] offset:112
	s_branch .LBB0_341
.Lp2_trans_setup:
	s_lshl_b32 s34, s30, 1
	s_add_u32 s34, s34, s13
	s_lshl_b32 s34, s34, 20
	s_lshl_b32 s35, s31, 1
	s_add_u32 s34, s34, s35
	s_add_u32 s33, s33, s34
	s_add_u32 s40, s88, s33
	s_addc_u32 s41, s89, 0
	v_lshlrev_b32_e32 v66, 1, v64
	v_lshl_add_u32 v66, v65, 16, v66
	s_movk_i32 s14, 0x4000
	v_mov_b32_e32 v67, v66
	v_cvt_pk_bf16_f32 v70, v48, v48
	global_store_short v67, v70, s[40:41]
	v_add_u32_e32 v67, 0x4000, v67
	v_cvt_pk_bf16_f32 v71, v49, v49
	global_store_short v67, v71, s[40:41]
	v_add_u32_e32 v67, 0x4000, v67
	v_cvt_pk_bf16_f32 v72, v50, v50
	global_store_short v67, v72, s[40:41]
	v_add_u32_e32 v67, 0x4000, v67
	v_cvt_pk_bf16_f32 v73, v51, v51
	global_store_short v67, v73, s[40:41]
	v_add_u32_e32 v67, 0x14000, v67
	v_cvt_pk_bf16_f32 v70, v52, v52
	global_store_short v67, v70, s[40:41]
	v_add_u32_e32 v67, 0x4000, v67
	v_cvt_pk_bf16_f32 v71, v53, v53
	global_store_short v67, v71, s[40:41]
	v_add_u32_e32 v67, 0x4000, v67
	v_cvt_pk_bf16_f32 v72, v54, v54
	global_store_short v67, v72, s[40:41]
	v_add_u32_e32 v67, 0x4000, v67
	v_cvt_pk_bf16_f32 v73, v55, v55
	global_store_short v67, v73, s[40:41]
	v_add_u32_e32 v67, 0x14000, v67
	s_waitcnt vmcnt(24)
	v_cvt_pk_bf16_f32 v70, v56, v56
	global_store_short v67, v70, s[40:41]
	v_add_u32_e32 v67, 0x4000, v67
	v_cvt_pk_bf16_f32 v71, v57, v57
	global_store_short v67, v71, s[40:41]
	v_add_u32_e32 v67, 0x4000, v67
	v_cvt_pk_bf16_f32 v72, v58, v58
	global_store_short v67, v72, s[40:41]
	v_add_u32_e32 v67, 0x4000, v67
	v_cvt_pk_bf16_f32 v73, v59, v59
	global_store_short v67, v73, s[40:41]
	v_add_u32_e32 v67, 0x14000, v67
	v_cvt_pk_bf16_f32 v70, v60, v60
	global_store_short v67, v70, s[40:41]
	v_add_u32_e32 v67, 0x4000, v67
	v_cvt_pk_bf16_f32 v71, v61, v61
	global_store_short v67, v71, s[40:41]
	v_add_u32_e32 v67, 0x4000, v67
	v_cvt_pk_bf16_f32 v72, v62, v62
	global_store_short v67, v72, s[40:41]
	v_add_u32_e32 v67, 0x4000, v67
	v_cvt_pk_bf16_f32 v73, v63, v63
	global_store_short v67, v73, s[40:41]
	v_add_u32_e32 v67, 0x14000, v67
	s_waitcnt vmcnt(24)
	v_cvt_pk_bf16_f32 v70, v32, v32
	global_store_short v67, v70, s[40:41]
	v_add_u32_e32 v67, 0x4000, v67
	v_cvt_pk_bf16_f32 v71, v33, v33
	global_store_short v67, v71, s[40:41]
	v_add_u32_e32 v67, 0x4000, v67
	v_cvt_pk_bf16_f32 v72, v34, v34
	global_store_short v67, v72, s[40:41]
	v_add_u32_e32 v67, 0x4000, v67
	v_cvt_pk_bf16_f32 v73, v35, v35
	global_store_short v67, v73, s[40:41]
	v_add_u32_e32 v67, 0x14000, v67
	v_cvt_pk_bf16_f32 v70, v36, v36
	global_store_short v67, v70, s[40:41]
	v_add_u32_e32 v67, 0x4000, v67
	v_cvt_pk_bf16_f32 v71, v37, v37
	global_store_short v67, v71, s[40:41]
	v_add_u32_e32 v67, 0x4000, v67
	v_cvt_pk_bf16_f32 v72, v38, v38
	global_store_short v67, v72, s[40:41]
	v_add_u32_e32 v67, 0x4000, v67
	v_cvt_pk_bf16_f32 v73, v39, v39
	global_store_short v67, v73, s[40:41]
	v_add_u32_e32 v67, 0x14000, v67
	s_waitcnt vmcnt(24)
	v_cvt_pk_bf16_f32 v70, v40, v40
	global_store_short v67, v70, s[40:41]
	v_add_u32_e32 v67, 0x4000, v67
	v_cvt_pk_bf16_f32 v71, v41, v41
	global_store_short v67, v71, s[40:41]
	v_add_u32_e32 v67, 0x4000, v67
	v_cvt_pk_bf16_f32 v72, v42, v42
	global_store_short v67, v72, s[40:41]
	v_add_u32_e32 v67, 0x4000, v67
	v_cvt_pk_bf16_f32 v73, v43, v43
	global_store_short v67, v73, s[40:41]
	v_add_u32_e32 v67, 0x14000, v67
	v_cvt_pk_bf16_f32 v70, v44, v44
	global_store_short v67, v70, s[40:41]
	v_add_u32_e32 v67, 0x4000, v67
	v_cvt_pk_bf16_f32 v71, v45, v45
	global_store_short v67, v71, s[40:41]
	v_add_u32_e32 v67, 0x4000, v67
	v_cvt_pk_bf16_f32 v72, v46, v46
	global_store_short v67, v72, s[40:41]
	v_add_u32_e32 v67, 0x4000, v67
	v_cvt_pk_bf16_f32 v73, v47, v47
	global_store_short v67, v73, s[40:41]
	v_add_u32_e32 v67, 0x14000, v67
	s_waitcnt vmcnt(24)
	v_add_u32_e32 v67, 64, v66
	v_cvt_pk_bf16_f32 v70, v16, v16
	global_store_short v67, v70, s[40:41]
	v_add_u32_e32 v67, 0x4000, v67
	v_cvt_pk_bf16_f32 v71, v17, v17
	global_store_short v67, v71, s[40:41]
	v_add_u32_e32 v67, 0x4000, v67
	v_cvt_pk_bf16_f32 v72, v18, v18
	global_store_short v67, v72, s[40:41]
	v_add_u32_e32 v67, 0x4000, v67
	v_cvt_pk_bf16_f32 v73, v19, v19
	global_store_short v67, v73, s[40:41]
	v_add_u32_e32 v67, 0x14000, v67
	v_cvt_pk_bf16_f32 v70, v20, v20
	global_store_short v67, v70, s[40:41]
	v_add_u32_e32 v67, 0x4000, v67
	v_cvt_pk_bf16_f32 v71, v21, v21
	global_store_short v67, v71, s[40:41]
	v_add_u32_e32 v67, 0x4000, v67
	v_cvt_pk_bf16_f32 v72, v22, v22
	global_store_short v67, v72, s[40:41]
	v_add_u32_e32 v67, 0x4000, v67
	v_cvt_pk_bf16_f32 v73, v23, v23
	global_store_short v67, v73, s[40:41]
	v_add_u32_e32 v67, 0x14000, v67
	s_waitcnt vmcnt(24)
	v_cvt_pk_bf16_f32 v70, v24, v24
	global_store_short v67, v70, s[40:41]
	v_add_u32_e32 v67, 0x4000, v67
	v_cvt_pk_bf16_f32 v71, v25, v25
	global_store_short v67, v71, s[40:41]
	v_add_u32_e32 v67, 0x4000, v67
	v_cvt_pk_bf16_f32 v72, v26, v26
	global_store_short v67, v72, s[40:41]
	v_add_u32_e32 v67, 0x4000, v67
	v_cvt_pk_bf16_f32 v73, v27, v27
	global_store_short v67, v73, s[40:41]
	v_add_u32_e32 v67, 0x14000, v67
	v_cvt_pk_bf16_f32 v70, v28, v28
	global_store_short v67, v70, s[40:41]
	v_add_u32_e32 v67, 0x4000, v67
	v_cvt_pk_bf16_f32 v71, v29, v29
	global_store_short v67, v71, s[40:41]
	v_add_u32_e32 v67, 0x4000, v67
	v_cvt_pk_bf16_f32 v72, v30, v30
	global_store_short v67, v72, s[40:41]
	v_add_u32_e32 v67, 0x4000, v67
	v_cvt_pk_bf16_f32 v73, v31, v31
	global_store_short v67, v73, s[40:41]
	v_add_u32_e32 v67, 0x14000, v67
	s_waitcnt vmcnt(24)
	v_cvt_pk_bf16_f32 v70, v0, v0
	global_store_short v67, v70, s[40:41]
	v_add_u32_e32 v67, 0x4000, v67
	v_cvt_pk_bf16_f32 v71, v1, v1
	global_store_short v67, v71, s[40:41]
	v_add_u32_e32 v67, 0x4000, v67
	v_cvt_pk_bf16_f32 v72, v2, v2
	global_store_short v67, v72, s[40:41]
	v_add_u32_e32 v67, 0x4000, v67
	v_cvt_pk_bf16_f32 v73, v3, v3
	global_store_short v67, v73, s[40:41]
	v_add_u32_e32 v67, 0x14000, v67
	v_cvt_pk_bf16_f32 v70, v4, v4
	global_store_short v67, v70, s[40:41]
	v_add_u32_e32 v67, 0x4000, v67
	v_cvt_pk_bf16_f32 v71, v5, v5
	global_store_short v67, v71, s[40:41]
	v_add_u32_e32 v67, 0x4000, v67
	v_cvt_pk_bf16_f32 v72, v6, v6
	global_store_short v67, v72, s[40:41]
	v_add_u32_e32 v67, 0x4000, v67
	v_cvt_pk_bf16_f32 v73, v7, v7
	global_store_short v67, v73, s[40:41]
	v_add_u32_e32 v67, 0x14000, v67
	s_waitcnt vmcnt(24)
	v_cvt_pk_bf16_f32 v70, v8, v8
	global_store_short v67, v70, s[40:41]
	v_add_u32_e32 v67, 0x4000, v67
	v_cvt_pk_bf16_f32 v71, v9, v9
	global_store_short v67, v71, s[40:41]
	v_add_u32_e32 v67, 0x4000, v67
	v_cvt_pk_bf16_f32 v72, v10, v10
	global_store_short v67, v72, s[40:41]
	v_add_u32_e32 v67, 0x4000, v67
	v_cvt_pk_bf16_f32 v73, v11, v11
	global_store_short v67, v73, s[40:41]
	v_add_u32_e32 v67, 0x14000, v67
	v_cvt_pk_bf16_f32 v70, v12, v12
	global_store_short v67, v70, s[40:41]
	v_add_u32_e32 v67, 0x4000, v67
	v_cvt_pk_bf16_f32 v71, v13, v13
	global_store_short v67, v71, s[40:41]
	v_add_u32_e32 v67, 0x4000, v67
	v_cvt_pk_bf16_f32 v72, v14, v14
	global_store_short v67, v72, s[40:41]
	v_add_u32_e32 v67, 0x4000, v67
	v_cvt_pk_bf16_f32 v73, v15, v15
	global_store_short v67, v73, s[40:41]
	v_add_u32_e32 v67, 0x14000, v67
	s_waitcnt vmcnt(24)
	s_branch .LBB0_341

.LBB0_1890:
	s_or_b64 exec, exec, s[0:1]
	s_mov_b64 s[0:1], s[88:89]
	s_waitcnt lgkmcnt(0)
	v_mov_b32_e32 v0, v186
	s_mov_b32 s2, s90
	s_barrier
	s_nop 0
	v_readlane_b32 s2, v252, 34
	v_readlane_b32 s3, v252, 35
	s_andn2_b64 vcc, exec, s[2:3]
	s_cbranch_vccnz .LBB0_2024
	v_mov_b32_e32 v220, v186
	v_ashrrev_i32_e32 v221, 31, v220
	v_lshrrev_b32_e32 v222, 29, v221
	v_add_u32_e32 v223, v220, v222
	v_ashrrev_i32_e32 v224, 3, v223
	v_and_b32_e32 v225, 0xffffff8, v223
	v_lshlrev_b32_e32 v226, 2, v224
	v_lshrrev_b32_e32 v227, 1, v224
	v_sub_u32_e32 v228, v220, v225
	v_and_b32_e32 v229, 16, v226
	v_and_b32_e32 v230, 12, v227
	v_and_b32_e32 v231, 35, v224
	v_or3_b32 v232, v231, v229, v230
	v_lshlrev_b32_e32 v233, 4, v228
	v_mad_u32_u24 v234, v232, s43, v233
	v_mov_b32_e32 v214, v234
	v_mov_b32_e32 v220, v186
	v_lshlrev_b32_e32 v221, 4, v220
	v_and_b32_e32 v222, 0x70, v221
	v_lshrrev_b32_e32 v223, 3, v220
	v_mad_u64_u32 v[224:225], vcc, v223, s43, v[222:223]
	v_mov_b32_e32 v218, v224
	v_mov_b32_e32 v220, v186
	v_mul_hi_i32 v221, v220, s91
	v_lshrrev_b32_e32 v222, 31, v221
	v_ashrrev_i32_e32 v223, 1, v221
	v_add_u32_e32 v224, v223, v222
	v_mul_lo_u32 v225, v224, 12
	v_lshlrev_b32_e32 v226, 2, v224
	v_lshrrev_b32_e32 v227, 1, v224
	v_sub_u32_e32 v228, v220, v225
	v_and_b32_e32 v229, 16, v226
	v_and_b32_e32 v230, 12, v227
	v_and_b32_e32 v231, 35, v224
	v_or3_b32 v232, v231, v229, v230
	v_lshlrev_b32_e32 v233, 4, v228
	v_mad_u32_u24 v234, v232, s36, v233
	v_mov_b32_e32 v215, v234
	v_mov_b32_e32 v220, v186
	v_add_u32_e32 v221, 0x100, v220
	v_mul_hi_i32 v222, v221, s91
	v_lshrrev_b32_e32 v223, 31, v222
	v_ashrrev_i32_e32 v224, 1, v222
	v_add_u32_e32 v225, v224, v223
	v_mul_lo_u32 v226, v225, 12
	v_lshlrev_b32_e32 v227, 2, v225
	v_lshrrev_b32_e32 v228, 1, v225
	v_sub_u32_e32 v229, v221, v226
	v_and_b32_e32 v230, 16, v227
	v_and_b32_e32 v231, 12, v228
	v_and_b32_e32 v232, 35, v225
	v_or3_b32 v233, v232, v230, v231
	v_lshlrev_b32_e32 v234, 4, v229
	v_mad_u32_u24 v235, v233, s36, v234
	v_mov_b32_e32 v216, v235
	v_mov_b32_e32 v220, v186
	v_add_u32_e32 v221, 0x200, v220
	v_mul_hi_i32 v222, v221, s91
	v_lshrrev_b32_e32 v223, 31, v222
	v_ashrrev_i32_e32 v224, 1, v222
	v_add_u32_e32 v225, v224, v223
	v_mul_lo_u32 v226, v225, 12
	v_sub_u32_e32 v227, v221, v226
	v_lshlrev_b32_e32 v228, 2, v225
	v_lshrrev_b32_e32 v229, 1, v225
	v_and_b32_e32 v230, 16, v228
	v_and_b32_e32 v231, 12, v229
	v_and_b32_e32 v232, 35, v225
	v_or3_b32 v233, v232, v230, v231
	v_lshlrev_b32_e32 v234, 4, v227
	v_mad_u32_u24 v235, v233, s36, v234
	v_mov_b32_e32 v217, v235
	v_lshlrev_b32_e32 v219, 4, v186
	v_add_u32_e32 v236, 0x1000, v219
	v_add_u32_e32 v241, 0x2000, v219
	v_and_b32_e32 v220, 0x70, v219
	v_lshrrev_b32_e32 v221, 3, v186
	v_lshl_or_b32 v237, v221, 14, v220
	v_add_u32_e32 v238, 0x80000, v237
	v_lshl_or_b32 v239, v221, 10, v220
	v_add_u32_e32 v240, 0x8000, v239
	s_add_u32 s2, s0, 0x7000000
	s_addc_u32 s3, s1, 0
	v_writelane_b32 v254, s2, 36
	s_nop 1
	v_writelane_b32 v254, s3, 37
	s_add_u32 s2, s0, 0x8000000
	v_writelane_b32 v254, s2, 38
	s_addc_u32 s2, s1, 0
	v_writelane_b32 v254, s2, 39
	s_lshl_b32 s2, s22, 3
	s_mov_b32 s3, s77
	s_lshl_b64 s[2:3], s[2:3], 2
	s_add_u32 s2, s58, s2
	s_addc_u32 s3, s59, s3
	v_writelane_b32 v254, s2, 40
	s_nop 1
	v_writelane_b32 v254, s3, 41
	s_add_u32 s2, s0, 0x8400000
	v_writelane_b32 v254, s2, 42
	s_addc_u32 s2, s1, 0
	v_writelane_b32 v254, s2, 43
	s_add_u32 s2, s0, 0x4800000
	s_addc_u32 s3, s1, 0
	v_writelane_b32 v254, s2, 30
	s_nop 1
	v_writelane_b32 v254, s3, 31
	s_add_u32 s2, s0, 0x6400000
	v_writelane_b32 v254, s2, 44
	s_addc_u32 s2, s1, 0
	v_writelane_b32 v254, s2, 45
	s_add_u32 s2, s0, 0x6c00000
	v_writelane_b32 v254, s2, 46
	s_addc_u32 s2, s1, 0
	v_writelane_b32 v254, s2, 47
	s_add_u32 s2, s0, 0xe200000
	v_writelane_b32 v254, s2, 48
	s_addc_u32 s2, s1, 0
	v_writelane_b32 v254, s2, 49
	s_add_u32 s2, s0, 0x6000000
	v_writelane_b32 v254, s2, 50
	s_addc_u32 s2, s1, 0
	v_writelane_b32 v254, s2, 51
	s_add_u32 s2, s0, 0x6800000
	v_writelane_b32 v254, s2, 52
	s_addc_u32 s2, s1, 0
	v_writelane_b32 v254, s2, 53
	s_add_u32 s2, s0, 0x9800000
	s_addc_u32 s3, s1, 0
	v_writelane_b32 v254, s2, 54
	s_nop 1
	v_writelane_b32 v254, s3, 55
	s_add_u32 s2, s0, 0xe240000
	v_writelane_b32 v254, s2, 56
	s_addc_u32 s2, s1, 0
	v_writelane_b32 v254, s2, 57
	s_add_u32 s2, s0, 0x9a00000
	s_addc_u32 s3, s1, 0
	v_writelane_b32 v254, s2, 58
	s_nop 1
	v_writelane_b32 v254, s3, 59
	s_add_u32 s2, s0, 0xca00000
	v_writelane_b32 v254, s2, 60
	s_addc_u32 s2, s1, 0
	v_writelane_b32 v254, s2, 61
	s_add_u32 s2, s0, 0xb200000
	v_writelane_b32 v254, s2, 62
	s_addc_u32 s2, s1, 0
	v_writelane_b32 v254, s2, 63
	s_add_u32 s2, s0, 0x8800000
	v_writelane_b32 v255, s2, 0
	s_addc_u32 s2, s1, 0
	v_writelane_b32 v255, s2, 1
	s_add_u32 s2, s0, 0x8002000
	s_addc_u32 s3, s1, 0
	v_writelane_b32 v255, s2, 2
	v_readlane_b32 s41, v254, 16
	v_readlane_b32 s96, v254, 17
	v_writelane_b32 v255, s3, 3
	s_add_u32 s2, s0, 0xe202000
	v_writelane_b32 v255, s2, 4
	s_addc_u32 s2, s1, 0
	v_writelane_b32 v255, s2, 5
	s_add_u32 s2, s0, 0xe240080
	v_writelane_b32 v255, s2, 6
	s_addc_u32 s2, s1, 0
	v_writelane_b32 v255, s2, 7
	s_add_u32 s2, s0, 0x6802000
	v_writelane_b32 v255, s2, 8
	s_addc_u32 s2, s1, 0
	v_writelane_b32 v255, s2, 9
	s_add_u32 s0, s0, 0xb209000
	v_writelane_b32 v255, s0, 10
	s_addc_u32 s0, s1, 0
	v_writelane_b32 v255, s0, 11
	s_mov_b32 s80, s41
	s_mov_b32 s81, s41
	v_readlane_b32 s97, v254, 18
	v_readlane_b32 s40, v254, 14
	s_branch .LBB0_1894

.LBB0_1900:
	s_barrier
	s_cmp_ge_u32 s12, s52
	s_waitcnt vmcnt(1)
	ds_write_b128 v214, v[52:55]
	s_waitcnt vmcnt(0)
	ds_write_b128 v214, v[60:63] offset:4608
	s_cselect_b64 s[72:73], -1, 0
	s_and_b64 vcc, exec, s[72:73]
	ds_write_b128 v218, v[48:51] offset:13312
	ds_write_b128 v218, v[56:59] offset:17920
	s_waitcnt lgkmcnt(0)
	s_barrier
	s_cbranch_vccnz .LBB0_1902
	v_mov_b32_e32 v48, v186
	s_mov_b32 s69, s77
	s_lshl_b64 s[0:1], s[68:69], 1
	v_add_u32_e32 v56, 0x100, v48
	v_ashrrev_i32_e32 v49, 31, v48
	v_ashrrev_i32_e32 v57, 31, v56
	s_add_u32 s0, s53, s0
	v_lshl_add_u64 v[50:51], v[48:49], 4, v[86:87]
	v_lshl_add_u64 v[58:59], v[56:57], 4, v[86:87]
	v_lshlrev_b32_e32 v49, 4, v48
	v_ashrrev_i32_e32 v48, 3, v48
	v_ashrrev_i32_e32 v56, 3, v56
	s_addc_u32 s1, s70, s1
	v_and_b32_e32 v160, 0x70, v49
	v_ashrrev_i32_e32 v49, 31, v48
	v_ashrrev_i32_e32 v57, 31, v56
	global_load_dwordx4 v[52:55], v[50:51], off
	global_load_dwordx4 v[60:63], v[58:59], off
	v_lshl_add_u64 v[50:51], s[0:1], 0, v[160:161]
	v_lshlrev_b64 v[48:49], 14, v[48:49]
	v_lshlrev_b64 v[56:57], 14, v[56:57]
	v_lshl_add_u64 v[48:49], v[50:51], 0, v[48:49]
	v_lshl_add_u64 v[56:57], v[50:51], 0, v[56:57]
	global_load_dwordx4 v[48:51], v[48:49], off
	s_nop 0
	global_load_dwordx4 v[56:59], v[56:57], off

.LBB0_1923:
	s_waitcnt lgkmcnt(0)
	s_barrier
	s_add_i32 s75, s75, 1
	s_waitcnt vmcnt(1)
	ds_write_b128 v214, v[46:49]
	s_cmp_ge_u32 s75, s70
	s_waitcnt vmcnt(0)
	ds_write_b128 v214, v[50:53] offset:4608
	s_waitcnt lgkmcnt(0)
	s_barrier
	s_cbranch_scc1 .LBB0_1925
	global_load_dwordx4 v[46:49], v219, s[12:13]
	global_load_dwordx4 v[50:53], v236, s[12:13]

.LBB0_1939:
	s_barrier
	s_cmp_ge_u32 s14, s13
	s_waitcnt vmcnt(8)
	ds_write_b128 v215, v[28:31]
	s_waitcnt vmcnt(8)
	ds_write_b128 v216, v[24:27]
	s_waitcnt vmcnt(7)
	ds_write_b128 v217, v[32:35]
	s_waitcnt vmcnt(6)
	ds_write_b128 v218, v[36:39] offset:13312
	s_waitcnt vmcnt(5)
	ds_write_b128 v218, v[44:47] offset:17920
	s_nop 0
	s_waitcnt vmcnt(4)
	ds_write_b128 v215, v[52:55] offset:22528
	s_waitcnt vmcnt(3)
	ds_write_b128 v216, v[56:59] offset:22528
	s_waitcnt vmcnt(2)
	ds_write_b128 v217, v[60:63] offset:22528
	s_cselect_b64 s[6:7], -1, 0
	s_and_b64 vcc, exec, s[6:7]
	s_waitcnt vmcnt(1)
	ds_write_b128 v218, v[64:67] offset:35840
	s_waitcnt vmcnt(0)
	ds_write_b128 v218, v[68:71] offset:40448
	s_waitcnt lgkmcnt(0)
	s_barrier
	s_cbranch_vccnz .LBB0_1941
	s_sub_i32 s8, s2, 64
	s_mov_b32 s9, s77
	s_lshl_b64 s[8:9], s[8:9], 1
	s_add_u32 s8, s4, s8
	s_addc_u32 s9, s5, s9
	s_add_u32 s20, s0, 0xffffd000
	s_addc_u32 s21, s1, -1
	global_load_dwordx4 v[24:27], v236, s[20:21]
	global_load_dwordx4 v[28:31], v219, s[20:21]
	global_load_dwordx4 v[32:35], v241, s[20:21]
	global_load_dwordx4 v[36:39], v237, s[8:9]
	global_load_dwordx4 v[44:47], v238, s[8:9]
	s_mov_b32 s3, s77
	s_lshl_b64 s[8:9], s[2:3], 1
	s_add_u32 s8, s4, s8
	s_addc_u32 s9, s5, s9
	global_load_dwordx4 v[52:55], v219, s[0:1]
	global_load_dwordx4 v[56:59], v236, s[0:1]
	global_load_dwordx4 v[60:63], v241, s[0:1]
	global_load_dwordx4 v[64:67], v237, s[8:9]
	global_load_dwordx4 v[68:71], v238, s[8:9]

.LBB0_1976:
	s_barrier
	s_add_i32 s33, s33, 1
	s_waitcnt vmcnt(3)
	ds_write_b128 v214, v[48:51]
	s_waitcnt vmcnt(2)
	ds_write_b128 v214, v[52:55] offset:4608
	s_cmp_ge_u32 s33, s70
	s_waitcnt vmcnt(1)
	ds_write_b128 v218, v[56:59] offset:13312
	s_waitcnt vmcnt(0)
	ds_write_b128 v218, v[60:63] offset:17920
	s_waitcnt lgkmcnt(0)
	s_barrier
	s_cbranch_scc1 .LBB0_1975
	global_load_dwordx4 v[48:51], v219, s[68:69]
	global_load_dwordx4 v[52:55], v236, s[68:69]
	global_load_dwordx4 v[56:59], v239, s[12:13]
	global_load_dwordx4 v[60:63], v240, s[12:13]
	s_branch .LBB0_1975

.LBB0_1994:
	s_waitcnt lgkmcnt(0)
	s_barrier
	s_mov_b32 s12, -1
	s_waitcnt vmcnt(3)
	ds_write_b128 v214, v[84:87]
	s_waitcnt vmcnt(2)
	ds_write_b128 v214, v[88:91] offset:4608
	s_cmp_ge_i32 s2, s70
	s_mov_b32 s3, s2
	s_waitcnt vmcnt(1)
	ds_write_b128 v218, v[92:95] offset:13312
	s_waitcnt vmcnt(0)
	ds_write_b128 v218, v[96:99] offset:17920
	s_waitcnt lgkmcnt(0)
	s_barrier
	s_cbranch_scc0 .LBB0_2001
.LBB0_1995:
	s_cmp_lt_i32 s12, 0
	s_cselect_b64 s[68:69], -1, 0
	s_and_b64 vcc, exec, s[68:69]
	s_cbranch_vccnz .LBB0_1997
	s_mov_b32 s13, s77
	s_lshl_b64 s[0:1], s[12:13], 13
	s_add_u32 s0, s78, s0
	s_addc_u32 s1, s79, s1
	s_lshl_b32 s3, s12, 7
	s_add_u32 s4, s33, s3
	s_addc_u32 s5, s39, 0
	global_load_dwordx4 v[84:87], v219, s[0:1]
	global_load_dwordx4 v[88:91], v236, s[0:1]
	global_load_dwordx4 v[92:95], v237, s[4:5]
	global_load_dwordx4 v[96:99], v238, s[4:5]

.LBB0_2013:
	s_barrier
	s_cmp_ge_u32 s12, s70
	s_waitcnt vmcnt(1)
	ds_write_b128 v214, v[112:115]
	s_waitcnt vmcnt(0)
	ds_write_b128 v214, v[120:123] offset:4608
	s_cselect_b64 s[78:79], -1, 0
	s_and_b64 vcc, exec, s[78:79]
	ds_write_b128 v218, v[116:119] offset:13312
	ds_write_b128 v218, v[124:127] offset:17920
	s_waitcnt lgkmcnt(0)
	s_barrier
	s_cbranch_vccnz .LBB0_2015
	s_mov_b32 s69, s77
	s_lshl_b64 s[0:1], s[68:69], 1
	s_add_u32 s0, s52, s0
	s_addc_u32 s1, s71, s1
	global_load_dwordx4 v[112:115], v219, s[72:73]
	global_load_dwordx4 v[120:123], v236, s[72:73]
	global_load_dwordx4 v[116:119], v237, s[0:1]
	global_load_dwordx4 v[124:127], v238, s[0:1]

.LBB0_2262:
	s_lshl_b32 s6, s5, 7
	s_ashr_i32 s7, s6, 31
	s_lshl_b64 s[8:9], s[6:7], 11
	v_mov_b32_e32 v0, v161
	s_add_u32 s8, s12, s8
	s_waitcnt vmcnt(8)
	v_mov_b32_e32 v49, v186
	s_addc_u32 s9, s13, s9
	s_ashr_i32 s5, s4, 31
	s_lshl_b64 s[10:11], s[4:5], 18
	v_lshlrev_b32_e32 v16, 4, v49
	v_ashrrev_i32_e32 v50, 3, v49
	v_and_b32_e32 v48, 0x70, v16
	s_add_u32 s10, s14, s10
	v_lshl_or_b32 v168, v50, 11, v48
	s_addc_u32 s11, s15, s11
	v_add_u32_e32 v169, 0x10000, v168
	v_add_u32_e32 v170, 0x20000, v168
	v_add_u32_e32 v171, 0x30000, v168
	s_barrier
	global_load_dwordx4 v[16:19], v168, s[8:9]
	global_load_dwordx4 v[20:23], v169, s[8:9]
	global_load_dwordx4 v[24:27], v170, s[8:9]
	global_load_dwordx4 v[28:31], v171, s[8:9]
	global_load_dwordx4 v[32:35], v168, s[10:11]
	global_load_dwordx4 v[36:39], v169, s[10:11]
	global_load_dwordx4 v[40:43], v170, s[10:11]
	global_load_dwordx4 v[44:47], v171, s[10:11]
	v_mad_u64_u32 v[130:131], s[18:19], v50, s43, v[48:49]
	v_mov_b32_e32 v1, v0
	v_mov_b32_e32 v2, v0
	v_mov_b32_e32 v3, v0
	v_mov_b32_e32 v4, v0
	v_mov_b32_e32 v5, v0
	v_mov_b32_e32 v6, v0
	v_mov_b32_e32 v7, v0
	s_waitcnt vmcnt(8)
	v_mov_b32_e32 v8, v0
	v_mov_b32_e32 v9, v0
	v_mov_b32_e32 v10, v0
	v_mov_b32_e32 v11, v0
	v_mov_b32_e32 v12, v0
	v_mov_b32_e32 v13, v0
	v_mov_b32_e32 v14, v0
	v_mov_b32_e32 v15, v0
	s_waitcnt vmcnt(7)
	ds_write_b128 v130, v[16:19]
	s_waitcnt vmcnt(6)
	ds_write_b128 v130, v[20:23] offset:4608
	s_waitcnt vmcnt(5)
	ds_write_b128 v130, v[24:27] offset:9216
	s_waitcnt vmcnt(4)
	ds_write_b128 v130, v[28:31] offset:13824
	s_waitcnt vmcnt(3)
	ds_write_b128 v130, v[32:35] offset:36864
	s_waitcnt vmcnt(2)
	ds_write_b128 v130, v[36:39] offset:41472
	s_waitcnt vmcnt(1)
	ds_write_b128 v130, v[40:43] offset:46080
	s_waitcnt vmcnt(0)
	ds_write_b128 v130, v[44:47] offset:50688
	global_load_dwordx4 v[96:99], v168, s[8:9] offset:128
	global_load_dwordx4 v[100:103], v169, s[8:9] offset:128
	global_load_dwordx4 v[104:107], v170, s[8:9] offset:128
	global_load_dwordx4 v[108:111], v171, s[8:9] offset:128
	global_load_dwordx4 v[64:67], v168, s[10:11] offset:128
	global_load_dwordx4 v[68:71], v169, s[10:11] offset:128
	global_load_dwordx4 v[72:75], v170, s[10:11] offset:128
	global_load_dwordx4 v[76:79], v171, s[10:11] offset:128
	v_lshrrev_b32_e32 v18, 1, v49
	v_and_b32_e32 v17, 0x5f, v49
	v_and_b32_e32 v16, 16, v18
	v_mad_u32_u24 v131, v17, s43, v16
	v_and_b32_e32 v17, 31, v49
	v_and_or_b32 v17, v18, s44, v17
	v_mad_u64_u32 v[128:129], s[18:19], v17, s43, v[16:17]
	s_waitcnt lgkmcnt(0)
	s_barrier
	ds_read_b128 v[16:19], v128
	ds_read_b128 v[84:87], v131 offset:41472
	ds_read_b128 v[80:83], v128 offset:4608
	ds_read_b128 v[172:175], v128 offset:32
	s_waitcnt lgkmcnt(2)
	v_mfma_f32_32x32x16_bf16 v[48:63], v[84:87], v[16:19], v[0:15]
	ds_read_b128 v[88:91], v131 offset:36864
	ds_read_b128 v[176:179], v128 offset:4640
	ds_read_b128 v[180:183], v131 offset:36896
	ds_read_b128 v[196:199], v131 offset:41504
	v_add_u32_e32 v129, 0xd800, v130
	s_waitcnt lgkmcnt(3)
	v_mfma_f32_32x32x16_bf16 v[32:47], v[88:91], v[16:19], v[0:15]
	v_mfma_f32_32x32x16_bf16 v[16:31], v[88:91], v[80:83], v[0:15]
	v_mfma_f32_32x32x16_bf16 v[0:15], v[84:87], v[80:83], v[0:15]
	s_waitcnt lgkmcnt(1)
	v_mfma_f32_32x32x16_bf16 v[32:47], v[180:183], v[172:175], v[32:47]
	s_waitcnt lgkmcnt(0)
	v_mfma_f32_32x32x16_bf16 v[48:63], v[196:199], v[172:175], v[48:63]
	v_mfma_f32_32x32x16_bf16 v[16:31], v[180:183], v[176:179], v[16:31]
	v_mfma_f32_32x32x16_bf16 v[0:15], v[196:199], v[176:179], v[0:15]
	ds_read_b128 v[200:203], v128 offset:64
	ds_read_b128 v[210:213], v128 offset:4672
	ds_read_b128 v[214:217], v131 offset:36928
	ds_read_b128 v[218:221], v131 offset:41536
	s_waitcnt lgkmcnt(1)
	v_mfma_f32_32x32x16_bf16 v[32:47], v[214:217], v[200:203], v[32:47]
	s_waitcnt lgkmcnt(0)
	v_mfma_f32_32x32x16_bf16 v[48:63], v[218:221], v[200:203], v[48:63]
	v_mfma_f32_32x32x16_bf16 v[16:31], v[214:217], v[210:213], v[16:31]
	v_mfma_f32_32x32x16_bf16 v[0:15], v[218:221], v[210:213], v[0:15]
	global_load_dwordx4 v[112:115], v168, s[8:9] offset:256
	global_load_dwordx4 v[116:119], v169, s[8:9] offset:256
	global_load_dwordx4 v[120:123], v170, s[8:9] offset:256
	global_load_dwordx4 v[124:127], v171, s[8:9] offset:256
	global_load_dwordx4 v[80:83], v168, s[10:11] offset:256
	global_load_dwordx4 v[84:87], v169, s[10:11] offset:256
	global_load_dwordx4 v[88:91], v170, s[10:11] offset:256
	global_load_dwordx4 v[92:95], v171, s[10:11] offset:256
	s_waitcnt vmcnt(15)
	ds_write_b128 v130, v[96:99] offset:18432
	s_waitcnt vmcnt(14)
	ds_write_b128 v130, v[100:103] offset:23040
	s_waitcnt vmcnt(13)
	ds_write_b128 v130, v[104:107] offset:27648
	s_waitcnt vmcnt(12)
	ds_write_b128 v130, v[108:111] offset:32256
	ds_read_b128 v[96:99], v128 offset:96
	ds_read_b128 v[100:103], v128 offset:4704
	ds_read_b128 v[104:107], v131 offset:36960
	ds_read_b128 v[108:111], v131 offset:41568
	s_waitcnt vmcnt(11)
	ds_write_b128 v130, v[64:67] offset:55296
	s_waitcnt vmcnt(10)
	ds_write_b128 v130, v[68:71] offset:59904
	s_waitcnt vmcnt(9)
	ds_write_b128 v130, v[72:75] offset:64512
	s_waitcnt vmcnt(8)
	ds_write_b128 v129, v[76:79] offset:13824
	s_waitcnt lgkmcnt(5)
	v_mfma_f32_32x32x16_bf16 v[32:47], v[104:107], v[96:99], v[32:47]
	s_waitcnt lgkmcnt(0)
	s_barrier
	v_mfma_f32_32x32x16_bf16 v[48:63], v[108:111], v[96:99], v[48:63]
	v_mfma_f32_32x32x16_bf16 v[16:31], v[104:107], v[100:103], v[16:31]
	v_mfma_f32_32x32x16_bf16 v[0:15], v[108:111], v[100:103], v[0:15]
	ds_read_b128 v[64:67], v128 offset:23040
	ds_read_b128 v[72:75], v128 offset:18432
	ds_read_b128 v[68:71], v131 offset:59904
	ds_read_b128 v[100:103], v131 offset:55296
	ds_read_b128 v[76:79], v128 offset:18464
	ds_read_b128 v[96:99], v128 offset:23072
	ds_read_b128 v[104:107], v131 offset:55328
	ds_read_b128 v[108:111], v131 offset:59936
	s_waitcnt lgkmcnt(4)
	v_mfma_f32_32x32x16_bf16 v[32:47], v[100:103], v[72:75], v[32:47]
	v_mfma_f32_32x32x16_bf16 v[48:63], v[68:71], v[72:75], v[48:63]
	v_mfma_f32_32x32x16_bf16 v[16:31], v[100:103], v[64:67], v[16:31]
	v_mfma_f32_32x32x16_bf16 v[0:15], v[68:71], v[64:67], v[0:15]
	global_load_dwordx4 v[64:67], v168, s[8:9] offset:384
	global_load_dwordx4 v[68:71], v169, s[8:9] offset:384
	global_load_dwordx4 v[72:75], v170, s[8:9] offset:384
	global_load_dwordx4 v[100:103], v171, s[8:9] offset:384
	global_load_dwordx4 v[172:175], v168, s[10:11] offset:384
	global_load_dwordx4 v[176:179], v169, s[10:11] offset:384
	global_load_dwordx4 v[180:183], v170, s[10:11] offset:384
	global_load_dwordx4 v[196:199], v171, s[10:11] offset:384
	ds_read_b128 v[200:203], v128 offset:18496
	ds_read_b128 v[210:213], v128 offset:23104
	ds_read_b128 v[214:217], v131 offset:55360
	ds_read_b128 v[218:221], v131 offset:59968
	s_waitcnt vmcnt(15)
	ds_write_b128 v130, v[112:115]
	s_waitcnt vmcnt(14)
	ds_write_b128 v130, v[116:119] offset:4608
	s_waitcnt vmcnt(13)
	ds_write_b128 v130, v[120:123] offset:9216
	s_waitcnt vmcnt(12)
	ds_write_b128 v130, v[124:127] offset:13824
	s_waitcnt lgkmcnt(9)
	v_mfma_f32_32x32x16_bf16 v[32:47], v[104:107], v[76:79], v[32:47]
	s_waitcnt lgkmcnt(8)
	v_mfma_f32_32x32x16_bf16 v[48:63], v[108:111], v[76:79], v[48:63]
	v_mfma_f32_32x32x16_bf16 v[16:31], v[104:107], v[96:99], v[16:31]
	v_mfma_f32_32x32x16_bf16 v[0:15], v[108:111], v[96:99], v[0:15]
	ds_read_b128 v[76:79], v128 offset:18528
	ds_read_b128 v[96:99], v128 offset:23136
	ds_read_b128 v[104:107], v131 offset:55392
	ds_read_b128 v[108:111], v131 offset:60000
	s_waitcnt vmcnt(11)
	ds_write_b128 v130, v[80:83] offset:36864
	s_waitcnt vmcnt(10)
	ds_write_b128 v130, v[84:87] offset:41472
	s_waitcnt vmcnt(9)
	ds_write_b128 v130, v[88:91] offset:46080
	s_waitcnt vmcnt(8)
	ds_write_b128 v130, v[92:95] offset:50688
	s_waitcnt lgkmcnt(13)
	v_mfma_f32_32x32x16_bf16 v[32:47], v[214:217], v[200:203], v[32:47]
	s_waitcnt lgkmcnt(0)
	s_barrier
	v_mfma_f32_32x32x16_bf16 v[48:63], v[218:221], v[200:203], v[48:63]
	v_mfma_f32_32x32x16_bf16 v[16:31], v[214:217], v[210:213], v[16:31]
	v_mfma_f32_32x32x16_bf16 v[0:15], v[218:221], v[210:213], v[0:15]
	v_mfma_f32_32x32x16_bf16 v[32:47], v[104:107], v[76:79], v[32:47]
	v_mfma_f32_32x32x16_bf16 v[48:63], v[108:111], v[76:79], v[48:63]
	v_mfma_f32_32x32x16_bf16 v[16:31], v[104:107], v[96:99], v[16:31]
	v_mfma_f32_32x32x16_bf16 v[0:15], v[108:111], v[96:99], v[0:15]
	ds_read_b128 v[76:79], v128 offset:4608
	ds_read_b128 v[84:87], v128
	ds_read_b128 v[80:83], v131 offset:41472
	ds_read_b128 v[96:99], v131 offset:36864
	ds_read_b128 v[88:91], v128 offset:32
	ds_read_b128 v[92:95], v128 offset:4640
	ds_read_b128 v[104:107], v131 offset:36896
	ds_read_b128 v[108:111], v131 offset:41504
	s_waitcnt lgkmcnt(4)
	v_mfma_f32_32x32x16_bf16 v[32:47], v[96:99], v[84:87], v[32:47]
	v_mfma_f32_32x32x16_bf16 v[48:63], v[80:83], v[84:87], v[48:63]
	v_mfma_f32_32x32x16_bf16 v[16:31], v[96:99], v[76:79], v[16:31]
	v_mfma_f32_32x32x16_bf16 v[0:15], v[80:83], v[76:79], v[0:15]
	global_load_dwordx4 v[76:79], v168, s[8:9] offset:512
	global_load_dwordx4 v[80:83], v169, s[8:9] offset:512
	global_load_dwordx4 v[84:87], v170, s[8:9] offset:512
	global_load_dwordx4 v[96:99], v171, s[8:9] offset:512
	global_load_dwordx4 v[112:115], v168, s[10:11] offset:512
	global_load_dwordx4 v[116:119], v169, s[10:11] offset:512
	global_load_dwordx4 v[120:123], v170, s[10:11] offset:512
	global_load_dwordx4 v[124:127], v171, s[10:11] offset:512
	ds_read_b128 v[200:203], v128 offset:64
	ds_read_b128 v[210:213], v128 offset:4672
	ds_read_b128 v[214:217], v131 offset:36928
	ds_read_b128 v[218:221], v131 offset:41536
	s_waitcnt vmcnt(15)
	ds_write_b128 v130, v[64:67] offset:18432
	s_waitcnt vmcnt(14)
	ds_write_b128 v130, v[68:71] offset:23040
	s_waitcnt vmcnt(13)
	ds_write_b128 v130, v[72:75] offset:27648
	s_waitcnt vmcnt(12)
	ds_write_b128 v130, v[100:103] offset:32256
	s_waitcnt lgkmcnt(9)
	v_mfma_f32_32x32x16_bf16 v[32:47], v[104:107], v[88:91], v[32:47]
	s_waitcnt lgkmcnt(8)
	v_mfma_f32_32x32x16_bf16 v[48:63], v[108:111], v[88:91], v[48:63]
	v_mfma_f32_32x32x16_bf16 v[16:31], v[104:107], v[92:95], v[16:31]
	v_mfma_f32_32x32x16_bf16 v[0:15], v[108:111], v[92:95], v[0:15]
	ds_read_b128 v[64:67], v128 offset:96
	ds_read_b128 v[68:71], v128 offset:4704
	ds_read_b128 v[72:75], v131 offset:36960
	ds_read_b128 v[88:91], v131 offset:41568
	s_waitcnt vmcnt(11)
	ds_write_b128 v130, v[172:175] offset:55296
	s_waitcnt vmcnt(10)
	ds_write_b128 v130, v[176:179] offset:59904
	s_waitcnt vmcnt(9)
	ds_write_b128 v130, v[180:183] offset:64512
	s_waitcnt vmcnt(8)
	ds_write_b128 v129, v[196:199] offset:13824
	s_waitcnt lgkmcnt(13)
	v_mfma_f32_32x32x16_bf16 v[32:47], v[214:217], v[200:203], v[32:47]
	s_waitcnt lgkmcnt(0)
	s_barrier
	v_mfma_f32_32x32x16_bf16 v[48:63], v[218:221], v[200:203], v[48:63]
	v_mfma_f32_32x32x16_bf16 v[16:31], v[214:217], v[210:213], v[16:31]
	v_mfma_f32_32x32x16_bf16 v[0:15], v[218:221], v[210:213], v[0:15]
	v_mfma_f32_32x32x16_bf16 v[32:47], v[72:75], v[64:67], v[32:47]
	v_mfma_f32_32x32x16_bf16 v[48:63], v[88:91], v[64:67], v[48:63]
	v_mfma_f32_32x32x16_bf16 v[16:31], v[72:75], v[68:71], v[16:31]
	v_mfma_f32_32x32x16_bf16 v[0:15], v[88:91], v[68:71], v[0:15]
	ds_read_b128 v[64:67], v128 offset:23040
	ds_read_b128 v[72:75], v128 offset:18432
	ds_read_b128 v[68:71], v131 offset:59904
	ds_read_b128 v[100:103], v131 offset:55296
	ds_read_b128 v[88:91], v128 offset:18464
	ds_read_b128 v[92:95], v128 offset:23072
	ds_read_b128 v[104:107], v131 offset:55328
	ds_read_b128 v[108:111], v131 offset:59936
	s_waitcnt lgkmcnt(4)
	v_mfma_f32_32x32x16_bf16 v[32:47], v[100:103], v[72:75], v[32:47]
	v_mfma_f32_32x32x16_bf16 v[48:63], v[68:71], v[72:75], v[48:63]
	v_mfma_f32_32x32x16_bf16 v[16:31], v[100:103], v[64:67], v[16:31]
	v_mfma_f32_32x32x16_bf16 v[0:15], v[68:71], v[64:67], v[0:15]
	global_load_dwordx4 v[64:67], v168, s[8:9] offset:640
	global_load_dwordx4 v[68:71], v169, s[8:9] offset:640
	global_load_dwordx4 v[72:75], v170, s[8:9] offset:640
	global_load_dwordx4 v[100:103], v171, s[8:9] offset:640
	global_load_dwordx4 v[172:175], v168, s[10:11] offset:640
	global_load_dwordx4 v[176:179], v169, s[10:11] offset:640
	global_load_dwordx4 v[180:183], v170, s[10:11] offset:640
	global_load_dwordx4 v[196:199], v171, s[10:11] offset:640
	ds_read_b128 v[200:203], v128 offset:18496
	ds_read_b128 v[210:213], v128 offset:23104
	ds_read_b128 v[214:217], v131 offset:55360
	ds_read_b128 v[218:221], v131 offset:59968
	s_waitcnt vmcnt(15)
	ds_write_b128 v130, v[76:79]
	s_waitcnt vmcnt(14)
	ds_write_b128 v130, v[80:83] offset:4608
	s_waitcnt vmcnt(13)
	ds_write_b128 v130, v[84:87] offset:9216
	s_waitcnt vmcnt(12)
	ds_write_b128 v130, v[96:99] offset:13824
	s_waitcnt lgkmcnt(9)
	v_mfma_f32_32x32x16_bf16 v[32:47], v[104:107], v[88:91], v[32:47]
	s_waitcnt lgkmcnt(8)
	v_mfma_f32_32x32x16_bf16 v[48:63], v[108:111], v[88:91], v[48:63]
	v_mfma_f32_32x32x16_bf16 v[16:31], v[104:107], v[92:95], v[16:31]
	v_mfma_f32_32x32x16_bf16 v[0:15], v[108:111], v[92:95], v[0:15]
	ds_read_b128 v[76:79], v128 offset:18528
	ds_read_b128 v[80:83], v128 offset:23136
	ds_read_b128 v[84:87], v131 offset:55392
	ds_read_b128 v[88:91], v131 offset:60000
	s_waitcnt vmcnt(11)
	ds_write_b128 v130, v[112:115] offset:36864
	s_waitcnt vmcnt(10)
	ds_write_b128 v130, v[116:119] offset:41472
	s_waitcnt vmcnt(9)
	ds_write_b128 v130, v[120:123] offset:46080
	s_waitcnt vmcnt(8)
	ds_write_b128 v130, v[124:127] offset:50688
	s_waitcnt lgkmcnt(13)
	v_mfma_f32_32x32x16_bf16 v[32:47], v[214:217], v[200:203], v[32:47]
	s_waitcnt lgkmcnt(0)
	s_barrier
	v_mfma_f32_32x32x16_bf16 v[48:63], v[218:221], v[200:203], v[48:63]
	v_mfma_f32_32x32x16_bf16 v[16:31], v[214:217], v[210:213], v[16:31]
	v_mfma_f32_32x32x16_bf16 v[0:15], v[218:221], v[210:213], v[0:15]
	v_mfma_f32_32x32x16_bf16 v[32:47], v[84:87], v[76:79], v[32:47]
	v_mfma_f32_32x32x16_bf16 v[48:63], v[88:91], v[76:79], v[48:63]
	v_mfma_f32_32x32x16_bf16 v[16:31], v[84:87], v[80:83], v[16:31]
	v_mfma_f32_32x32x16_bf16 v[0:15], v[88:91], v[80:83], v[0:15]
	ds_read_b128 v[76:79], v128 offset:4608
	ds_read_b128 v[84:87], v128
	ds_read_b128 v[80:83], v131 offset:41472
	ds_read_b128 v[96:99], v131 offset:36864
	ds_read_b128 v[88:91], v128 offset:32
	ds_read_b128 v[92:95], v128 offset:4640
	ds_read_b128 v[104:107], v131 offset:36896
	ds_read_b128 v[108:111], v131 offset:41504
	s_waitcnt lgkmcnt(4)
	v_mfma_f32_32x32x16_bf16 v[32:47], v[96:99], v[84:87], v[32:47]
	v_mfma_f32_32x32x16_bf16 v[48:63], v[80:83], v[84:87], v[48:63]
	v_mfma_f32_32x32x16_bf16 v[16:31], v[96:99], v[76:79], v[16:31]
	v_mfma_f32_32x32x16_bf16 v[0:15], v[80:83], v[76:79], v[0:15]
	global_load_dwordx4 v[76:79], v168, s[8:9] offset:768
	global_load_dwordx4 v[80:83], v169, s[8:9] offset:768
	global_load_dwordx4 v[84:87], v170, s[8:9] offset:768
	global_load_dwordx4 v[96:99], v171, s[8:9] offset:768
	global_load_dwordx4 v[112:115], v168, s[10:11] offset:768
	global_load_dwordx4 v[116:119], v169, s[10:11] offset:768
	global_load_dwordx4 v[120:123], v170, s[10:11] offset:768
	global_load_dwordx4 v[124:127], v171, s[10:11] offset:768
	ds_read_b128 v[200:203], v128 offset:64
	ds_read_b128 v[210:213], v128 offset:4672
	ds_read_b128 v[214:217], v131 offset:36928
	ds_read_b128 v[218:221], v131 offset:41536
	s_waitcnt vmcnt(15)
	ds_write_b128 v130, v[64:67] offset:18432
	s_waitcnt vmcnt(14)
	ds_write_b128 v130, v[68:71] offset:23040
	s_waitcnt vmcnt(13)
	ds_write_b128 v130, v[72:75] offset:27648
	s_waitcnt vmcnt(12)
	ds_write_b128 v130, v[100:103] offset:32256
	s_waitcnt lgkmcnt(9)
	v_mfma_f32_32x32x16_bf16 v[32:47], v[104:107], v[88:91], v[32:47]
	s_waitcnt lgkmcnt(8)
	v_mfma_f32_32x32x16_bf16 v[48:63], v[108:111], v[88:91], v[48:63]
	v_mfma_f32_32x32x16_bf16 v[16:31], v[104:107], v[92:95], v[16:31]
	v_mfma_f32_32x32x16_bf16 v[0:15], v[108:111], v[92:95], v[0:15]
	ds_read_b128 v[64:67], v128 offset:96
	ds_read_b128 v[68:71], v128 offset:4704
	ds_read_b128 v[72:75], v131 offset:36960
	ds_read_b128 v[88:91], v131 offset:41568
	s_waitcnt vmcnt(11)
	ds_write_b128 v130, v[172:175] offset:55296
	s_waitcnt vmcnt(10)
	ds_write_b128 v130, v[176:179] offset:59904
	s_waitcnt vmcnt(9)
	ds_write_b128 v130, v[180:183] offset:64512
	s_waitcnt vmcnt(8)
	ds_write_b128 v129, v[196:199] offset:13824
	s_waitcnt lgkmcnt(13)
	v_mfma_f32_32x32x16_bf16 v[32:47], v[214:217], v[200:203], v[32:47]
	s_waitcnt lgkmcnt(0)
	s_barrier
	v_mfma_f32_32x32x16_bf16 v[48:63], v[218:221], v[200:203], v[48:63]
	v_mfma_f32_32x32x16_bf16 v[16:31], v[214:217], v[210:213], v[16:31]
	v_mfma_f32_32x32x16_bf16 v[0:15], v[218:221], v[210:213], v[0:15]
	v_mfma_f32_32x32x16_bf16 v[32:47], v[72:75], v[64:67], v[32:47]
	v_mfma_f32_32x32x16_bf16 v[48:63], v[88:91], v[64:67], v[48:63]
	v_mfma_f32_32x32x16_bf16 v[16:31], v[72:75], v[68:71], v[16:31]
	v_mfma_f32_32x32x16_bf16 v[0:15], v[88:91], v[68:71], v[0:15]
	ds_read_b128 v[64:67], v128 offset:23040
	ds_read_b128 v[72:75], v128 offset:18432
	ds_read_b128 v[68:71], v131 offset:59904
	ds_read_b128 v[100:103], v131 offset:55296
	ds_read_b128 v[88:91], v128 offset:18464
	ds_read_b128 v[92:95], v128 offset:23072
	ds_read_b128 v[104:107], v131 offset:55328
	ds_read_b128 v[108:111], v131 offset:59936
	s_waitcnt lgkmcnt(4)
	v_mfma_f32_32x32x16_bf16 v[32:47], v[100:103], v[72:75], v[32:47]
	v_mfma_f32_32x32x16_bf16 v[48:63], v[68:71], v[72:75], v[48:63]
	v_mfma_f32_32x32x16_bf16 v[16:31], v[100:103], v[64:67], v[16:31]
	v_mfma_f32_32x32x16_bf16 v[0:15], v[68:71], v[64:67], v[0:15]
	global_load_dwordx4 v[64:67], v168, s[8:9] offset:896
	global_load_dwordx4 v[68:71], v169, s[8:9] offset:896
	global_load_dwordx4 v[72:75], v170, s[8:9] offset:896
	global_load_dwordx4 v[100:103], v171, s[8:9] offset:896
	global_load_dwordx4 v[172:175], v168, s[10:11] offset:896
	global_load_dwordx4 v[176:179], v169, s[10:11] offset:896
	global_load_dwordx4 v[180:183], v170, s[10:11] offset:896
	global_load_dwordx4 v[196:199], v171, s[10:11] offset:896
	ds_read_b128 v[200:203], v128 offset:18496
	ds_read_b128 v[210:213], v128 offset:23104
	ds_read_b128 v[214:217], v131 offset:55360
	ds_read_b128 v[218:221], v131 offset:59968
	s_waitcnt vmcnt(15)
	ds_write_b128 v130, v[76:79]
	s_waitcnt vmcnt(14)
	ds_write_b128 v130, v[80:83] offset:4608
	s_waitcnt vmcnt(13)
	ds_write_b128 v130, v[84:87] offset:9216
	s_waitcnt vmcnt(12)
	ds_write_b128 v130, v[96:99] offset:13824
	s_waitcnt lgkmcnt(9)
	v_mfma_f32_32x32x16_bf16 v[32:47], v[104:107], v[88:91], v[32:47]
	s_waitcnt lgkmcnt(8)
	v_mfma_f32_32x32x16_bf16 v[48:63], v[108:111], v[88:91], v[48:63]
	v_mfma_f32_32x32x16_bf16 v[16:31], v[104:107], v[92:95], v[16:31]
	v_mfma_f32_32x32x16_bf16 v[0:15], v[108:111], v[92:95], v[0:15]
	ds_read_b128 v[76:79], v128 offset:18528
	ds_read_b128 v[80:83], v128 offset:23136
	ds_read_b128 v[84:87], v131 offset:55392
	ds_read_b128 v[88:91], v131 offset:60000
	s_waitcnt vmcnt(11)
	ds_write_b128 v130, v[112:115] offset:36864
	s_waitcnt vmcnt(10)
	ds_write_b128 v130, v[116:119] offset:41472
	s_waitcnt vmcnt(9)
	ds_write_b128 v130, v[120:123] offset:46080
	s_waitcnt vmcnt(8)
	ds_write_b128 v130, v[124:127] offset:50688
	s_waitcnt lgkmcnt(13)
	v_mfma_f32_32x32x16_bf16 v[32:47], v[214:217], v[200:203], v[32:47]
	s_waitcnt lgkmcnt(0)
	s_barrier
	v_mfma_f32_32x32x16_bf16 v[48:63], v[218:221], v[200:203], v[48:63]
	v_mfma_f32_32x32x16_bf16 v[16:31], v[214:217], v[210:213], v[16:31]
	v_mfma_f32_32x32x16_bf16 v[0:15], v[218:221], v[210:213], v[0:15]
	v_mfma_f32_32x32x16_bf16 v[32:47], v[84:87], v[76:79], v[32:47]
	v_mfma_f32_32x32x16_bf16 v[48:63], v[88:91], v[76:79], v[48:63]
	v_mfma_f32_32x32x16_bf16 v[16:31], v[84:87], v[80:83], v[16:31]
	v_mfma_f32_32x32x16_bf16 v[0:15], v[88:91], v[80:83], v[0:15]
	ds_read_b128 v[76:79], v128 offset:4608
	ds_read_b128 v[84:87], v128
	ds_read_b128 v[80:83], v131 offset:41472
	ds_read_b128 v[96:99], v131 offset:36864
	ds_read_b128 v[88:91], v128 offset:32
	ds_read_b128 v[92:95], v128 offset:4640
	ds_read_b128 v[104:107], v131 offset:36896
	ds_read_b128 v[108:111], v131 offset:41504
	s_waitcnt lgkmcnt(4)
	v_mfma_f32_32x32x16_bf16 v[32:47], v[96:99], v[84:87], v[32:47]
	v_mfma_f32_32x32x16_bf16 v[48:63], v[80:83], v[84:87], v[48:63]
	v_mfma_f32_32x32x16_bf16 v[16:31], v[96:99], v[76:79], v[16:31]
	v_mfma_f32_32x32x16_bf16 v[0:15], v[80:83], v[76:79], v[0:15]
	global_load_dwordx4 v[76:79], v168, s[8:9] offset:1024
	global_load_dwordx4 v[80:83], v169, s[8:9] offset:1024
	global_load_dwordx4 v[84:87], v170, s[8:9] offset:1024
	global_load_dwordx4 v[96:99], v171, s[8:9] offset:1024
	global_load_dwordx4 v[112:115], v168, s[10:11] offset:1024
	global_load_dwordx4 v[116:119], v169, s[10:11] offset:1024
	global_load_dwordx4 v[120:123], v170, s[10:11] offset:1024
	global_load_dwordx4 v[124:127], v171, s[10:11] offset:1024
	ds_read_b128 v[200:203], v128 offset:64
	ds_read_b128 v[210:213], v128 offset:4672
	ds_read_b128 v[214:217], v131 offset:36928
	ds_read_b128 v[218:221], v131 offset:41536
	s_waitcnt vmcnt(15)
	ds_write_b128 v130, v[64:67] offset:18432
	s_waitcnt vmcnt(14)
	ds_write_b128 v130, v[68:71] offset:23040
	s_waitcnt vmcnt(13)
	ds_write_b128 v130, v[72:75] offset:27648
	s_waitcnt vmcnt(12)
	ds_write_b128 v130, v[100:103] offset:32256
	s_waitcnt lgkmcnt(9)
	v_mfma_f32_32x32x16_bf16 v[32:47], v[104:107], v[88:91], v[32:47]
	s_waitcnt lgkmcnt(8)
	v_mfma_f32_32x32x16_bf16 v[48:63], v[108:111], v[88:91], v[48:63]
	v_mfma_f32_32x32x16_bf16 v[16:31], v[104:107], v[92:95], v[16:31]
	v_mfma_f32_32x32x16_bf16 v[0:15], v[108:111], v[92:95], v[0:15]
	ds_read_b128 v[64:67], v128 offset:96
	ds_read_b128 v[68:71], v128 offset:4704
	ds_read_b128 v[72:75], v131 offset:36960
	ds_read_b128 v[88:91], v131 offset:41568
	s_waitcnt vmcnt(11)
	ds_write_b128 v130, v[172:175] offset:55296
	s_waitcnt vmcnt(10)
	ds_write_b128 v130, v[176:179] offset:59904
	s_waitcnt vmcnt(9)
	ds_write_b128 v130, v[180:183] offset:64512
	s_waitcnt vmcnt(8)
	ds_write_b128 v129, v[196:199] offset:13824
	s_waitcnt lgkmcnt(13)
	v_mfma_f32_32x32x16_bf16 v[32:47], v[214:217], v[200:203], v[32:47]
	s_waitcnt lgkmcnt(0)
	s_barrier
	v_mfma_f32_32x32x16_bf16 v[48:63], v[218:221], v[200:203], v[48:63]
	v_mfma_f32_32x32x16_bf16 v[16:31], v[214:217], v[210:213], v[16:31]
	v_mfma_f32_32x32x16_bf16 v[0:15], v[218:221], v[210:213], v[0:15]
	v_mfma_f32_32x32x16_bf16 v[32:47], v[72:75], v[64:67], v[32:47]
	v_mfma_f32_32x32x16_bf16 v[48:63], v[88:91], v[64:67], v[48:63]
	v_mfma_f32_32x32x16_bf16 v[16:31], v[72:75], v[68:71], v[16:31]
	v_mfma_f32_32x32x16_bf16 v[0:15], v[88:91], v[68:71], v[0:15]
	ds_read_b128 v[64:67], v128 offset:23040
	ds_read_b128 v[72:75], v128 offset:18432
	ds_read_b128 v[68:71], v131 offset:59904
	ds_read_b128 v[100:103], v131 offset:55296
	ds_read_b128 v[88:91], v128 offset:18464
	ds_read_b128 v[92:95], v128 offset:23072
	ds_read_b128 v[104:107], v131 offset:55328
	ds_read_b128 v[108:111], v131 offset:59936
	s_waitcnt lgkmcnt(4)
	v_mfma_f32_32x32x16_bf16 v[32:47], v[100:103], v[72:75], v[32:47]
	v_mfma_f32_32x32x16_bf16 v[48:63], v[68:71], v[72:75], v[48:63]
	v_mfma_f32_32x32x16_bf16 v[16:31], v[100:103], v[64:67], v[16:31]
	v_mfma_f32_32x32x16_bf16 v[0:15], v[68:71], v[64:67], v[0:15]
	global_load_dwordx4 v[64:67], v168, s[8:9] offset:1152
	global_load_dwordx4 v[68:71], v169, s[8:9] offset:1152
	global_load_dwordx4 v[72:75], v170, s[8:9] offset:1152
	global_load_dwordx4 v[100:103], v171, s[8:9] offset:1152
	global_load_dwordx4 v[172:175], v168, s[10:11] offset:1152
	global_load_dwordx4 v[176:179], v169, s[10:11] offset:1152
	global_load_dwordx4 v[180:183], v170, s[10:11] offset:1152
	global_load_dwordx4 v[196:199], v171, s[10:11] offset:1152
	ds_read_b128 v[200:203], v128 offset:18496
	ds_read_b128 v[210:213], v128 offset:23104
	ds_read_b128 v[214:217], v131 offset:55360
	ds_read_b128 v[218:221], v131 offset:59968
	s_waitcnt vmcnt(15)
	ds_write_b128 v130, v[76:79]
	s_waitcnt vmcnt(14)
	ds_write_b128 v130, v[80:83] offset:4608
	s_waitcnt vmcnt(13)
	ds_write_b128 v130, v[84:87] offset:9216
	s_waitcnt vmcnt(12)
	ds_write_b128 v130, v[96:99] offset:13824
	s_waitcnt lgkmcnt(9)
	v_mfma_f32_32x32x16_bf16 v[32:47], v[104:107], v[88:91], v[32:47]
	s_waitcnt lgkmcnt(8)
	v_mfma_f32_32x32x16_bf16 v[48:63], v[108:111], v[88:91], v[48:63]
	v_mfma_f32_32x32x16_bf16 v[16:31], v[104:107], v[92:95], v[16:31]
	v_mfma_f32_32x32x16_bf16 v[0:15], v[108:111], v[92:95], v[0:15]
	ds_read_b128 v[76:79], v128 offset:18528
	ds_read_b128 v[80:83], v128 offset:23136
	ds_read_b128 v[84:87], v131 offset:55392
	ds_read_b128 v[88:91], v131 offset:60000
	s_waitcnt vmcnt(11)
	ds_write_b128 v130, v[112:115] offset:36864
	s_waitcnt vmcnt(10)
	ds_write_b128 v130, v[116:119] offset:41472
	s_waitcnt vmcnt(9)
	ds_write_b128 v130, v[120:123] offset:46080
	s_waitcnt vmcnt(8)
	ds_write_b128 v130, v[124:127] offset:50688
	s_waitcnt lgkmcnt(13)
	v_mfma_f32_32x32x16_bf16 v[32:47], v[214:217], v[200:203], v[32:47]
	s_waitcnt lgkmcnt(0)
	s_barrier
	v_mfma_f32_32x32x16_bf16 v[48:63], v[218:221], v[200:203], v[48:63]
	v_mfma_f32_32x32x16_bf16 v[16:31], v[214:217], v[210:213], v[16:31]
	v_mfma_f32_32x32x16_bf16 v[0:15], v[218:221], v[210:213], v[0:15]
	v_mfma_f32_32x32x16_bf16 v[32:47], v[84:87], v[76:79], v[32:47]
	v_mfma_f32_32x32x16_bf16 v[48:63], v[88:91], v[76:79], v[48:63]
	v_mfma_f32_32x32x16_bf16 v[16:31], v[84:87], v[80:83], v[16:31]
	v_mfma_f32_32x32x16_bf16 v[0:15], v[88:91], v[80:83], v[0:15]
	ds_read_b128 v[76:79], v128 offset:4608
	ds_read_b128 v[84:87], v128
	ds_read_b128 v[80:83], v131 offset:41472
	ds_read_b128 v[96:99], v131 offset:36864
	ds_read_b128 v[88:91], v128 offset:32
	ds_read_b128 v[92:95], v128 offset:4640
	ds_read_b128 v[104:107], v131 offset:36896
	ds_read_b128 v[108:111], v131 offset:41504
	s_waitcnt lgkmcnt(4)
	v_mfma_f32_32x32x16_bf16 v[32:47], v[96:99], v[84:87], v[32:47]
	v_mfma_f32_32x32x16_bf16 v[48:63], v[80:83], v[84:87], v[48:63]
	v_mfma_f32_32x32x16_bf16 v[16:31], v[96:99], v[76:79], v[16:31]
	v_mfma_f32_32x32x16_bf16 v[0:15], v[80:83], v[76:79], v[0:15]
	global_load_dwordx4 v[76:79], v168, s[8:9] offset:1280
	global_load_dwordx4 v[80:83], v169, s[8:9] offset:1280
	global_load_dwordx4 v[84:87], v170, s[8:9] offset:1280
	global_load_dwordx4 v[96:99], v171, s[8:9] offset:1280
	global_load_dwordx4 v[112:115], v168, s[10:11] offset:1280
	global_load_dwordx4 v[116:119], v169, s[10:11] offset:1280
	global_load_dwordx4 v[120:123], v170, s[10:11] offset:1280
	global_load_dwordx4 v[124:127], v171, s[10:11] offset:1280
	ds_read_b128 v[200:203], v128 offset:64
	ds_read_b128 v[210:213], v128 offset:4672
	ds_read_b128 v[214:217], v131 offset:36928
	ds_read_b128 v[218:221], v131 offset:41536
	s_waitcnt vmcnt(15)
	ds_write_b128 v130, v[64:67] offset:18432
	s_waitcnt vmcnt(14)
	ds_write_b128 v130, v[68:71] offset:23040
	s_waitcnt vmcnt(13)
	ds_write_b128 v130, v[72:75] offset:27648
	s_waitcnt vmcnt(12)
	ds_write_b128 v130, v[100:103] offset:32256
	s_waitcnt lgkmcnt(9)
	v_mfma_f32_32x32x16_bf16 v[32:47], v[104:107], v[88:91], v[32:47]
	s_waitcnt lgkmcnt(8)
	v_mfma_f32_32x32x16_bf16 v[48:63], v[108:111], v[88:91], v[48:63]
	v_mfma_f32_32x32x16_bf16 v[16:31], v[104:107], v[92:95], v[16:31]
	v_mfma_f32_32x32x16_bf16 v[0:15], v[108:111], v[92:95], v[0:15]
	ds_read_b128 v[64:67], v128 offset:96
	ds_read_b128 v[68:71], v128 offset:4704
	ds_read_b128 v[72:75], v131 offset:36960
	ds_read_b128 v[88:91], v131 offset:41568
	s_waitcnt vmcnt(11)
	ds_write_b128 v130, v[172:175] offset:55296
	s_waitcnt vmcnt(10)
	ds_write_b128 v130, v[176:179] offset:59904
	s_waitcnt vmcnt(9)
	ds_write_b128 v130, v[180:183] offset:64512
	s_waitcnt vmcnt(8)
	ds_write_b128 v129, v[196:199] offset:13824
	s_waitcnt lgkmcnt(13)
	v_mfma_f32_32x32x16_bf16 v[32:47], v[214:217], v[200:203], v[32:47]
	s_waitcnt lgkmcnt(0)
	s_barrier
	v_mfma_f32_32x32x16_bf16 v[48:63], v[218:221], v[200:203], v[48:63]
	v_mfma_f32_32x32x16_bf16 v[16:31], v[214:217], v[210:213], v[16:31]
	v_mfma_f32_32x32x16_bf16 v[0:15], v[218:221], v[210:213], v[0:15]
	v_mfma_f32_32x32x16_bf16 v[32:47], v[72:75], v[64:67], v[32:47]
	v_mfma_f32_32x32x16_bf16 v[48:63], v[88:91], v[64:67], v[48:63]
	v_mfma_f32_32x32x16_bf16 v[16:31], v[72:75], v[68:71], v[16:31]
	v_mfma_f32_32x32x16_bf16 v[0:15], v[88:91], v[68:71], v[0:15]
	ds_read_b128 v[64:67], v128 offset:23040
	ds_read_b128 v[72:75], v128 offset:18432
	ds_read_b128 v[68:71], v131 offset:59904
	ds_read_b128 v[100:103], v131 offset:55296
	ds_read_b128 v[88:91], v128 offset:18464
	ds_read_b128 v[92:95], v128 offset:23072
	ds_read_b128 v[104:107], v131 offset:55328
	ds_read_b128 v[108:111], v131 offset:59936
	s_waitcnt lgkmcnt(4)
	v_mfma_f32_32x32x16_bf16 v[32:47], v[100:103], v[72:75], v[32:47]
	v_mfma_f32_32x32x16_bf16 v[48:63], v[68:71], v[72:75], v[48:63]
	v_mfma_f32_32x32x16_bf16 v[16:31], v[100:103], v[64:67], v[16:31]
	v_mfma_f32_32x32x16_bf16 v[0:15], v[68:71], v[64:67], v[0:15]
	global_load_dwordx4 v[64:67], v168, s[8:9] offset:1408
	global_load_dwordx4 v[68:71], v169, s[8:9] offset:1408
	global_load_dwordx4 v[72:75], v170, s[8:9] offset:1408
	global_load_dwordx4 v[100:103], v171, s[8:9] offset:1408
	global_load_dwordx4 v[172:175], v168, s[10:11] offset:1408
	global_load_dwordx4 v[176:179], v169, s[10:11] offset:1408
	global_load_dwordx4 v[180:183], v170, s[10:11] offset:1408
	global_load_dwordx4 v[196:199], v171, s[10:11] offset:1408
	ds_read_b128 v[200:203], v128 offset:18496
	ds_read_b128 v[210:213], v128 offset:23104
	ds_read_b128 v[214:217], v131 offset:55360
	ds_read_b128 v[218:221], v131 offset:59968
	s_waitcnt vmcnt(15)
	ds_write_b128 v130, v[76:79]
	s_waitcnt vmcnt(14)
	ds_write_b128 v130, v[80:83] offset:4608
	s_waitcnt vmcnt(13)
	ds_write_b128 v130, v[84:87] offset:9216
	s_waitcnt vmcnt(12)
	ds_write_b128 v130, v[96:99] offset:13824
	s_waitcnt lgkmcnt(9)
	v_mfma_f32_32x32x16_bf16 v[32:47], v[104:107], v[88:91], v[32:47]
	s_waitcnt lgkmcnt(8)
	v_mfma_f32_32x32x16_bf16 v[48:63], v[108:111], v[88:91], v[48:63]
	v_mfma_f32_32x32x16_bf16 v[16:31], v[104:107], v[92:95], v[16:31]
	v_mfma_f32_32x32x16_bf16 v[0:15], v[108:111], v[92:95], v[0:15]
	ds_read_b128 v[76:79], v128 offset:18528
	ds_read_b128 v[80:83], v128 offset:23136
	ds_read_b128 v[84:87], v131 offset:55392
	ds_read_b128 v[88:91], v131 offset:60000
	s_waitcnt vmcnt(11)
	ds_write_b128 v130, v[112:115] offset:36864
	s_waitcnt vmcnt(10)
	ds_write_b128 v130, v[116:119] offset:41472
	s_waitcnt vmcnt(9)
	ds_write_b128 v130, v[120:123] offset:46080
	s_waitcnt vmcnt(8)
	ds_write_b128 v130, v[124:127] offset:50688
	s_waitcnt lgkmcnt(13)
	v_mfma_f32_32x32x16_bf16 v[32:47], v[214:217], v[200:203], v[32:47]
	s_waitcnt lgkmcnt(0)
	s_barrier
	v_mfma_f32_32x32x16_bf16 v[48:63], v[218:221], v[200:203], v[48:63]
	v_mfma_f32_32x32x16_bf16 v[16:31], v[214:217], v[210:213], v[16:31]
	v_mfma_f32_32x32x16_bf16 v[0:15], v[218:221], v[210:213], v[0:15]
	v_mfma_f32_32x32x16_bf16 v[32:47], v[84:87], v[76:79], v[32:47]
	v_mfma_f32_32x32x16_bf16 v[48:63], v[88:91], v[76:79], v[48:63]
	v_mfma_f32_32x32x16_bf16 v[16:31], v[84:87], v[80:83], v[16:31]
	v_mfma_f32_32x32x16_bf16 v[0:15], v[88:91], v[80:83], v[0:15]
	ds_read_b128 v[76:79], v128 offset:4608
	ds_read_b128 v[84:87], v128
	ds_read_b128 v[80:83], v131 offset:41472
	ds_read_b128 v[96:99], v131 offset:36864
	ds_read_b128 v[88:91], v128 offset:32
	ds_read_b128 v[92:95], v128 offset:4640
	ds_read_b128 v[104:107], v131 offset:36896
	ds_read_b128 v[108:111], v131 offset:41504
	s_waitcnt lgkmcnt(4)
	v_mfma_f32_32x32x16_bf16 v[32:47], v[96:99], v[84:87], v[32:47]
	v_mfma_f32_32x32x16_bf16 v[48:63], v[80:83], v[84:87], v[48:63]
	v_mfma_f32_32x32x16_bf16 v[16:31], v[96:99], v[76:79], v[16:31]
	v_mfma_f32_32x32x16_bf16 v[0:15], v[80:83], v[76:79], v[0:15]
	global_load_dwordx4 v[76:79], v168, s[8:9] offset:1536
	global_load_dwordx4 v[80:83], v169, s[8:9] offset:1536
	global_load_dwordx4 v[84:87], v170, s[8:9] offset:1536
	global_load_dwordx4 v[96:99], v171, s[8:9] offset:1536
	global_load_dwordx4 v[112:115], v168, s[10:11] offset:1536
	global_load_dwordx4 v[116:119], v169, s[10:11] offset:1536
	global_load_dwordx4 v[120:123], v170, s[10:11] offset:1536
	global_load_dwordx4 v[124:127], v171, s[10:11] offset:1536
	ds_read_b128 v[200:203], v128 offset:64
	ds_read_b128 v[210:213], v128 offset:4672
	ds_read_b128 v[214:217], v131 offset:36928
	ds_read_b128 v[218:221], v131 offset:41536
	s_waitcnt vmcnt(15)
	ds_write_b128 v130, v[64:67] offset:18432
	s_waitcnt vmcnt(14)
	ds_write_b128 v130, v[68:71] offset:23040
	s_waitcnt vmcnt(13)
	ds_write_b128 v130, v[72:75] offset:27648
	s_waitcnt vmcnt(12)
	ds_write_b128 v130, v[100:103] offset:32256
	s_waitcnt lgkmcnt(9)
	v_mfma_f32_32x32x16_bf16 v[32:47], v[104:107], v[88:91], v[32:47]
	s_waitcnt lgkmcnt(8)
	v_mfma_f32_32x32x16_bf16 v[48:63], v[108:111], v[88:91], v[48:63]
	v_mfma_f32_32x32x16_bf16 v[16:31], v[104:107], v[92:95], v[16:31]
	v_mfma_f32_32x32x16_bf16 v[0:15], v[108:111], v[92:95], v[0:15]
	ds_read_b128 v[64:67], v128 offset:96
	ds_read_b128 v[68:71], v128 offset:4704
	ds_read_b128 v[72:75], v131 offset:36960
	ds_read_b128 v[88:91], v131 offset:41568
	s_waitcnt vmcnt(11)
	ds_write_b128 v130, v[172:175] offset:55296
	s_waitcnt vmcnt(10)
	ds_write_b128 v130, v[176:179] offset:59904
	s_waitcnt vmcnt(9)
	ds_write_b128 v130, v[180:183] offset:64512
	s_waitcnt vmcnt(8)
	ds_write_b128 v129, v[196:199] offset:13824
	s_waitcnt lgkmcnt(13)
	v_mfma_f32_32x32x16_bf16 v[32:47], v[214:217], v[200:203], v[32:47]
	s_waitcnt lgkmcnt(0)
	s_barrier
	v_mfma_f32_32x32x16_bf16 v[48:63], v[218:221], v[200:203], v[48:63]
	v_mfma_f32_32x32x16_bf16 v[16:31], v[214:217], v[210:213], v[16:31]
	v_mfma_f32_32x32x16_bf16 v[0:15], v[218:221], v[210:213], v[0:15]
	v_mfma_f32_32x32x16_bf16 v[32:47], v[72:75], v[64:67], v[32:47]
	v_mfma_f32_32x32x16_bf16 v[48:63], v[88:91], v[64:67], v[48:63]
	v_mfma_f32_32x32x16_bf16 v[16:31], v[72:75], v[68:71], v[16:31]
	v_mfma_f32_32x32x16_bf16 v[0:15], v[88:91], v[68:71], v[0:15]
	ds_read_b128 v[64:67], v128 offset:23040
	ds_read_b128 v[72:75], v128 offset:18432
	ds_read_b128 v[68:71], v131 offset:59904
	ds_read_b128 v[100:103], v131 offset:55296
	ds_read_b128 v[88:91], v128 offset:18464
	ds_read_b128 v[92:95], v128 offset:23072
	ds_read_b128 v[104:107], v131 offset:55328
	ds_read_b128 v[108:111], v131 offset:59936
	s_waitcnt lgkmcnt(4)
	v_mfma_f32_32x32x16_bf16 v[32:47], v[100:103], v[72:75], v[32:47]
	v_mfma_f32_32x32x16_bf16 v[48:63], v[68:71], v[72:75], v[48:63]
	v_mfma_f32_32x32x16_bf16 v[16:31], v[100:103], v[64:67], v[16:31]
	v_mfma_f32_32x32x16_bf16 v[0:15], v[68:71], v[64:67], v[0:15]
	global_load_dwordx4 v[64:67], v168, s[8:9] offset:1664
	global_load_dwordx4 v[68:71], v169, s[8:9] offset:1664
	global_load_dwordx4 v[72:75], v170, s[8:9] offset:1664
	global_load_dwordx4 v[100:103], v171, s[8:9] offset:1664
	global_load_dwordx4 v[172:175], v168, s[10:11] offset:1664
	global_load_dwordx4 v[176:179], v169, s[10:11] offset:1664
	global_load_dwordx4 v[180:183], v170, s[10:11] offset:1664
	global_load_dwordx4 v[196:199], v171, s[10:11] offset:1664
	ds_read_b128 v[200:203], v128 offset:18496
	ds_read_b128 v[210:213], v128 offset:23104
	ds_read_b128 v[214:217], v131 offset:55360
	ds_read_b128 v[218:221], v131 offset:59968
	s_waitcnt vmcnt(15)
	ds_write_b128 v130, v[76:79]
	s_waitcnt vmcnt(14)
	ds_write_b128 v130, v[80:83] offset:4608
	s_waitcnt vmcnt(13)
	ds_write_b128 v130, v[84:87] offset:9216
	s_waitcnt vmcnt(12)
	ds_write_b128 v130, v[96:99] offset:13824
	s_waitcnt lgkmcnt(9)
	v_mfma_f32_32x32x16_bf16 v[32:47], v[104:107], v[88:91], v[32:47]
	s_waitcnt lgkmcnt(8)
	v_mfma_f32_32x32x16_bf16 v[48:63], v[108:111], v[88:91], v[48:63]
	v_mfma_f32_32x32x16_bf16 v[16:31], v[104:107], v[92:95], v[16:31]
	v_mfma_f32_32x32x16_bf16 v[0:15], v[108:111], v[92:95], v[0:15]
	ds_read_b128 v[76:79], v128 offset:18528
	ds_read_b128 v[80:83], v128 offset:23136
	ds_read_b128 v[84:87], v131 offset:55392
	ds_read_b128 v[88:91], v131 offset:60000
	s_waitcnt vmcnt(11)
	ds_write_b128 v130, v[112:115] offset:36864
	s_waitcnt vmcnt(10)
	ds_write_b128 v130, v[116:119] offset:41472
	s_waitcnt vmcnt(9)
	ds_write_b128 v130, v[120:123] offset:46080
	s_waitcnt vmcnt(8)
	ds_write_b128 v130, v[124:127] offset:50688
	s_waitcnt lgkmcnt(13)
	v_mfma_f32_32x32x16_bf16 v[32:47], v[214:217], v[200:203], v[32:47]
	s_waitcnt lgkmcnt(0)
	s_barrier
	v_mfma_f32_32x32x16_bf16 v[48:63], v[218:221], v[200:203], v[48:63]
	v_mfma_f32_32x32x16_bf16 v[16:31], v[214:217], v[210:213], v[16:31]
	v_mfma_f32_32x32x16_bf16 v[0:15], v[218:221], v[210:213], v[0:15]
	v_mfma_f32_32x32x16_bf16 v[32:47], v[84:87], v[76:79], v[32:47]
	v_mfma_f32_32x32x16_bf16 v[48:63], v[88:91], v[76:79], v[48:63]
	v_mfma_f32_32x32x16_bf16 v[16:31], v[84:87], v[80:83], v[16:31]
	v_mfma_f32_32x32x16_bf16 v[0:15], v[88:91], v[80:83], v[0:15]
	ds_read_b128 v[76:79], v128 offset:4608
	ds_read_b128 v[84:87], v128
	ds_read_b128 v[80:83], v131 offset:41472
	ds_read_b128 v[96:99], v131 offset:36864
	ds_read_b128 v[88:91], v128 offset:32
	ds_read_b128 v[92:95], v128 offset:4640
	ds_read_b128 v[104:107], v131 offset:36896
	ds_read_b128 v[108:111], v131 offset:41504
	s_waitcnt lgkmcnt(4)
	v_mfma_f32_32x32x16_bf16 v[32:47], v[96:99], v[84:87], v[32:47]
	v_mfma_f32_32x32x16_bf16 v[48:63], v[80:83], v[84:87], v[48:63]
	v_mfma_f32_32x32x16_bf16 v[16:31], v[96:99], v[76:79], v[16:31]
	v_mfma_f32_32x32x16_bf16 v[0:15], v[80:83], v[76:79], v[0:15]
	global_load_dwordx4 v[76:79], v168, s[8:9] offset:1792
	global_load_dwordx4 v[80:83], v169, s[8:9] offset:1792
	global_load_dwordx4 v[84:87], v170, s[8:9] offset:1792
	global_load_dwordx4 v[96:99], v171, s[8:9] offset:1792
	global_load_dwordx4 v[112:115], v168, s[10:11] offset:1792
	global_load_dwordx4 v[116:119], v169, s[10:11] offset:1792
	global_load_dwordx4 v[120:123], v170, s[10:11] offset:1792
	global_load_dwordx4 v[124:127], v171, s[10:11] offset:1792
	ds_read_b128 v[200:203], v128 offset:64
	ds_read_b128 v[210:213], v128 offset:4672
	ds_read_b128 v[214:217], v131 offset:36928
	ds_read_b128 v[218:221], v131 offset:41536
	s_waitcnt vmcnt(15)
	ds_write_b128 v130, v[64:67] offset:18432
	s_waitcnt vmcnt(14)
	ds_write_b128 v130, v[68:71] offset:23040
	s_waitcnt vmcnt(13)
	ds_write_b128 v130, v[72:75] offset:27648
	s_waitcnt vmcnt(12)
	ds_write_b128 v130, v[100:103] offset:32256
	s_waitcnt lgkmcnt(9)
	v_mfma_f32_32x32x16_bf16 v[32:47], v[104:107], v[88:91], v[32:47]
	s_waitcnt lgkmcnt(8)
	v_mfma_f32_32x32x16_bf16 v[48:63], v[108:111], v[88:91], v[48:63]
	v_mfma_f32_32x32x16_bf16 v[16:31], v[104:107], v[92:95], v[16:31]
	v_mfma_f32_32x32x16_bf16 v[0:15], v[108:111], v[92:95], v[0:15]
	ds_read_b128 v[64:67], v128 offset:96
	ds_read_b128 v[68:71], v128 offset:4704
	ds_read_b128 v[72:75], v131 offset:36960
	ds_read_b128 v[88:91], v131 offset:41568
	s_waitcnt vmcnt(11)
	ds_write_b128 v130, v[172:175] offset:55296
	s_waitcnt vmcnt(10)
	ds_write_b128 v130, v[176:179] offset:59904
	s_waitcnt vmcnt(9)
	ds_write_b128 v130, v[180:183] offset:64512
	s_waitcnt vmcnt(8)
	ds_write_b128 v129, v[196:199] offset:13824
	s_waitcnt lgkmcnt(13)
	v_mfma_f32_32x32x16_bf16 v[32:47], v[214:217], v[200:203], v[32:47]
	s_waitcnt lgkmcnt(0)
	s_barrier
	v_mfma_f32_32x32x16_bf16 v[48:63], v[218:221], v[200:203], v[48:63]
	v_mfma_f32_32x32x16_bf16 v[16:31], v[214:217], v[210:213], v[16:31]
	v_mfma_f32_32x32x16_bf16 v[0:15], v[218:221], v[210:213], v[0:15]
	v_mfma_f32_32x32x16_bf16 v[32:47], v[72:75], v[64:67], v[32:47]
	v_mfma_f32_32x32x16_bf16 v[48:63], v[88:91], v[64:67], v[48:63]
	v_mfma_f32_32x32x16_bf16 v[16:31], v[72:75], v[68:71], v[16:31]
	v_mfma_f32_32x32x16_bf16 v[0:15], v[88:91], v[68:71], v[0:15]
	ds_read_b128 v[64:67], v128 offset:23040
	ds_read_b128 v[72:75], v128 offset:18432
	ds_read_b128 v[68:71], v131 offset:59904
	ds_read_b128 v[100:103], v131 offset:55296
	ds_read_b128 v[88:91], v128 offset:18464
	ds_read_b128 v[92:95], v128 offset:23072
	ds_read_b128 v[104:107], v131 offset:55328
	ds_read_b128 v[108:111], v131 offset:59936
	s_waitcnt lgkmcnt(4)
	v_mfma_f32_32x32x16_bf16 v[32:47], v[100:103], v[72:75], v[32:47]
	v_mfma_f32_32x32x16_bf16 v[48:63], v[68:71], v[72:75], v[48:63]
	v_mfma_f32_32x32x16_bf16 v[16:31], v[100:103], v[64:67], v[16:31]
	v_mfma_f32_32x32x16_bf16 v[0:15], v[68:71], v[64:67], v[0:15]
	global_load_dwordx4 v[64:67], v168, s[8:9] offset:1920
	global_load_dwordx4 v[68:71], v169, s[8:9] offset:1920
	global_load_dwordx4 v[72:75], v170, s[8:9] offset:1920
	global_load_dwordx4 v[100:103], v171, s[8:9] offset:1920
	global_load_dwordx4 v[172:175], v168, s[10:11] offset:1920
	global_load_dwordx4 v[176:179], v169, s[10:11] offset:1920
	global_load_dwordx4 v[180:183], v170, s[10:11] offset:1920
	s_nop 0
	global_load_dwordx4 v[168:171], v171, s[10:11] offset:1920
	ds_read_b128 v[196:199], v128 offset:18496
	ds_read_b128 v[200:203], v128 offset:23104
	ds_read_b128 v[210:213], v131 offset:55360
	ds_read_b128 v[214:217], v131 offset:59968
	s_waitcnt vmcnt(15)
	ds_write_b128 v130, v[76:79]
	s_waitcnt vmcnt(14)
	ds_write_b128 v130, v[80:83] offset:4608
	s_waitcnt vmcnt(13)
	ds_write_b128 v130, v[84:87] offset:9216
	s_waitcnt vmcnt(12)
	ds_write_b128 v130, v[96:99] offset:13824
	s_waitcnt lgkmcnt(9)
	v_mfma_f32_32x32x16_bf16 v[32:47], v[104:107], v[88:91], v[32:47]
	s_waitcnt lgkmcnt(8)
	v_mfma_f32_32x32x16_bf16 v[48:63], v[108:111], v[88:91], v[48:63]
	v_mfma_f32_32x32x16_bf16 v[0:15], v[108:111], v[92:95], v[0:15]
	v_mfma_f32_32x32x16_bf16 v[16:31], v[104:107], v[92:95], v[16:31]
	ds_read_b128 v[76:79], v128 offset:18528
	ds_read_b128 v[80:83], v128 offset:23136
	ds_read_b128 v[84:87], v131 offset:55392
	ds_read_b128 v[88:91], v131 offset:60000
	s_waitcnt vmcnt(11)
	ds_write_b128 v130, v[112:115] offset:36864
	s_waitcnt vmcnt(10)
	ds_write_b128 v130, v[116:119] offset:41472
	s_waitcnt vmcnt(9)
	ds_write_b128 v130, v[120:123] offset:46080
	s_waitcnt vmcnt(8)
	ds_write_b128 v130, v[124:127] offset:50688
	s_waitcnt lgkmcnt(13)
	v_mfma_f32_32x32x16_bf16 v[32:47], v[210:213], v[196:199], v[32:47]
	s_waitcnt lgkmcnt(0)
	s_barrier
	ds_read_b128 v[92:95], v128
	ds_read_b128 v[96:99], v128 offset:32
	ds_read_b128 v[104:107], v131 offset:36928
	ds_read_b128 v[108:111], v131 offset:41536
	v_mfma_f32_32x32x16_bf16 v[48:63], v[214:217], v[196:199], v[48:63]
	v_mfma_f32_32x32x16_bf16 v[0:15], v[214:217], v[200:203], v[0:15]
	v_mfma_f32_32x32x16_bf16 v[16:31], v[210:213], v[200:203], v[16:31]
	v_mfma_f32_32x32x16_bf16 v[32:47], v[84:87], v[76:79], v[32:47]
	v_mfma_f32_32x32x16_bf16 v[48:63], v[88:91], v[76:79], v[48:63]
	ds_read_b128 v[76:79], v128 offset:4608
	v_mfma_f32_32x32x16_bf16 v[0:15], v[88:91], v[80:83], v[0:15]
	ds_read_b128 v[88:91], v131 offset:36896
	v_mfma_f32_32x32x16_bf16 v[16:31], v[84:87], v[80:83], v[16:31]
	ds_read_b128 v[80:83], v131 offset:41472
	ds_read_b128 v[84:87], v131 offset:36864
	s_waitcnt lgkmcnt(1)
	v_mfma_f32_32x32x16_bf16 v[48:63], v[80:83], v[92:95], v[48:63]
	v_mfma_f32_32x32x16_bf16 v[0:15], v[80:83], v[76:79], v[0:15]
	ds_read_b128 v[80:83], v128 offset:4640
	s_waitcnt lgkmcnt(1)
	v_mfma_f32_32x32x16_bf16 v[32:47], v[84:87], v[92:95], v[32:47]
	ds_read_b128 v[92:95], v128 offset:4672
	v_mfma_f32_32x32x16_bf16 v[16:31], v[84:87], v[76:79], v[16:31]
	ds_read_b128 v[76:79], v131 offset:41504
	ds_read_b128 v[84:87], v128 offset:64
	s_waitcnt vmcnt(7)
	ds_write_b128 v130, v[64:67] offset:18432
	s_waitcnt vmcnt(6)
	ds_write_b128 v130, v[68:71] offset:23040
	s_waitcnt vmcnt(5)
	ds_write_b128 v130, v[72:75] offset:27648
	s_waitcnt vmcnt(4)
	ds_write_b128 v130, v[100:103] offset:32256
	ds_read_b128 v[64:67], v128 offset:96
	v_mfma_f32_32x32x16_bf16 v[32:47], v[88:91], v[96:99], v[32:47]
	ds_read_b128 v[68:71], v128 offset:4704
	ds_read_b128 v[72:75], v131 offset:36960
	s_waitcnt lgkmcnt(10)
	v_mfma_f32_32x32x16_bf16 v[16:31], v[88:91], v[80:83], v[16:31]
	s_waitcnt lgkmcnt(8)
	v_mfma_f32_32x32x16_bf16 v[48:63], v[76:79], v[96:99], v[48:63]
	v_mfma_f32_32x32x16_bf16 v[0:15], v[76:79], v[80:83], v[0:15]
	ds_read_b128 v[76:79], v131 offset:41568
	s_waitcnt vmcnt(3)
	ds_write_b128 v130, v[172:175] offset:55296
	s_waitcnt vmcnt(2)
	ds_write_b128 v130, v[176:179] offset:59904
	s_waitcnt vmcnt(1)
	ds_write_b128 v130, v[180:183] offset:64512
	s_waitcnt vmcnt(0)
	ds_write_b128 v129, v[168:171] offset:13824
	s_waitcnt lgkmcnt(0)
	s_barrier
	v_mfma_f32_32x32x16_bf16 v[32:47], v[104:107], v[84:87], v[32:47]
	ds_read_b128 v[96:99], v128 offset:18464
	ds_read_b128 v[100:103], v128 offset:23072
	ds_read_b128 v[80:83], v131 offset:55360
	ds_read_b128 v[88:91], v131 offset:55392
	v_mfma_f32_32x32x16_bf16 v[16:31], v[104:107], v[92:95], v[16:31]
	ds_read_b128 v[104:107], v131 offset:55328
	v_mfma_f32_32x32x16_bf16 v[48:63], v[108:111], v[84:87], v[48:63]
	ds_read_b128 v[84:87], v131 offset:59968
	v_mfma_f32_32x32x16_bf16 v[0:15], v[108:111], v[92:95], v[0:15]
	ds_read_b128 v[108:111], v131 offset:59936
	ds_read_b128 v[92:95], v131 offset:60000
	v_mfma_f32_32x32x16_bf16 v[32:47], v[72:75], v[64:67], v[32:47]
	v_mfma_f32_32x32x16_bf16 v[16:31], v[72:75], v[68:71], v[16:31]
	ds_read_b128 v[72:75], v128 offset:18432
	v_mfma_f32_32x32x16_bf16 v[48:63], v[76:79], v[64:67], v[48:63]
	ds_read_b128 v[64:67], v128 offset:23040
	v_mfma_f32_32x32x16_bf16 v[0:15], v[76:79], v[68:71], v[0:15]
	ds_read_b128 v[76:79], v131 offset:55296
	ds_read_b128 v[68:71], v131 offset:59904
	s_waitcnt lgkmcnt(1)
	v_mfma_f32_32x32x16_bf16 v[32:47], v[76:79], v[72:75], v[32:47]
	s_waitcnt lgkmcnt(0)
	v_mfma_f32_32x32x16_bf16 v[48:63], v[68:71], v[72:75], v[48:63]
	ds_read_b128 v[72:75], v128 offset:18496
	v_mfma_f32_32x32x16_bf16 v[16:31], v[76:79], v[64:67], v[16:31]
	ds_read_b128 v[76:79], v128 offset:18528
	v_mfma_f32_32x32x16_bf16 v[0:15], v[68:71], v[64:67], v[0:15]
	ds_read_b128 v[64:67], v128 offset:23104
	ds_read_b128 v[68:71], v128 offset:23136
	s_waitcnt lgkmcnt(0)
	s_barrier
	v_mfma_f32_32x32x16_bf16 v[32:47], v[104:107], v[96:99], v[32:47]
	v_mfma_f32_32x32x16_bf16 v[16:31], v[104:107], v[100:103], v[16:31]
	v_mfma_f32_32x32x16_bf16 v[0:15], v[108:111], v[100:103], v[0:15]
	v_mfma_f32_32x32x16_bf16 v[32:47], v[80:83], v[72:75], v[32:47]
	v_mfma_f32_32x32x16_bf16 v[16:31], v[80:83], v[64:67], v[16:31]
	v_mfma_f32_32x32x16_bf16 v[0:15], v[84:87], v[64:67], v[0:15]
	v_mfma_f32_32x32x16_bf16 v[32:47], v[88:91], v[76:79], v[32:47]
	v_mfma_f32_32x32x16_bf16 v[48:63], v[108:111], v[96:99], v[48:63]
	v_mfma_f32_32x32x16_bf16 v[16:31], v[88:91], v[68:71], v[16:31]
	v_mfma_f32_32x32x16_bf16 v[0:15], v[92:95], v[68:71], v[0:15]
	v_mfma_f32_32x32x16_bf16 v[48:63], v[84:87], v[72:75], v[48:63]
	v_mfma_f32_32x32x16_bf16 v[48:63], v[92:95], v[76:79], v[48:63]
	v_and_b32_e32 v64, 63, v186
	v_lshrrev_b32_e32 v65, 6, v186
	v_and_b32_e32 v66, 31, v64
	v_lshrrev_b32_e32 v67, 5, v64
	v_lshrrev_b32_e32 v68, 1, v65
	v_and_b32_e32 v65, 1, v65
	v_lshl_add_u32 v66, v68, 6, v66
	v_mul_u32_u24_e32 v66, 0x1600, v66
	v_lshl_add_u32 v66, v65, 6, v66
	v_lshl_add_u32 v66, v67, 3, v66
	v_add_u32_e32 v67, 0x2c000, v66
	s_mul_i32 s8, s6, 0x1600
	s_lshl_b32 s9, s4, 7
	s_add_i32 s8, s8, s9
	s_add_u32 s10, s0, s8
	s_addc_u32 s11, s1, 0
	s_nop 7
	s_nop 3
	v_mul_f32_e32 v70, 0xbfb8aa3b, v32
	v_mul_f32_e32 v71, 0xbfb8aa3b, v33
	v_mul_f32_e32 v72, 0xbfb8aa3b, v34
	v_mul_f32_e32 v73, 0xbfb8aa3b, v35
	v_exp_f32_e32 v70, v70
	v_exp_f32_e32 v71, v71
	v_exp_f32_e32 v72, v72
	v_exp_f32_e32 v73, v73
	v_add_f32_e32 v70, 1.0, v70
	v_add_f32_e32 v71, 1.0, v71
	v_add_f32_e32 v72, 1.0, v72
	v_add_f32_e32 v73, 1.0, v73
	v_rcp_f32_e32 v70, v70
	v_rcp_f32_e32 v71, v71
	v_rcp_f32_e32 v72, v72
	v_rcp_f32_e32 v73, v73
	v_mul_f32_e32 v70, v32, v70
	v_mul_f32_e32 v71, v33, v71
	v_mul_f32_e32 v72, v34, v72
	v_mul_f32_e32 v73, v35, v73
	v_mul_f32_e32 v70, v48, v70
	v_mul_f32_e32 v71, v49, v71
	v_mul_f32_e32 v72, v50, v72
	v_mul_f32_e32 v73, v51, v73
	v_cvt_pk_bf16_f32 v74, v70, v71
	v_cvt_pk_bf16_f32 v75, v72, v73
	global_store_dwordx2 v66, v[74:75], s[10:11]
	v_mul_f32_e32 v76, 0xbfb8aa3b, v36
	v_mul_f32_e32 v77, 0xbfb8aa3b, v37
	v_mul_f32_e32 v78, 0xbfb8aa3b, v38
	v_mul_f32_e32 v79, 0xbfb8aa3b, v39
	v_exp_f32_e32 v76, v76
	v_exp_f32_e32 v77, v77
	v_exp_f32_e32 v78, v78
	v_exp_f32_e32 v79, v79
	v_add_f32_e32 v76, 1.0, v76
	v_add_f32_e32 v77, 1.0, v77
	v_add_f32_e32 v78, 1.0, v78
	v_add_f32_e32 v79, 1.0, v79
	v_rcp_f32_e32 v76, v76
	v_rcp_f32_e32 v77, v77
	v_rcp_f32_e32 v78, v78
	v_rcp_f32_e32 v79, v79
	v_mul_f32_e32 v76, v36, v76
	v_mul_f32_e32 v77, v37, v77
	v_mul_f32_e32 v78, v38, v78
	v_mul_f32_e32 v79, v39, v79
	v_mul_f32_e32 v76, v52, v76
	v_mul_f32_e32 v77, v53, v77
	v_mul_f32_e32 v78, v54, v78
	v_mul_f32_e32 v79, v55, v79
	v_cvt_pk_bf16_f32 v80, v76, v77
	v_cvt_pk_bf16_f32 v81, v78, v79
	global_store_dwordx2 v66, v[80:81], s[10:11] offset:16
	v_mul_f32_e32 v82, 0xbfb8aa3b, v40
	v_mul_f32_e32 v83, 0xbfb8aa3b, v41
	v_mul_f32_e32 v84, 0xbfb8aa3b, v42
	v_mul_f32_e32 v85, 0xbfb8aa3b, v43
	v_exp_f32_e32 v82, v82
	v_exp_f32_e32 v83, v83
	v_exp_f32_e32 v84, v84
	v_exp_f32_e32 v85, v85
	v_add_f32_e32 v82, 1.0, v82
	v_add_f32_e32 v83, 1.0, v83
	v_add_f32_e32 v84, 1.0, v84
	v_add_f32_e32 v85, 1.0, v85
	v_rcp_f32_e32 v82, v82
	v_rcp_f32_e32 v83, v83
	v_rcp_f32_e32 v84, v84
	v_rcp_f32_e32 v85, v85
	v_mul_f32_e32 v82, v40, v82
	v_mul_f32_e32 v83, v41, v83
	v_mul_f32_e32 v84, v42, v84
	v_mul_f32_e32 v85, v43, v85
	v_mul_f32_e32 v82, v56, v82
	v_mul_f32_e32 v83, v57, v83
	v_mul_f32_e32 v84, v58, v84
	v_mul_f32_e32 v85, v59, v85
	v_cvt_pk_bf16_f32 v86, v82, v83
	v_cvt_pk_bf16_f32 v87, v84, v85
	global_store_dwordx2 v66, v[86:87], s[10:11] offset:32
	v_mul_f32_e32 v70, 0xbfb8aa3b, v44
	v_mul_f32_e32 v71, 0xbfb8aa3b, v45
	v_mul_f32_e32 v72, 0xbfb8aa3b, v46
	v_mul_f32_e32 v73, 0xbfb8aa3b, v47
	v_exp_f32_e32 v70, v70
	v_exp_f32_e32 v71, v71
	v_exp_f32_e32 v72, v72
	v_exp_f32_e32 v73, v73
	v_add_f32_e32 v70, 1.0, v70
	v_add_f32_e32 v71, 1.0, v71
	v_add_f32_e32 v72, 1.0, v72
	v_add_f32_e32 v73, 1.0, v73
	v_rcp_f32_e32 v70, v70
	v_rcp_f32_e32 v71, v71
	v_rcp_f32_e32 v72, v72
	v_rcp_f32_e32 v73, v73
	v_mul_f32_e32 v70, v44, v70
	v_mul_f32_e32 v71, v45, v71
	v_mul_f32_e32 v72, v46, v72
	v_mul_f32_e32 v73, v47, v73
	v_mul_f32_e32 v70, v60, v70
	v_mul_f32_e32 v71, v61, v71
	v_mul_f32_e32 v72, v62, v72
	v_mul_f32_e32 v73, v63, v73
	v_cvt_pk_bf16_f32 v74, v70, v71
	v_cvt_pk_bf16_f32 v75, v72, v73
	global_store_dwordx2 v66, v[74:75], s[10:11] offset:48
	v_mul_f32_e32 v76, 0xbfb8aa3b, v16
	v_mul_f32_e32 v77, 0xbfb8aa3b, v17
	v_mul_f32_e32 v78, 0xbfb8aa3b, v18
	v_mul_f32_e32 v79, 0xbfb8aa3b, v19
	v_exp_f32_e32 v76, v76
	v_exp_f32_e32 v77, v77
	v_exp_f32_e32 v78, v78
	v_exp_f32_e32 v79, v79
	v_add_f32_e32 v76, 1.0, v76
	v_add_f32_e32 v77, 1.0, v77
	v_add_f32_e32 v78, 1.0, v78
	v_add_f32_e32 v79, 1.0, v79
	v_rcp_f32_e32 v76, v76
	v_rcp_f32_e32 v77, v77
	v_rcp_f32_e32 v78, v78
	v_rcp_f32_e32 v79, v79
	v_mul_f32_e32 v76, v16, v76
	v_mul_f32_e32 v77, v17, v77
	v_mul_f32_e32 v78, v18, v78
	v_mul_f32_e32 v79, v19, v79
	v_mul_f32_e32 v76, v0, v76
	v_mul_f32_e32 v77, v1, v77
	v_mul_f32_e32 v78, v2, v78
	v_mul_f32_e32 v79, v3, v79
	v_cvt_pk_bf16_f32 v80, v76, v77
	v_cvt_pk_bf16_f32 v81, v78, v79
	global_store_dwordx2 v67, v[80:81], s[10:11]
	v_mul_f32_e32 v82, 0xbfb8aa3b, v20
	v_mul_f32_e32 v83, 0xbfb8aa3b, v21
	v_mul_f32_e32 v84, 0xbfb8aa3b, v22
	v_mul_f32_e32 v85, 0xbfb8aa3b, v23
	v_exp_f32_e32 v82, v82
	v_exp_f32_e32 v83, v83
	v_exp_f32_e32 v84, v84
	v_exp_f32_e32 v85, v85
	v_add_f32_e32 v82, 1.0, v82
	v_add_f32_e32 v83, 1.0, v83
	v_add_f32_e32 v84, 1.0, v84
	v_add_f32_e32 v85, 1.0, v85
	v_rcp_f32_e32 v82, v82
	v_rcp_f32_e32 v83, v83
	v_rcp_f32_e32 v84, v84
	v_rcp_f32_e32 v85, v85
	v_mul_f32_e32 v82, v20, v82
	v_mul_f32_e32 v83, v21, v83
	v_mul_f32_e32 v84, v22, v84
	v_mul_f32_e32 v85, v23, v85
	v_mul_f32_e32 v82, v4, v82
	v_mul_f32_e32 v83, v5, v83
	v_mul_f32_e32 v84, v6, v84
	v_mul_f32_e32 v85, v7, v85
	v_cvt_pk_bf16_f32 v86, v82, v83
	v_cvt_pk_bf16_f32 v87, v84, v85
	global_store_dwordx2 v67, v[86:87], s[10:11] offset:16
	v_mul_f32_e32 v70, 0xbfb8aa3b, v24
	v_mul_f32_e32 v71, 0xbfb8aa3b, v25
	v_mul_f32_e32 v72, 0xbfb8aa3b, v26
	v_mul_f32_e32 v73, 0xbfb8aa3b, v27
	v_exp_f32_e32 v70, v70
	v_exp_f32_e32 v71, v71
	v_exp_f32_e32 v72, v72
	v_exp_f32_e32 v73, v73
	v_add_f32_e32 v70, 1.0, v70
	v_add_f32_e32 v71, 1.0, v71
	v_add_f32_e32 v72, 1.0, v72
	v_add_f32_e32 v73, 1.0, v73
	v_rcp_f32_e32 v70, v70
	v_rcp_f32_e32 v71, v71
	v_rcp_f32_e32 v72, v72
	v_rcp_f32_e32 v73, v73
	v_mul_f32_e32 v70, v24, v70
	v_mul_f32_e32 v71, v25, v71
	v_mul_f32_e32 v72, v26, v72
	v_mul_f32_e32 v73, v27, v73
	v_mul_f32_e32 v70, v8, v70
	v_mul_f32_e32 v71, v9, v71
	v_mul_f32_e32 v72, v10, v72
	v_mul_f32_e32 v73, v11, v73
	v_cvt_pk_bf16_f32 v74, v70, v71
	v_cvt_pk_bf16_f32 v75, v72, v73
	global_store_dwordx2 v67, v[74:75], s[10:11] offset:32
	v_mul_f32_e32 v76, 0xbfb8aa3b, v28
	v_mul_f32_e32 v77, 0xbfb8aa3b, v29
	v_mul_f32_e32 v78, 0xbfb8aa3b, v30
	v_mul_f32_e32 v79, 0xbfb8aa3b, v31
	v_exp_f32_e32 v76, v76
	v_exp_f32_e32 v77, v77
	v_exp_f32_e32 v78, v78
	v_exp_f32_e32 v79, v79
	v_add_f32_e32 v76, 1.0, v76
	v_add_f32_e32 v77, 1.0, v77
	v_add_f32_e32 v78, 1.0, v78
	v_add_f32_e32 v79, 1.0, v79
	v_rcp_f32_e32 v76, v76
	v_rcp_f32_e32 v77, v77
	v_rcp_f32_e32 v78, v78
	v_rcp_f32_e32 v79, v79
	v_mul_f32_e32 v76, v28, v76
	v_mul_f32_e32 v77, v29, v77
	v_mul_f32_e32 v78, v30, v78
	v_mul_f32_e32 v79, v31, v79
	v_mul_f32_e32 v76, v12, v76
	v_mul_f32_e32 v77, v13, v77
	v_mul_f32_e32 v78, v14, v78
	v_mul_f32_e32 v79, v15, v79
	v_cvt_pk_bf16_f32 v80, v76, v77
	v_cvt_pk_bf16_f32 v81, v78, v79
	global_store_dwordx2 v67, v[80:81], s[10:11] offset:48
	v_readlane_b32 s4, v252, 22
	s_add_i32 s16, s16, s4
	s_cmp_ge_i32 s16, s23
	s_cbranch_scc1 .LBB0_2270
